# K-loops: setprio flips removed, duplicate lgkmcnt(0) removed, address ALU moved from MFMA-tail to after the barrier; barrier: early L1 invalidate + every-8th-arriver L2 writeback
# speedup vs baseline: 1.0128x; 1.0128x over previous
; #define PG8_STAGE(bufoff, gbase, voff) do { _Pragma("unroll") for (int _i = 0; _i < 2; ++_i) \
;         __builtin_amdgcn_global_load_lds((const unsigned*)((const char*)(gbase) + (voff)[_i]), (LAS unsigned*)(lds + (bufoff) + ldsw + _i * 8192), 16, 0, 0); } while (0)
; #define PG8_LDA(dst, b, h) do { _Pragma("unroll") for (int m = 0; m < 4; ++m) _Pragma("unroll") for (int k = 0; k < 2; ++k) dst[m][k] = *(const LAS bf16x8*)(lds + PG8_SA(b, h) + aoff + m * 2048 + k * 1024); } while (0)
; #define PG8_LDB(dst, b, h) do { _Pragma("unroll") for (int n = 0; n < 2; ++n) _Pragma("unroll") for (int k = 0; k < 2; ++k) dst[n][k] = *(const LAS bf16x8*)(lds + PG8_SB(b, h) + boff + n * 2048 + k * 1024); } while (0)
; #define PG8_MMA(ai, bj, At, Bt) do { __builtin_amdgcn_s_setprio(1); _Pragma("unroll") for (int m = 0; m < 4; ++m) _Pragma("unroll") for (int n = 0; n < 2; ++n) _Pragma("unroll") for (int k = 0; k < 2; ++k) \
;         acc[ai][bj][m][n] = __builtin_amdgcn_mfma_f32_16x16x32_bf16(Bt[n][k], At[m][k], acc[ai][bj][m][n], 0, 0, 0); __builtin_amdgcn_s_setprio(0); } while (0)
; #define PG8_WAIT_L(n) asm volatile("s_waitcnt lgkmcnt(" #n ")" ::: "memory")
; #define PG8_BAR __builtin_amdgcn_s_barrier()
; #define PG8_SCHED __builtin_amdgcn_sched_barrier(0)
; template <int MODE, class EpiT, class Sched>
; __device__ __forceinline__ void gemm_phase(LAS unsigned char* lds, const Gemm g, const Sched& S, const EpiT& E) {
;     ...
;         for (int t = 0; t < nt; t += 2) {
;             const bool last = (t == nt - 2);
;             const char* a1 = cA + (size_t)(t + 1) * kstep;
;             const char* a2 = last ? nA : cA + (size_t)(t + 2) * kstep; const char* b2 = last ? nB : cB + (size_t)(t + 2) * kstep;
;             const char* a3 = a2 + kstep; const char* b3 = b2 + kstep;
;             PG8_LDB(B0, 0, 0); PG8_SCHED; PG8_LDA(At, 0, 0); PG8_STAGE(PG8_SA(1, 1), a1 + hstep, voffA);
;             PG8_WAIT_L(8); PG8_BAR; PG8_WAIT_L(0); PG8_MMA(0, 0, At, B0); PG8_BAR; PG8_SCHED;
;             PG8_LDB(B1, 0, 1); PG8_STAGE(PG8_SB(0, 0), b2, voffB);
;             PG8_BAR; PG8_WAIT_L(0); PG8_MMA(0, 1, At, B1); PG8_BAR;
;             PG8_LDA(At, 0, 1); PG8_STAGE(PG8_SA(0, 0), a2, voffA);
;             PG8_BAR; PG8_WAIT_L(0); PG8_MMA(1, 0, At, B0); PG8_BAR; PG8_SCHED;
.LBB0_115:
	s_add_i32 s58, s52, 2
	s_add_u32 s59, s44, 0x80
	s_addc_u32 s53, s45, 0
	s_add_i32 s91, 0, 0x10000
	v_add_u32_e32 v86, s91, v192
	ds_read_b128 v[70:73], v86
	ds_read_b128 v[74:77], v86 offset:1024
	ds_read_b128 v[82:85], v86 offset:2048
	ds_read_b128 v[86:89], v86 offset:3072
	s_cmp_eq_u32 s57, s52
	s_cselect_b32 s52, s4, s59
	s_cselect_b32 s53, s5, s53
	s_cselect_b32 s75, s47, vcc_hi
	s_cselect_b32 s74, s46, vcc_lo
	v_lshl_add_u64 v[188:189], s[44:45], 0, v[176:177]
	s_add_i32 m0, s20, 0xc000
	ds_read_b128 v[138:141], v194
	ds_read_b128 v[142:145], v194 offset:1024
	ds_read_b128 v[146:149], v194 offset:2048
	ds_read_b128 v[154:157], v194 offset:3072
	ds_read_b128 v[162:165], v194 offset:4096
	ds_read_b128 v[166:169], v194 offset:5120
	ds_read_b128 v[170:173], v194 offset:6144
	ds_read_b128 v[184:187], v194 offset:7168
	global_load_lds_dwordx4 v[188:189], off
	v_lshl_add_u64 v[188:189], s[44:45], 0, v[182:183]
	s_add_i32 m0, s20, 0xe000
	s_nop 0
	global_load_lds_dwordx4 v[188:189], off
	s_waitcnt lgkmcnt(8)
	s_barrier
	s_waitcnt lgkmcnt(0)
	v_mfma_f32_16x16x32_bf16 v[158:161], v[70:73], v[138:141], v[158:161]
	v_mfma_f32_16x16x32_bf16 v[150:153], v[82:85], v[138:141], v[150:153]
	v_mfma_f32_16x16x32_bf16 v[126:129], v[70:73], v[146:149], v[126:129]
	v_mfma_f32_16x16x32_bf16 v[122:125], v[82:85], v[146:149], v[122:125]
	v_mfma_f32_16x16x32_bf16 v[110:113], v[70:73], v[162:165], v[110:113]
	v_mfma_f32_16x16x32_bf16 v[106:109], v[82:85], v[162:165], v[106:109]
	v_mfma_f32_16x16x32_bf16 v[94:97], v[70:73], v[170:173], v[94:97]
	v_mfma_f32_16x16x32_bf16 v[90:93], v[82:85], v[170:173], v[90:93]
	v_mfma_f32_16x16x32_bf16 v[158:161], v[74:77], v[142:145], v[158:161]
	v_mfma_f32_16x16x32_bf16 v[150:153], v[86:89], v[142:145], v[150:153]
	v_mfma_f32_16x16x32_bf16 v[126:129], v[74:77], v[154:157], v[126:129]
	v_mfma_f32_16x16x32_bf16 v[122:125], v[86:89], v[154:157], v[122:125]
	v_mfma_f32_16x16x32_bf16 v[110:113], v[74:77], v[166:169], v[110:113]
	v_mfma_f32_16x16x32_bf16 v[106:109], v[86:89], v[166:169], v[106:109]
	v_mfma_f32_16x16x32_bf16 v[94:97], v[74:77], v[184:187], v[94:97]
	v_mfma_f32_16x16x32_bf16 v[90:93], v[86:89], v[184:187], v[90:93]
	s_barrier
	s_add_i32 s59, 0, 0x14000
	s_add_i32 s91, s91, s9
	v_add_u32_e32 v195, s59, v192
	v_lshl_add_u64 v[228:229], s[74:75], 0, v[0:1]
	s_mov_b32 m0, s91
	ds_read_b128 v[188:191], v195
	ds_read_b128 v[196:199], v195 offset:1024
	ds_read_b128 v[220:223], v195 offset:2048
	ds_read_b128 v[224:227], v195 offset:3072
	global_load_lds_dwordx4 v[228:229], off
	v_lshl_add_u64 v[230:231], s[74:75], 0, v[174:175]
	s_add_i32 m0, s91, 0x2000
	s_nop 0
	global_load_lds_dwordx4 v[230:231], off
	s_barrier
	s_waitcnt lgkmcnt(0)
	v_mfma_f32_16x16x32_bf16 v[134:137], v[188:191], v[138:141], v[134:137]
	v_mfma_f32_16x16x32_bf16 v[130:133], v[220:223], v[138:141], v[130:133]
	v_mfma_f32_16x16x32_bf16 v[118:121], v[188:191], v[146:149], v[118:121]
	v_mfma_f32_16x16x32_bf16 v[114:117], v[220:223], v[146:149], v[114:117]
	v_mfma_f32_16x16x32_bf16 v[102:105], v[188:191], v[162:165], v[102:105]
	v_mfma_f32_16x16x32_bf16 v[98:101], v[220:223], v[162:165], v[98:101]
	v_mfma_f32_16x16x32_bf16 v[78:81], v[188:191], v[170:173], v[78:81]
	v_mfma_f32_16x16x32_bf16 v[66:69], v[220:223], v[170:173], v[66:69]
	v_mfma_f32_16x16x32_bf16 v[134:137], v[196:199], v[142:145], v[134:137]
	v_mfma_f32_16x16x32_bf16 v[130:133], v[224:227], v[142:145], v[130:133]
	v_mfma_f32_16x16x32_bf16 v[118:121], v[196:199], v[154:157], v[118:121]
	v_mfma_f32_16x16x32_bf16 v[114:117], v[224:227], v[154:157], v[114:117]
	v_mfma_f32_16x16x32_bf16 v[102:105], v[196:199], v[166:169], v[102:105]
	v_mfma_f32_16x16x32_bf16 v[98:101], v[224:227], v[166:169], v[98:101]
	v_mfma_f32_16x16x32_bf16 v[78:81], v[196:199], v[184:187], v[78:81]
	v_mfma_f32_16x16x32_bf16 v[66:69], v[224:227], v[184:187], v[66:69]
	s_barrier
	s_mov_b32 m0, s20
	v_lshl_add_u64 v[232:233], s[52:53], 0, v[0:1]
	ds_read_b128 v[138:141], v194 offset:16384
	ds_read_b128 v[142:145], v194 offset:17408
	ds_read_b128 v[146:149], v194 offset:18432
	ds_read_b128 v[154:157], v194 offset:19456
	ds_read_b128 v[162:165], v194 offset:20480
	ds_read_b128 v[166:169], v194 offset:21504
	ds_read_b128 v[170:173], v194 offset:22528
	ds_read_b128 v[184:187], v194 offset:23552
	global_load_lds_dwordx4 v[232:233], off
	v_lshl_add_u64 v[234:235], s[52:53], 0, v[174:175]
	s_mov_b32 m0, s21
	s_nop 0
	global_load_lds_dwordx4 v[234:235], off
	s_barrier
	s_waitcnt lgkmcnt(0)
	v_mfma_f32_16x16x32_bf16 v[62:65], v[70:73], v[138:141], v[62:65]
	v_mfma_f32_16x16x32_bf16 v[58:61], v[82:85], v[138:141], v[58:61]
	v_mfma_f32_16x16x32_bf16 v[46:49], v[70:73], v[146:149], v[46:49]
	v_mfma_f32_16x16x32_bf16 v[42:45], v[82:85], v[146:149], v[42:45]
	v_mfma_f32_16x16x32_bf16 v[30:33], v[70:73], v[162:165], v[30:33]
	v_mfma_f32_16x16x32_bf16 v[26:29], v[82:85], v[162:165], v[26:29]
	v_mfma_f32_16x16x32_bf16 v[14:17], v[70:73], v[170:173], v[14:17]
	v_mfma_f32_16x16x32_bf16 v[10:13], v[82:85], v[170:173], v[10:13]
	v_mfma_f32_16x16x32_bf16 v[62:65], v[74:77], v[142:145], v[62:65]
	v_mfma_f32_16x16x32_bf16 v[58:61], v[86:89], v[142:145], v[58:61]
	v_mfma_f32_16x16x32_bf16 v[46:49], v[74:77], v[154:157], v[46:49]
	v_mfma_f32_16x16x32_bf16 v[42:45], v[86:89], v[154:157], v[42:45]
	v_mfma_f32_16x16x32_bf16 v[30:33], v[74:77], v[166:169], v[30:33]
	v_mfma_f32_16x16x32_bf16 v[26:29], v[86:89], v[166:169], v[26:29]
	v_mfma_f32_16x16x32_bf16 v[14:17], v[74:77], v[184:187], v[14:17]
	v_mfma_f32_16x16x32_bf16 v[10:13], v[86:89], v[184:187], v[10:13]
	s_barrier
; #define PG8_STAGE(bufoff, gbase, voff) do { _Pragma("unroll") for (int _i = 0; _i < 2; ++_i) \
;         __builtin_amdgcn_global_load_lds((const unsigned*)((const char*)(gbase) + (voff)[_i]), (LAS unsigned*)(lds + (bufoff) + ldsw + _i * 8192), 16, 0, 0); } while (0)
; #define PG8_LDA(dst, b, h) do { _Pragma("unroll") for (int m = 0; m < 4; ++m) _Pragma("unroll") for (int k = 0; k < 2; ++k) dst[m][k] = *(const LAS bf16x8*)(lds + PG8_SA(b, h) + aoff + m * 2048 + k * 1024); } while (0)
; #define PG8_LDB(dst, b, h) do { _Pragma("unroll") for (int n = 0; n < 2; ++n) _Pragma("unroll") for (int k = 0; k < 2; ++k) dst[n][k] = *(const LAS bf16x8*)(lds + PG8_SB(b, h) + boff + n * 2048 + k * 1024); } while (0)
; #define PG8_MMA(ai, bj, At, Bt) do { __builtin_amdgcn_s_setprio(1); _Pragma("unroll") for (int m = 0; m < 4; ++m) _Pragma("unroll") for (int n = 0; n < 2; ++n) _Pragma("unroll") for (int k = 0; k < 2; ++k) \
;         acc[ai][bj][m][n] = __builtin_amdgcn_mfma_f32_16x16x32_bf16(Bt[n][k], At[m][k], acc[ai][bj][m][n], 0, 0, 0); __builtin_amdgcn_s_setprio(0); } while (0)
; #define PG8_WAIT_V(n) asm volatile("s_waitcnt vmcnt(" #n ")" ::: "memory")
; #define PG8_WAIT_L(n) asm volatile("s_waitcnt lgkmcnt(" #n ")" ::: "memory")
; #define PG8_BAR __builtin_amdgcn_s_barrier()
; #define PG8_SCHED __builtin_amdgcn_sched_barrier(0)
; template <int MODE, class EpiT, class Sched>
; __device__ __forceinline__ void gemm_phase(LAS unsigned char* lds, const Gemm g, const Sched& S, const EpiT& E) {
;     ...
;             PG8_STAGE(PG8_SB(0, 1), b2 + hstep, voffB);
;             PG8_WAIT_V(6); PG8_BAR; PG8_MMA(1, 1, At, B1); PG8_BAR;
;             PG8_LDB(B0, 1, 0); PG8_SCHED; PG8_LDA(At, 1, 0); PG8_STAGE(PG8_SA(0, 1), a2 + hstep, voffA);
;             PG8_WAIT_L(8); PG8_BAR; PG8_WAIT_L(0); PG8_MMA(0, 0, At, B0); PG8_BAR; PG8_SCHED;
;             PG8_LDB(B1, 1, 1); PG8_STAGE(PG8_SB(1, 0), b3, voffB);
;             PG8_BAR; PG8_WAIT_L(0); PG8_MMA(0, 1, At, B1); PG8_BAR;
	s_add_u32 s74, s74, s78
	s_addc_u32 s75, s75, 0
	s_add_i32 s59, s59, s9
	v_lshl_add_u64 v[236:237], s[74:75], 0, v[0:1]
	s_mov_b32 m0, s59
	v_lshl_add_u64 v[238:239], s[74:75], 0, v[174:175]
	global_load_lds_dwordx4 v[236:237], off
	s_add_i32 m0, s59, 0x2000
	s_nop 0
	global_load_lds_dwordx4 v[238:239], off
	s_waitcnt vmcnt(6)
	s_barrier
	v_mfma_f32_16x16x32_bf16 v[54:57], v[188:191], v[138:141], v[54:57]
	v_mfma_f32_16x16x32_bf16 v[50:53], v[220:223], v[138:141], v[50:53]
	v_mfma_f32_16x16x32_bf16 v[38:41], v[188:191], v[146:149], v[38:41]
	v_mfma_f32_16x16x32_bf16 v[34:37], v[220:223], v[146:149], v[34:37]
	v_mfma_f32_16x16x32_bf16 v[22:25], v[188:191], v[162:165], v[22:25]
	v_mfma_f32_16x16x32_bf16 v[18:21], v[220:223], v[162:165], v[18:21]
	v_mfma_f32_16x16x32_bf16 v[6:9], v[188:191], v[170:173], v[6:9]
	v_mfma_f32_16x16x32_bf16 v[2:5], v[220:223], v[170:173], v[2:5]
	v_mfma_f32_16x16x32_bf16 v[54:57], v[196:199], v[142:145], v[54:57]
	v_mfma_f32_16x16x32_bf16 v[50:53], v[224:227], v[142:145], v[50:53]
	v_mfma_f32_16x16x32_bf16 v[38:41], v[196:199], v[154:157], v[38:41]
	v_mfma_f32_16x16x32_bf16 v[34:37], v[224:227], v[154:157], v[34:37]
	v_mfma_f32_16x16x32_bf16 v[22:25], v[196:199], v[166:169], v[22:25]
	v_mfma_f32_16x16x32_bf16 v[18:21], v[224:227], v[166:169], v[18:21]
	v_mfma_f32_16x16x32_bf16 v[6:9], v[196:199], v[184:187], v[6:9]
	v_mfma_f32_16x16x32_bf16 v[2:5], v[224:227], v[184:187], v[2:5]
	s_barrier
	s_add_i32 s59, 0, 0x18000
	v_add_u32_e32 v86, s59, v192
	ds_read_b128 v[70:73], v86
	ds_read_b128 v[74:77], v86 offset:1024
	ds_read_b128 v[82:85], v86 offset:2048
	ds_read_b128 v[86:89], v86 offset:3072
	s_add_u32 s52, s52, s78
	s_addc_u32 s53, s53, 0
	s_mov_b32 m0, s22
	v_lshl_add_u64 v[188:189], s[52:53], 0, v[0:1]
	ds_read_b128 v[138:141], v194 offset:32768
	ds_read_b128 v[142:145], v194 offset:33792
	ds_read_b128 v[146:149], v194 offset:34816
	ds_read_b128 v[154:157], v194 offset:35840
	ds_read_b128 v[162:165], v194 offset:36864
	ds_read_b128 v[166:169], v194 offset:37888
	ds_read_b128 v[170:173], v194 offset:38912
	ds_read_b128 v[184:187], v194 offset:39936
	global_load_lds_dwordx4 v[188:189], off
	v_lshl_add_u64 v[188:189], s[52:53], 0, v[174:175]
	s_mov_b32 m0, s23
	s_nop 0
	global_load_lds_dwordx4 v[188:189], off
	s_waitcnt lgkmcnt(8)
	s_barrier
	s_waitcnt lgkmcnt(0)
	v_mfma_f32_16x16x32_bf16 v[158:161], v[70:73], v[138:141], v[158:161]
	v_mfma_f32_16x16x32_bf16 v[150:153], v[82:85], v[138:141], v[150:153]
	v_mfma_f32_16x16x32_bf16 v[126:129], v[70:73], v[146:149], v[126:129]
	v_mfma_f32_16x16x32_bf16 v[122:125], v[82:85], v[146:149], v[122:125]
	v_mfma_f32_16x16x32_bf16 v[110:113], v[70:73], v[162:165], v[110:113]
	v_mfma_f32_16x16x32_bf16 v[106:109], v[82:85], v[162:165], v[106:109]
	v_mfma_f32_16x16x32_bf16 v[94:97], v[70:73], v[170:173], v[94:97]
	v_mfma_f32_16x16x32_bf16 v[90:93], v[82:85], v[170:173], v[90:93]
	v_mfma_f32_16x16x32_bf16 v[158:161], v[74:77], v[142:145], v[158:161]
	v_mfma_f32_16x16x32_bf16 v[150:153], v[86:89], v[142:145], v[150:153]
	v_mfma_f32_16x16x32_bf16 v[126:129], v[74:77], v[154:157], v[126:129]
	v_mfma_f32_16x16x32_bf16 v[122:125], v[86:89], v[154:157], v[122:125]
	v_mfma_f32_16x16x32_bf16 v[110:113], v[74:77], v[166:169], v[110:113]
	v_mfma_f32_16x16x32_bf16 v[106:109], v[86:89], v[166:169], v[106:109]
	v_mfma_f32_16x16x32_bf16 v[94:97], v[74:77], v[184:187], v[94:97]
	v_mfma_f32_16x16x32_bf16 v[90:93], v[86:89], v[184:187], v[90:93]
	s_barrier
	s_add_i32 s52, 0, 0x1c000
	s_add_i32 s53, s59, s9
	v_add_u32_e32 v195, s52, v192
	v_lshl_add_u64 v[228:229], v[228:229], 0, s[76:77]
	s_mov_b32 m0, s53
	ds_read_b128 v[188:191], v195
	ds_read_b128 v[196:199], v195 offset:1024
	ds_read_b128 v[220:223], v195 offset:2048
	ds_read_b128 v[224:227], v195 offset:3072
	global_load_lds_dwordx4 v[228:229], off
	v_lshl_add_u64 v[228:229], v[230:231], 0, s[76:77]
	s_add_i32 m0, s53, 0x2000
	s_nop 0
	global_load_lds_dwordx4 v[228:229], off
	s_barrier
; #define PG8_STAGE(bufoff, gbase, voff) do { _Pragma("unroll") for (int _i = 0; _i < 2; ++_i) \
;         __builtin_amdgcn_global_load_lds((const unsigned*)((const char*)(gbase) + (voff)[_i]), (LAS unsigned*)(lds + (bufoff) + ldsw + _i * 8192), 16, 0, 0); } while (0)
; #define PG8_LDA(dst, b, h) do { _Pragma("unroll") for (int m = 0; m < 4; ++m) _Pragma("unroll") for (int k = 0; k < 2; ++k) dst[m][k] = *(const LAS bf16x8*)(lds + PG8_SA(b, h) + aoff + m * 2048 + k * 1024); } while (0)
; #define PG8_MMA(ai, bj, At, Bt) do { __builtin_amdgcn_s_setprio(1); _Pragma("unroll") for (int m = 0; m < 4; ++m) _Pragma("unroll") for (int n = 0; n < 2; ++n) _Pragma("unroll") for (int k = 0; k < 2; ++k) \
;         acc[ai][bj][m][n] = __builtin_amdgcn_mfma_f32_16x16x32_bf16(Bt[n][k], At[m][k], acc[ai][bj][m][n], 0, 0, 0); __builtin_amdgcn_s_setprio(0); } while (0)
; #define PG8_WAIT_V(n) asm volatile("s_waitcnt vmcnt(" #n ")" ::: "memory")
; #define PG8_WAIT_L(n) asm volatile("s_waitcnt lgkmcnt(" #n ")" ::: "memory")
; #define PG8_BAR __builtin_amdgcn_s_barrier()
; #define PG8_SCHED __builtin_amdgcn_sched_barrier(0)
;     template <int mode> __device__ __forceinline__ void run(const f32x4 (&acc)[2][2][4][2], const Unit& u, int wr, int wc, int fr, int fq, const LAS float* sc) const {
;     ...
;             f32x4 bvv[4];
; #pragma unroll
;             for (int q = 0; q < 4; ++q) bvv[q] = (mode != 4 && bias) ? *(const f32x4*)(bias + col0 + (q >> 1) * HALF + (q & 1) * 4) : (f32x4){0.f, 0.f, 0.f, 0.f};
; template <int MODE, class EpiT, class Sched>
; __device__ __forceinline__ void gemm_phase(LAS unsigned char* lds, const Gemm g, const Sched& S, const EpiT& E) {
;     ...
;             PG8_BAR; PG8_WAIT_L(0); PG8_MMA(0, 1, At, B1); PG8_BAR;
;             PG8_LDA(At, 1, 1); PG8_STAGE(PG8_SA(1, 0), a3, voffA);
;             PG8_BAR; PG8_WAIT_L(0); PG8_MMA(1, 0, At, B0); PG8_BAR; PG8_SCHED;
;             PG8_STAGE(PG8_SB(1, 1), b3 + hstep, voffB);
;             PG8_WAIT_V(6); PG8_BAR; PG8_MMA(1, 1, At, B1); PG8_BAR;
;         }
	s_waitcnt lgkmcnt(0)
	v_mfma_f32_16x16x32_bf16 v[134:137], v[188:191], v[138:141], v[134:137]
	v_mfma_f32_16x16x32_bf16 v[130:133], v[220:223], v[138:141], v[130:133]
	v_mfma_f32_16x16x32_bf16 v[118:121], v[188:191], v[146:149], v[118:121]
	v_mfma_f32_16x16x32_bf16 v[114:117], v[220:223], v[146:149], v[114:117]
	v_mfma_f32_16x16x32_bf16 v[102:105], v[188:191], v[162:165], v[102:105]
	v_mfma_f32_16x16x32_bf16 v[98:101], v[220:223], v[162:165], v[98:101]
	v_mfma_f32_16x16x32_bf16 v[78:81], v[188:191], v[170:173], v[78:81]
	v_mfma_f32_16x16x32_bf16 v[66:69], v[220:223], v[170:173], v[66:69]
	v_mfma_f32_16x16x32_bf16 v[134:137], v[196:199], v[142:145], v[134:137]
	v_mfma_f32_16x16x32_bf16 v[130:133], v[224:227], v[142:145], v[130:133]
	v_mfma_f32_16x16x32_bf16 v[118:121], v[196:199], v[154:157], v[118:121]
	v_mfma_f32_16x16x32_bf16 v[114:117], v[224:227], v[154:157], v[114:117]
	v_mfma_f32_16x16x32_bf16 v[102:105], v[196:199], v[166:169], v[102:105]
	v_mfma_f32_16x16x32_bf16 v[98:101], v[224:227], v[166:169], v[98:101]
	v_mfma_f32_16x16x32_bf16 v[78:81], v[196:199], v[184:187], v[78:81]
	v_mfma_f32_16x16x32_bf16 v[66:69], v[224:227], v[184:187], v[66:69]
	s_barrier
	s_mov_b32 m0, s51
	v_lshl_add_u64 v[228:229], v[232:233], 0, s[76:77]
	ds_read_b128 v[138:141], v194 offset:49152
	ds_read_b128 v[142:145], v194 offset:50176
	ds_read_b128 v[146:149], v194 offset:51200
	ds_read_b128 v[154:157], v194 offset:52224
	ds_read_b128 v[162:165], v194 offset:53248
	ds_read_b128 v[166:169], v194 offset:54272
	ds_read_b128 v[170:173], v194 offset:55296
	ds_read_b128 v[184:187], v194 offset:56320
	global_load_lds_dwordx4 v[228:229], off
	v_lshl_add_u64 v[228:229], v[234:235], 0, s[76:77]
	s_mov_b32 m0, s56
	s_nop 0
	global_load_lds_dwordx4 v[228:229], off
	s_barrier
	s_waitcnt lgkmcnt(0)
	v_mfma_f32_16x16x32_bf16 v[62:65], v[70:73], v[138:141], v[62:65]
	v_mfma_f32_16x16x32_bf16 v[58:61], v[82:85], v[138:141], v[58:61]
	v_mfma_f32_16x16x32_bf16 v[46:49], v[70:73], v[146:149], v[46:49]
	v_mfma_f32_16x16x32_bf16 v[42:45], v[82:85], v[146:149], v[42:45]
	v_mfma_f32_16x16x32_bf16 v[30:33], v[70:73], v[162:165], v[30:33]
	v_mfma_f32_16x16x32_bf16 v[26:29], v[82:85], v[162:165], v[26:29]
	v_mfma_f32_16x16x32_bf16 v[14:17], v[70:73], v[170:173], v[14:17]
	v_mfma_f32_16x16x32_bf16 v[10:13], v[82:85], v[170:173], v[10:13]
	v_mfma_f32_16x16x32_bf16 v[62:65], v[74:77], v[142:145], v[62:65]
	v_mfma_f32_16x16x32_bf16 v[58:61], v[86:89], v[142:145], v[58:61]
	v_mfma_f32_16x16x32_bf16 v[46:49], v[74:77], v[154:157], v[46:49]
	v_mfma_f32_16x16x32_bf16 v[42:45], v[86:89], v[154:157], v[42:45]
	v_mfma_f32_16x16x32_bf16 v[30:33], v[74:77], v[166:169], v[30:33]
	v_mfma_f32_16x16x32_bf16 v[26:29], v[86:89], v[166:169], v[26:29]
	v_mfma_f32_16x16x32_bf16 v[14:17], v[74:77], v[184:187], v[14:17]
	v_mfma_f32_16x16x32_bf16 v[10:13], v[86:89], v[184:187], v[10:13]
	s_barrier
	s_add_i32 s52, s52, s9
	v_lshl_add_u64 v[70:71], v[236:237], 0, s[76:77]
	s_mov_b32 m0, s52
	s_nop 0
	global_load_lds_dwordx4 v[70:71], off
	v_lshl_add_u64 v[70:71], v[238:239], 0, s[76:77]
	s_add_i32 m0, s52, 0x2000
	s_nop 0
	global_load_lds_dwordx4 v[70:71], off
	s_waitcnt vmcnt(6)
	s_barrier
	v_mfma_f32_16x16x32_bf16 v[54:57], v[188:191], v[138:141], v[54:57]
	v_mfma_f32_16x16x32_bf16 v[50:53], v[220:223], v[138:141], v[50:53]
	v_mfma_f32_16x16x32_bf16 v[38:41], v[188:191], v[146:149], v[38:41]
	v_mfma_f32_16x16x32_bf16 v[34:37], v[220:223], v[146:149], v[34:37]
	v_mfma_f32_16x16x32_bf16 v[22:25], v[188:191], v[162:165], v[22:25]
	v_mfma_f32_16x16x32_bf16 v[18:21], v[220:223], v[162:165], v[18:21]
	v_mfma_f32_16x16x32_bf16 v[6:9], v[188:191], v[170:173], v[6:9]
	v_mfma_f32_16x16x32_bf16 v[2:5], v[220:223], v[170:173], v[2:5]
	v_mfma_f32_16x16x32_bf16 v[54:57], v[196:199], v[142:145], v[54:57]
	v_mfma_f32_16x16x32_bf16 v[50:53], v[224:227], v[142:145], v[50:53]
	v_mfma_f32_16x16x32_bf16 v[38:41], v[196:199], v[154:157], v[38:41]
	v_mfma_f32_16x16x32_bf16 v[34:37], v[224:227], v[154:157], v[34:37]
	v_mfma_f32_16x16x32_bf16 v[22:25], v[196:199], v[166:169], v[22:25]
	v_mfma_f32_16x16x32_bf16 v[18:21], v[224:227], v[166:169], v[18:21]
	v_mfma_f32_16x16x32_bf16 v[6:9], v[196:199], v[184:187], v[6:9]
	v_mfma_f32_16x16x32_bf16 v[2:5], v[224:227], v[184:187], v[2:5]
	s_barrier
	s_add_u32 s44, s44, 0x100
	s_addc_u32 s45, s45, 0
	s_add_u32 vcc_lo, vcc_lo, 0x100
	s_addc_u32 vcc_hi, vcc_hi, 0
	s_cmp_ge_u32 s58, s50
	s_mov_b32 s52, s58
	s_cbranch_scc0 .LBB0_115
	v_lshl_or_b32 v184, s24, 8, v193
	v_ashrrev_i32_e32 v185, 31, v184
	v_mov_b32_e32 v74, 0
	v_cndmask_b32_e64 v70, 0, 1, s[68:69]
	v_lshl_add_u64 v[138:139], v[184:185], 2, s[12:13]
	v_cmp_ne_u32_e64 s[44:45], 1, v70
	s_andn2_b64 vcc, exec, s[68:69]
	v_mov_b32_e32 v86, 0
	v_mov_b32_e32 v87, v74
	v_mov_b32_e32 v186, 0
	v_mov_b32_e32 v187, v74
	s_cbranch_vccnz .LBB0_118
	global_load_dwordx4 v[86:89], v[138:139], off
	s_waitcnt vmcnt(0)
	v_mov_b32_e32 v186, v88
	v_mov_b32_e32 v187, v89

; #define PG8_STAGE(bufoff, gbase, voff) do { _Pragma("unroll") for (int _i = 0; _i < 2; ++_i) \
;         __builtin_amdgcn_global_load_lds((const unsigned*)((const char*)(gbase) + (voff)[_i]), (LAS unsigned*)(lds + (bufoff) + ldsw + _i * 8192), 16, 0, 0); } while (0)
; #define PG8_LDA(dst, b, h) do { _Pragma("unroll") for (int m = 0; m < 4; ++m) _Pragma("unroll") for (int k = 0; k < 2; ++k) dst[m][k] = *(const LAS bf16x8*)(lds + PG8_SA(b, h) + aoff + m * 2048 + k * 1024); } while (0)
; #define PG8_LDB(dst, b, h) do { _Pragma("unroll") for (int n = 0; n < 2; ++n) _Pragma("unroll") for (int k = 0; k < 2; ++k) dst[n][k] = *(const LAS bf16x8*)(lds + PG8_SB(b, h) + boff + n * 2048 + k * 1024); } while (0)
; #define PG8_MMA(ai, bj, At, Bt) do { __builtin_amdgcn_s_setprio(1); _Pragma("unroll") for (int m = 0; m < 4; ++m) _Pragma("unroll") for (int n = 0; n < 2; ++n) _Pragma("unroll") for (int k = 0; k < 2; ++k) \
;         acc[ai][bj][m][n] = __builtin_amdgcn_mfma_f32_16x16x32_bf16(Bt[n][k], At[m][k], acc[ai][bj][m][n], 0, 0, 0); __builtin_amdgcn_s_setprio(0); } while (0)
; #define PG8_WAIT_L(n) asm volatile("s_waitcnt lgkmcnt(" #n ")" ::: "memory")
; #define PG8_BAR __builtin_amdgcn_s_barrier()
; #define PG8_SCHED __builtin_amdgcn_sched_barrier(0)
; template <int MODE, class EpiT, class Sched>
; __device__ __forceinline__ void gemm_phase(LAS unsigned char* lds, const Gemm g, const Sched& S, const EpiT& E) {
;     ...
;         for (int t = 0; t < nt; t += 2) {
;             const bool last = (t == nt - 2);
;             const char* a1 = cA + (size_t)(t + 1) * kstep;
;             const char* a2 = last ? nA : cA + (size_t)(t + 2) * kstep; const char* b2 = last ? nB : cB + (size_t)(t + 2) * kstep;
;             const char* a3 = a2 + kstep; const char* b3 = b2 + kstep;
;             PG8_LDB(B0, 0, 0); PG8_SCHED; PG8_LDA(At, 0, 0); PG8_STAGE(PG8_SA(1, 1), a1 + hstep, voffA);
;             PG8_WAIT_L(8); PG8_BAR; PG8_WAIT_L(0); PG8_MMA(0, 0, At, B0); PG8_BAR; PG8_SCHED;
;             PG8_LDB(B1, 0, 1); PG8_STAGE(PG8_SB(0, 0), b2, voffB);
;             PG8_BAR; PG8_WAIT_L(0); PG8_MMA(0, 1, At, B1); PG8_BAR;
;             PG8_LDA(At, 0, 1); PG8_STAGE(PG8_SA(0, 0), a2, voffA);
;             PG8_BAR; PG8_WAIT_L(0); PG8_MMA(1, 0, At, B0); PG8_BAR; PG8_SCHED;
.LBB0_159:
	s_add_i32 s89, s30, 2
	s_add_u32 s44, s4, 0x80
	s_addc_u32 s45, s5, 0
	s_add_i32 s58, 0, 0x10000
	v_add_u32_e32 v142, s58, v220
	ds_read_b128 v[130:133], v142
	ds_read_b128 v[134:137], v142 offset:1024
	ds_read_b128 v[138:141], v142 offset:2048
	ds_read_b128 v[142:145], v142 offset:3072
	s_cmp_eq_u32 s61, s30
	s_cselect_b32 s45, s79, s45
	s_cselect_b32 s44, s78, s44
	s_cselect_b32 s53, s47, s24
	s_cselect_b32 s52, s46, s23
	v_lshl_add_u64 v[188:189], s[4:5], 0, v[184:185]
	s_add_i32 m0, s69, 0xc000
	ds_read_b128 v[146:149], v223
	ds_read_b128 v[150:153], v223 offset:1024
	ds_read_b128 v[154:157], v223 offset:2048
	ds_read_b128 v[158:161], v223 offset:3072
	ds_read_b128 v[162:165], v223 offset:4096
	ds_read_b128 v[166:169], v223 offset:5120
	ds_read_b128 v[170:173], v223 offset:6144
	ds_read_b128 v[174:177], v223 offset:7168
	global_load_lds_dwordx4 v[188:189], off
	v_lshl_add_u64 v[188:189], s[4:5], 0, v[186:187]
	s_add_i32 m0, s69, 0xe000
	s_nop 0
	global_load_lds_dwordx4 v[188:189], off
	s_waitcnt lgkmcnt(8)
	s_barrier
	s_waitcnt lgkmcnt(0)
	v_mfma_f32_16x16x32_bf16 v[126:129], v[130:133], v[146:149], v[126:129]
	v_mfma_f32_16x16x32_bf16 v[122:125], v[138:141], v[146:149], v[122:125]
	v_mfma_f32_16x16x32_bf16 v[110:113], v[130:133], v[154:157], v[110:113]
	v_mfma_f32_16x16x32_bf16 v[106:109], v[138:141], v[154:157], v[106:109]
	v_mfma_f32_16x16x32_bf16 v[94:97], v[130:133], v[162:165], v[94:97]
	v_mfma_f32_16x16x32_bf16 v[90:93], v[138:141], v[162:165], v[90:93]
	v_mfma_f32_16x16x32_bf16 v[78:81], v[130:133], v[170:173], v[78:81]
	v_mfma_f32_16x16x32_bf16 v[74:77], v[138:141], v[170:173], v[74:77]
	v_mfma_f32_16x16x32_bf16 v[126:129], v[134:137], v[150:153], v[126:129]
	v_mfma_f32_16x16x32_bf16 v[122:125], v[142:145], v[150:153], v[122:125]
	v_mfma_f32_16x16x32_bf16 v[110:113], v[134:137], v[158:161], v[110:113]
	v_mfma_f32_16x16x32_bf16 v[106:109], v[142:145], v[158:161], v[106:109]
	v_mfma_f32_16x16x32_bf16 v[94:97], v[134:137], v[166:169], v[94:97]
	v_mfma_f32_16x16x32_bf16 v[90:93], v[142:145], v[166:169], v[90:93]
	v_mfma_f32_16x16x32_bf16 v[78:81], v[134:137], v[174:177], v[78:81]
	v_mfma_f32_16x16x32_bf16 v[74:77], v[142:145], v[174:177], v[74:77]
	s_barrier
	s_add_i32 s30, 0, 0x14000
	s_add_i32 s58, s58, s68
	v_add_u32_e32 v200, s30, v220
	v_lshl_add_u64 v[228:229], s[52:53], 0, v[0:1]
	s_mov_b32 m0, s58
	ds_read_b128 v[188:191], v200
	ds_read_b128 v[192:195], v200 offset:1024
	ds_read_b128 v[196:199], v200 offset:2048
	ds_read_b128 v[224:227], v200 offset:3072
	global_load_lds_dwordx4 v[228:229], off
	v_lshl_add_u64 v[230:231], s[52:53], 0, v[182:183]
	s_add_i32 m0, s58, 0x2000
	s_nop 0
	global_load_lds_dwordx4 v[230:231], off
	s_barrier
	s_waitcnt lgkmcnt(0)
	v_mfma_f32_16x16x32_bf16 v[118:121], v[188:191], v[146:149], v[118:121]
	v_mfma_f32_16x16x32_bf16 v[114:117], v[196:199], v[146:149], v[114:117]
	v_mfma_f32_16x16x32_bf16 v[102:105], v[188:191], v[154:157], v[102:105]
	v_mfma_f32_16x16x32_bf16 v[98:101], v[196:199], v[154:157], v[98:101]
	v_mfma_f32_16x16x32_bf16 v[86:89], v[188:191], v[162:165], v[86:89]
	v_mfma_f32_16x16x32_bf16 v[82:85], v[196:199], v[162:165], v[82:85]
	v_mfma_f32_16x16x32_bf16 v[70:73], v[188:191], v[170:173], v[70:73]
	v_mfma_f32_16x16x32_bf16 v[66:69], v[196:199], v[170:173], v[66:69]
	v_mfma_f32_16x16x32_bf16 v[118:121], v[192:195], v[150:153], v[118:121]
	v_mfma_f32_16x16x32_bf16 v[114:117], v[224:227], v[150:153], v[114:117]
	v_mfma_f32_16x16x32_bf16 v[102:105], v[192:195], v[158:161], v[102:105]
	v_mfma_f32_16x16x32_bf16 v[98:101], v[224:227], v[158:161], v[98:101]
	v_mfma_f32_16x16x32_bf16 v[86:89], v[192:195], v[166:169], v[86:89]
	v_mfma_f32_16x16x32_bf16 v[82:85], v[224:227], v[166:169], v[82:85]
	v_mfma_f32_16x16x32_bf16 v[70:73], v[192:195], v[174:177], v[70:73]
	v_mfma_f32_16x16x32_bf16 v[66:69], v[224:227], v[174:177], v[66:69]
	s_barrier
	s_mov_b32 m0, s69
	v_lshl_add_u64 v[232:233], s[44:45], 0, v[0:1]
	ds_read_b128 v[146:149], v223 offset:16384
	ds_read_b128 v[150:153], v223 offset:17408
	ds_read_b128 v[154:157], v223 offset:18432
	ds_read_b128 v[158:161], v223 offset:19456
	ds_read_b128 v[162:165], v223 offset:20480
	ds_read_b128 v[166:169], v223 offset:21504
	ds_read_b128 v[170:173], v223 offset:22528
	ds_read_b128 v[174:177], v223 offset:23552
	global_load_lds_dwordx4 v[232:233], off
	v_lshl_add_u64 v[234:235], s[44:45], 0, v[182:183]
	s_mov_b32 m0, s74
	s_nop 0
	global_load_lds_dwordx4 v[234:235], off
	s_barrier
	s_waitcnt lgkmcnt(0)
	v_mfma_f32_16x16x32_bf16 v[62:65], v[130:133], v[146:149], v[62:65]
	v_mfma_f32_16x16x32_bf16 v[58:61], v[138:141], v[146:149], v[58:61]
	v_mfma_f32_16x16x32_bf16 v[46:49], v[130:133], v[154:157], v[46:49]
	v_mfma_f32_16x16x32_bf16 v[42:45], v[138:141], v[154:157], v[42:45]
	v_mfma_f32_16x16x32_bf16 v[30:33], v[130:133], v[162:165], v[30:33]
	v_mfma_f32_16x16x32_bf16 v[26:29], v[138:141], v[162:165], v[26:29]
	v_mfma_f32_16x16x32_bf16 v[14:17], v[130:133], v[170:173], v[14:17]
	v_mfma_f32_16x16x32_bf16 v[10:13], v[138:141], v[170:173], v[10:13]
	v_mfma_f32_16x16x32_bf16 v[62:65], v[134:137], v[150:153], v[62:65]
	v_mfma_f32_16x16x32_bf16 v[58:61], v[142:145], v[150:153], v[58:61]
	v_mfma_f32_16x16x32_bf16 v[46:49], v[134:137], v[158:161], v[46:49]
	v_mfma_f32_16x16x32_bf16 v[42:45], v[142:145], v[158:161], v[42:45]
	v_mfma_f32_16x16x32_bf16 v[30:33], v[134:137], v[166:169], v[30:33]
	v_mfma_f32_16x16x32_bf16 v[26:29], v[142:145], v[166:169], v[26:29]
	v_mfma_f32_16x16x32_bf16 v[14:17], v[134:137], v[174:177], v[14:17]
	v_mfma_f32_16x16x32_bf16 v[10:13], v[142:145], v[174:177], v[10:13]
	s_barrier
; #define PG8_STAGE(bufoff, gbase, voff) do { _Pragma("unroll") for (int _i = 0; _i < 2; ++_i) \
;         __builtin_amdgcn_global_load_lds((const unsigned*)((const char*)(gbase) + (voff)[_i]), (LAS unsigned*)(lds + (bufoff) + ldsw + _i * 8192), 16, 0, 0); } while (0)
; #define PG8_LDA(dst, b, h) do { _Pragma("unroll") for (int m = 0; m < 4; ++m) _Pragma("unroll") for (int k = 0; k < 2; ++k) dst[m][k] = *(const LAS bf16x8*)(lds + PG8_SA(b, h) + aoff + m * 2048 + k * 1024); } while (0)
; #define PG8_LDB(dst, b, h) do { _Pragma("unroll") for (int n = 0; n < 2; ++n) _Pragma("unroll") for (int k = 0; k < 2; ++k) dst[n][k] = *(const LAS bf16x8*)(lds + PG8_SB(b, h) + boff + n * 2048 + k * 1024); } while (0)
; #define PG8_MMA(ai, bj, At, Bt) do { __builtin_amdgcn_s_setprio(1); _Pragma("unroll") for (int m = 0; m < 4; ++m) _Pragma("unroll") for (int n = 0; n < 2; ++n) _Pragma("unroll") for (int k = 0; k < 2; ++k) \
;         acc[ai][bj][m][n] = __builtin_amdgcn_mfma_f32_16x16x32_bf16(Bt[n][k], At[m][k], acc[ai][bj][m][n], 0, 0, 0); __builtin_amdgcn_s_setprio(0); } while (0)
; #define PG8_WAIT_V(n) asm volatile("s_waitcnt vmcnt(" #n ")" ::: "memory")
; #define PG8_WAIT_L(n) asm volatile("s_waitcnt lgkmcnt(" #n ")" ::: "memory")
; #define PG8_BAR __builtin_amdgcn_s_barrier()
; #define PG8_SCHED __builtin_amdgcn_sched_barrier(0)
; template <int MODE, class EpiT, class Sched>
; __device__ __forceinline__ void gemm_phase(LAS unsigned char* lds, const Gemm g, const Sched& S, const EpiT& E) {
;     ...
;             PG8_STAGE(PG8_SB(0, 1), b2 + hstep, voffB);
;             PG8_WAIT_V(6); PG8_BAR; PG8_MMA(1, 1, At, B1); PG8_BAR;
;             PG8_LDB(B0, 1, 0); PG8_SCHED; PG8_LDA(At, 1, 0); PG8_STAGE(PG8_SA(0, 1), a2 + hstep, voffA);
;             PG8_WAIT_L(8); PG8_BAR; PG8_WAIT_L(0); PG8_MMA(0, 0, At, B0); PG8_BAR; PG8_SCHED;
;             PG8_LDB(B1, 1, 1); PG8_STAGE(PG8_SB(1, 0), b3, voffB);
;             PG8_BAR; PG8_WAIT_L(0); PG8_MMA(0, 1, At, B1); PG8_BAR;
	s_add_u32 s52, s52, s38
	s_addc_u32 s53, s53, 0
	s_add_i32 s30, s30, s68
	v_lshl_add_u64 v[236:237], s[52:53], 0, v[0:1]
	s_mov_b32 m0, s30
	v_lshl_add_u64 v[238:239], s[52:53], 0, v[182:183]
	global_load_lds_dwordx4 v[236:237], off
	s_add_i32 m0, s30, 0x2000
	s_nop 0
	global_load_lds_dwordx4 v[238:239], off
	s_waitcnt vmcnt(6)
	s_barrier
	v_mfma_f32_16x16x32_bf16 v[54:57], v[188:191], v[146:149], v[54:57]
	v_mfma_f32_16x16x32_bf16 v[50:53], v[196:199], v[146:149], v[50:53]
	v_mfma_f32_16x16x32_bf16 v[38:41], v[188:191], v[154:157], v[38:41]
	v_mfma_f32_16x16x32_bf16 v[34:37], v[196:199], v[154:157], v[34:37]
	v_mfma_f32_16x16x32_bf16 v[22:25], v[188:191], v[162:165], v[22:25]
	v_mfma_f32_16x16x32_bf16 v[18:21], v[196:199], v[162:165], v[18:21]
	v_mfma_f32_16x16x32_bf16 v[6:9], v[188:191], v[170:173], v[6:9]
	v_mfma_f32_16x16x32_bf16 v[2:5], v[196:199], v[170:173], v[2:5]
	v_mfma_f32_16x16x32_bf16 v[54:57], v[192:195], v[150:153], v[54:57]
	v_mfma_f32_16x16x32_bf16 v[50:53], v[224:227], v[150:153], v[50:53]
	v_mfma_f32_16x16x32_bf16 v[38:41], v[192:195], v[158:161], v[38:41]
	v_mfma_f32_16x16x32_bf16 v[34:37], v[224:227], v[158:161], v[34:37]
	v_mfma_f32_16x16x32_bf16 v[22:25], v[192:195], v[166:169], v[22:25]
	v_mfma_f32_16x16x32_bf16 v[18:21], v[224:227], v[166:169], v[18:21]
	v_mfma_f32_16x16x32_bf16 v[6:9], v[192:195], v[174:177], v[6:9]
	v_mfma_f32_16x16x32_bf16 v[2:5], v[224:227], v[174:177], v[2:5]
	s_barrier
	s_add_i32 s30, 0, 0x18000
	v_add_u32_e32 v142, s30, v220
	ds_read_b128 v[130:133], v142
	ds_read_b128 v[134:137], v142 offset:1024
	ds_read_b128 v[138:141], v142 offset:2048
	ds_read_b128 v[142:145], v142 offset:3072
	s_add_u32 s44, s44, s38
	s_addc_u32 s45, s45, 0
	s_mov_b32 m0, s75
	v_lshl_add_u64 v[188:189], s[44:45], 0, v[0:1]
	ds_read_b128 v[146:149], v223 offset:32768
	ds_read_b128 v[150:153], v223 offset:33792
	ds_read_b128 v[154:157], v223 offset:34816
	ds_read_b128 v[158:161], v223 offset:35840
	ds_read_b128 v[162:165], v223 offset:36864
	ds_read_b128 v[166:169], v223 offset:37888
	ds_read_b128 v[170:173], v223 offset:38912
	ds_read_b128 v[174:177], v223 offset:39936
	global_load_lds_dwordx4 v[188:189], off
	v_lshl_add_u64 v[188:189], s[44:45], 0, v[182:183]
	s_mov_b32 m0, s9
	s_nop 0
	global_load_lds_dwordx4 v[188:189], off
	s_waitcnt lgkmcnt(8)
	s_barrier
	s_waitcnt lgkmcnt(0)
	v_mfma_f32_16x16x32_bf16 v[126:129], v[130:133], v[146:149], v[126:129]
	v_mfma_f32_16x16x32_bf16 v[122:125], v[138:141], v[146:149], v[122:125]
	v_mfma_f32_16x16x32_bf16 v[110:113], v[130:133], v[154:157], v[110:113]
	v_mfma_f32_16x16x32_bf16 v[106:109], v[138:141], v[154:157], v[106:109]
	v_mfma_f32_16x16x32_bf16 v[94:97], v[130:133], v[162:165], v[94:97]
	v_mfma_f32_16x16x32_bf16 v[90:93], v[138:141], v[162:165], v[90:93]
	v_mfma_f32_16x16x32_bf16 v[78:81], v[130:133], v[170:173], v[78:81]
	v_mfma_f32_16x16x32_bf16 v[74:77], v[138:141], v[170:173], v[74:77]
	v_mfma_f32_16x16x32_bf16 v[126:129], v[134:137], v[150:153], v[126:129]
	v_mfma_f32_16x16x32_bf16 v[122:125], v[142:145], v[150:153], v[122:125]
	v_mfma_f32_16x16x32_bf16 v[110:113], v[134:137], v[158:161], v[110:113]
	v_mfma_f32_16x16x32_bf16 v[106:109], v[142:145], v[158:161], v[106:109]
	v_mfma_f32_16x16x32_bf16 v[94:97], v[134:137], v[166:169], v[94:97]
	v_mfma_f32_16x16x32_bf16 v[90:93], v[142:145], v[166:169], v[90:93]
	v_mfma_f32_16x16x32_bf16 v[78:81], v[134:137], v[174:177], v[78:81]
	v_mfma_f32_16x16x32_bf16 v[74:77], v[142:145], v[174:177], v[74:77]
	s_barrier
	s_add_i32 s44, 0, 0x1c000
	s_add_i32 s30, s30, s68
	v_add_u32_e32 v200, s44, v220
	v_lshl_add_u64 v[228:229], v[228:229], 0, s[76:77]
	s_mov_b32 m0, s30
	ds_read_b128 v[188:191], v200
	ds_read_b128 v[192:195], v200 offset:1024
	ds_read_b128 v[196:199], v200 offset:2048
	ds_read_b128 v[224:227], v200 offset:3072
	global_load_lds_dwordx4 v[228:229], off
	v_lshl_add_u64 v[228:229], v[230:231], 0, s[76:77]
	s_add_i32 m0, s30, 0x2000
	s_nop 0
	global_load_lds_dwordx4 v[228:229], off
	s_barrier
	s_waitcnt lgkmcnt(0)
	v_mfma_f32_16x16x32_bf16 v[118:121], v[188:191], v[146:149], v[118:121]
	v_mfma_f32_16x16x32_bf16 v[114:117], v[196:199], v[146:149], v[114:117]
	v_mfma_f32_16x16x32_bf16 v[102:105], v[188:191], v[154:157], v[102:105]
	v_mfma_f32_16x16x32_bf16 v[98:101], v[196:199], v[154:157], v[98:101]
	v_mfma_f32_16x16x32_bf16 v[86:89], v[188:191], v[162:165], v[86:89]
	v_mfma_f32_16x16x32_bf16 v[82:85], v[196:199], v[162:165], v[82:85]
	v_mfma_f32_16x16x32_bf16 v[70:73], v[188:191], v[170:173], v[70:73]
	v_mfma_f32_16x16x32_bf16 v[66:69], v[196:199], v[170:173], v[66:69]
	v_mfma_f32_16x16x32_bf16 v[118:121], v[192:195], v[150:153], v[118:121]
	v_mfma_f32_16x16x32_bf16 v[114:117], v[224:227], v[150:153], v[114:117]
	v_mfma_f32_16x16x32_bf16 v[102:105], v[192:195], v[158:161], v[102:105]
	v_mfma_f32_16x16x32_bf16 v[98:101], v[224:227], v[158:161], v[98:101]
	v_mfma_f32_16x16x32_bf16 v[86:89], v[192:195], v[166:169], v[86:89]
	v_mfma_f32_16x16x32_bf16 v[82:85], v[224:227], v[166:169], v[82:85]
	v_mfma_f32_16x16x32_bf16 v[70:73], v[192:195], v[174:177], v[70:73]
	v_mfma_f32_16x16x32_bf16 v[66:69], v[224:227], v[174:177], v[66:69]
	s_barrier
	s_mov_b32 m0, s57
	v_lshl_add_u64 v[228:229], v[232:233], 0, s[76:77]
	ds_read_b128 v[146:149], v223 offset:49152
	ds_read_b128 v[150:153], v223 offset:50176
	ds_read_b128 v[154:157], v223 offset:51200
	ds_read_b128 v[158:161], v223 offset:52224
	ds_read_b128 v[162:165], v223 offset:53248
	ds_read_b128 v[166:169], v223 offset:54272
	ds_read_b128 v[170:173], v223 offset:55296
	ds_read_b128 v[174:177], v223 offset:56320
	global_load_lds_dwordx4 v[228:229], off
	v_lshl_add_u64 v[228:229], v[234:235], 0, s[76:77]
	s_mov_b32 m0, s60
	s_nop 0
	global_load_lds_dwordx4 v[228:229], off
	s_barrier
; #define PG8_STAGE(bufoff, gbase, voff) do { _Pragma("unroll") for (int _i = 0; _i < 2; ++_i) \
;         __builtin_amdgcn_global_load_lds((const unsigned*)((const char*)(gbase) + (voff)[_i]), (LAS unsigned*)(lds + (bufoff) + ldsw + _i * 8192), 16, 0, 0); } while (0)
; #define PG8_LDA(dst, b, h) do { _Pragma("unroll") for (int m = 0; m < 4; ++m) _Pragma("unroll") for (int k = 0; k < 2; ++k) dst[m][k] = *(const LAS bf16x8*)(lds + PG8_SA(b, h) + aoff + m * 2048 + k * 1024); } while (0)
; #define PG8_MMA(ai, bj, At, Bt) do { __builtin_amdgcn_s_setprio(1); _Pragma("unroll") for (int m = 0; m < 4; ++m) _Pragma("unroll") for (int n = 0; n < 2; ++n) _Pragma("unroll") for (int k = 0; k < 2; ++k) \
;         acc[ai][bj][m][n] = __builtin_amdgcn_mfma_f32_16x16x32_bf16(Bt[n][k], At[m][k], acc[ai][bj][m][n], 0, 0, 0); __builtin_amdgcn_s_setprio(0); } while (0)
; #define PG8_WAIT_V(n) asm volatile("s_waitcnt vmcnt(" #n ")" ::: "memory")
;     __device__ __forceinline__ void scales2(const Unit& u, int wr, int fr, int fq, float& sA, float& sB) const {
;         const int rowA = u.pm * BM + wr * 64 + fq * 16 + fr;
;         const f32x4* pa = (const f32x4*)(ssq_in + (size_t)rowA * 16); const f32x4* pb = (const f32x4*)(ssq_in + (size_t)(rowA + HALF) * 16);
;         const f32x4 a0 = pa[0], a1 = pa[1], a2 = pa[2], a3 = pa[3], b0 = pb[0], b1 = pb[1], b2 = pb[2], b3 = pb[3];
;         const float ta = (((a0[0] + a0[1]) + (a0[2] + a0[3])) + ((a1[0] + a1[1]) + (a1[2] + a1[3]))) + (((a2[0] + a2[1]) + (a2[2] + a2[3])) + ((a3[0] + a3[1]) + (a3[2] + a3[3])));
;         const float tb = (((b0[0] + b0[1]) + (b0[2] + b0[3])) + ((b1[0] + b1[1]) + (b1[2] + b1[3]))) + (((b2[0] + b2[1]) + (b2[2] + b2[3])) + ((b3[0] + b3[1]) + (b3[2] + b3[3])));
;         sA = rsqrtf(ta * (1.0f / 1024.0f) + EPS); sB = rsqrtf(tb * (1.0f / 1024.0f) + EPS);
;     }
; template <int MODE, class EpiT, class Sched>
; __device__ __forceinline__ void gemm_phase(LAS unsigned char* lds, const Gemm g, const Sched& S, const EpiT& E) {
;     ...
;             PG8_BAR; PG8_WAIT_L(0); PG8_MMA(0, 1, At, B1); PG8_BAR;
;             PG8_LDA(At, 1, 1); PG8_STAGE(PG8_SA(1, 0), a3, voffA);
;             PG8_BAR; PG8_WAIT_L(0); PG8_MMA(1, 0, At, B0); PG8_BAR; PG8_SCHED;
;             PG8_STAGE(PG8_SB(1, 1), b3 + hstep, voffB);
;             PG8_WAIT_V(6); PG8_BAR; PG8_MMA(1, 1, At, B1); PG8_BAR;
;         }
	s_waitcnt lgkmcnt(0)
	v_mfma_f32_16x16x32_bf16 v[62:65], v[130:133], v[146:149], v[62:65]
	v_mfma_f32_16x16x32_bf16 v[58:61], v[138:141], v[146:149], v[58:61]
	v_mfma_f32_16x16x32_bf16 v[46:49], v[130:133], v[154:157], v[46:49]
	v_mfma_f32_16x16x32_bf16 v[42:45], v[138:141], v[154:157], v[42:45]
	v_mfma_f32_16x16x32_bf16 v[30:33], v[130:133], v[162:165], v[30:33]
	v_mfma_f32_16x16x32_bf16 v[26:29], v[138:141], v[162:165], v[26:29]
	v_mfma_f32_16x16x32_bf16 v[14:17], v[130:133], v[170:173], v[14:17]
	v_mfma_f32_16x16x32_bf16 v[10:13], v[138:141], v[170:173], v[10:13]
	v_mfma_f32_16x16x32_bf16 v[62:65], v[134:137], v[150:153], v[62:65]
	v_mfma_f32_16x16x32_bf16 v[58:61], v[142:145], v[150:153], v[58:61]
	v_mfma_f32_16x16x32_bf16 v[46:49], v[134:137], v[158:161], v[46:49]
	v_mfma_f32_16x16x32_bf16 v[42:45], v[142:145], v[158:161], v[42:45]
	v_mfma_f32_16x16x32_bf16 v[30:33], v[134:137], v[166:169], v[30:33]
	v_mfma_f32_16x16x32_bf16 v[26:29], v[142:145], v[166:169], v[26:29]
	v_mfma_f32_16x16x32_bf16 v[14:17], v[134:137], v[174:177], v[14:17]
	v_mfma_f32_16x16x32_bf16 v[10:13], v[142:145], v[174:177], v[10:13]
	s_barrier
	s_add_i32 s30, s44, s68
	v_lshl_add_u64 v[130:131], v[236:237], 0, s[76:77]
	s_mov_b32 m0, s30
	s_nop 0
	global_load_lds_dwordx4 v[130:131], off
	v_lshl_add_u64 v[130:131], v[238:239], 0, s[76:77]
	s_add_i32 m0, s30, 0x2000
	s_nop 0
	global_load_lds_dwordx4 v[130:131], off
	s_waitcnt vmcnt(6)
	s_barrier
	v_mfma_f32_16x16x32_bf16 v[54:57], v[188:191], v[146:149], v[54:57]
	v_mfma_f32_16x16x32_bf16 v[50:53], v[196:199], v[146:149], v[50:53]
	v_mfma_f32_16x16x32_bf16 v[38:41], v[188:191], v[154:157], v[38:41]
	v_mfma_f32_16x16x32_bf16 v[34:37], v[196:199], v[154:157], v[34:37]
	v_mfma_f32_16x16x32_bf16 v[22:25], v[188:191], v[162:165], v[22:25]
	v_mfma_f32_16x16x32_bf16 v[18:21], v[196:199], v[162:165], v[18:21]
	v_mfma_f32_16x16x32_bf16 v[6:9], v[188:191], v[170:173], v[6:9]
	v_mfma_f32_16x16x32_bf16 v[2:5], v[196:199], v[170:173], v[2:5]
	v_mfma_f32_16x16x32_bf16 v[54:57], v[192:195], v[150:153], v[54:57]
	v_mfma_f32_16x16x32_bf16 v[50:53], v[224:227], v[150:153], v[50:53]
	v_mfma_f32_16x16x32_bf16 v[38:41], v[192:195], v[158:161], v[38:41]
	v_mfma_f32_16x16x32_bf16 v[34:37], v[224:227], v[158:161], v[34:37]
	v_mfma_f32_16x16x32_bf16 v[22:25], v[192:195], v[166:169], v[22:25]
	v_mfma_f32_16x16x32_bf16 v[18:21], v[224:227], v[166:169], v[18:21]
	v_mfma_f32_16x16x32_bf16 v[6:9], v[192:195], v[174:177], v[6:9]
	v_mfma_f32_16x16x32_bf16 v[2:5], v[224:227], v[174:177], v[2:5]
	s_barrier
	s_add_u32 s4, s4, 0x100
	s_addc_u32 s5, s5, 0
	s_add_u32 s23, s23, 0x100
	s_addc_u32 s24, s24, 0
	s_cmp_ge_u32 s89, s21
	s_mov_b32 s30, s89
	s_cbranch_scc0 .LBB0_159
	s_lshl_b32 s4, s22, 8
	s_add_i32 s4, s4, s56
	v_or_b32_e32 v130, s4, v222
	v_ashrrev_i32_e32 v131, 31, v130
	v_lshlrev_b64 v[130:131], 6, v[130:131]
	v_lshl_add_u64 v[146:147], s[66:67], 0, v[130:131]
	global_load_dwordx4 v[130:133], v[146:147], off offset:16
	global_load_dwordx4 v[134:137], v[146:147], off offset:48
	global_load_dwordx4 v[138:141], v[146:147], off
	global_load_dwordx4 v[142:145], v[146:147], off offset:32
	v_or_b32_e32 v192, s4, v181
	s_mov_b64 s[4:5], 0x2000
	v_lshl_add_u64 v[158:159], v[146:147], 0, s[4:5]
	v_add_co_u32_e32 v146, vcc, 0x2000, v146
	s_mov_b32 s4, 0x3a800000
	s_nop 0
	v_addc_co_u32_e32 v147, vcc, 0, v147, vcc
	global_load_dwordx4 v[146:149], v[146:147], off
	s_nop 0
	global_load_dwordx4 v[150:153], v[158:159], off offset:16
	global_load_dwordx4 v[154:157], v[158:159], off offset:48
	s_nop 0
	global_load_dwordx4 v[158:161], v[158:159], off offset:32
	v_lshl_or_b32 v188, s2, 8, v221
	v_ashrrev_i32_e32 v193, 31, v192
	v_ashrrev_i32_e32 v189, 31, v188
	v_or_b32_e32 v194, 16, v192
	v_ashrrev_i32_e32 v195, 31, v194
	s_waitcnt vmcnt(0)
	v_mov_b32_e32 v162, v138
	v_mov_b32_e32 v163, v142
	v_mov_b32_e32 v142, v139
	v_pk_add_f32 v[138:139], v[162:163], v[142:143]
	v_mov_b32_e32 v142, v140
	v_mov_b32_e32 v143, v144
	v_mov_b32_e32 v144, v141
	v_pk_add_f32 v[140:141], v[142:143], v[144:145]
	s_nop 0
	v_pk_add_f32 v[138:139], v[138:139], v[140:141]
	v_mov_b32_e32 v140, v130
	v_mov_b32_e32 v141, v134
	v_mov_b32_e32 v134, v131
	v_pk_add_f32 v[130:131], v[140:141], v[134:135]
	v_mov_b32_e32 v134, v132
	v_mov_b32_e32 v135, v136
	v_mov_b32_e32 v136, v133
	v_pk_add_f32 v[132:133], v[134:135], v[136:137]
	v_mov_b32_e32 v134, v148
	v_pk_add_f32 v[130:131], v[130:131], v[132:133]
	v_mov_b32_e32 v132, v146
	v_mov_b32_e32 v133, v158
	v_mov_b32_e32 v158, v147
	v_mov_b32_e32 v135, v160
	v_mov_b32_e32 v160, v149
	v_pk_add_f32 v[132:133], v[132:133], v[158:159]
	v_pk_add_f32 v[134:135], v[134:135], v[160:161]
	v_mov_b32_e32 v136, v152
	v_pk_add_f32 v[132:133], v[132:133], v[134:135]
	v_mov_b32_e32 v134, v150
	v_mov_b32_e32 v135, v154
	v_mov_b32_e32 v154, v151
	v_mov_b32_e32 v137, v156
	v_mov_b32_e32 v156, v153
	v_pk_add_f32 v[134:135], v[134:135], v[154:155]
	v_pk_add_f32 v[136:137], v[136:137], v[156:157]
	v_pk_add_f32 v[130:131], v[138:139], v[130:131]
	v_pk_add_f32 v[134:135], v[134:135], v[136:137]
	s_nop 0
	v_pk_add_f32 v[132:133], v[132:133], v[134:135]
	v_mov_b32_e32 v135, v130
	v_mov_b32_e32 v134, v132
	v_mov_b32_e32 v130, v133
	v_pk_add_f32 v[130:131], v[134:135], v[130:131]
	s_nop 0
	v_pk_fma_f32 v[190:191], v[130:131], s[4:5], v[178:179] op_sel_hi:[1,0,0]
	s_mov_b32 s4, 0x800000
	v_mul_f32_e32 v130, 0x4b800000, v191
	v_cmp_gt_f32_e64 s[44:45], s4, v191
	v_cmp_gt_f32_e32 vcc, s4, v190
	s_nop 0
	v_cndmask_b32_e64 v130, v191, v130, s[44:45]
	v_rsq_f32_e32 v130, v130
	s_nop 0
	v_mul_f32_e32 v131, 0x45800000, v130
	v_cndmask_b32_e64 v226, v130, v131, s[44:45]
	v_lshlrev_b64 v[130:131], 10, v[192:193]
	v_lshl_add_u64 v[130:131], v[130:131], 0, v[188:189]
	v_lshlrev_b64 v[198:199], 1, v[130:131]
	v_lshl_add_u64 v[130:131], s[34:35], 0, v[198:199]
	v_lshl_add_u64 v[132:133], s[92:93], 0, v[198:199]
	global_load_dwordx4 v[170:173], v[130:131], off
	global_load_dwordx4 v[174:177], v[132:133], off
	v_lshl_add_u64 v[134:135], s[6:7], 0, v[198:199]
	global_load_dwordx4 v[166:169], v[134:135], off
	global_load_dwordx4 v[158:161], v[130:131], off offset:256
	global_load_dwordx4 v[162:165], v[132:133], off offset:256
	global_load_dwordx4 v[146:149], v[134:135], off offset:256
	v_and_b32_e32 v130, 64, v205
	v_or_b32_e32 v200, v130, v181
	v_lshlrev_b32_e32 v225, 2, v200
	ds_bpermute_b32 v200, v225, v226
	v_xor_b32_e32 v131, 16, v205
	v_add_u32_e32 v130, 64, v130
	v_cmp_lt_i32_e64 s[44:45], v131, v130
	s_waitcnt lgkmcnt(0)
;     template <int mode> __device__ __forceinline__ void run(const f32x4 (&acc)[2][2][4][2], const Unit& u, int wr, int wc, int fr, int fq, const LAS float* sc) const {
;     ...
;                 if (g < 7) {
;                     const size_t offn = (size_t)(row0 + ((g + 1) >> 2) * HALF + ((g + 1) & 3) * 16) * D + col0;
; #pragma unroll
;                     for (int bj = 0; bj < 2; ++bj) {
;                         const size_t o = offn + bj * HALF;
;                         if (mode == 5) { xi[nb][2 * bj] = *(const f32x4*)(xin + o); xi[nb][2 * bj + 1] = *(const f32x4*)(xin + o + 4); }
;                         else { xh[nb][bj] = *(const u32x4*)(hin + o); xl[nb][bj] = *(const u32x4*)(lin + o); }
;                         if (mode == 4) pq[nb][bj] = *(const u32x4*)(ob + o);
;                     }
;                 }
;                 float s = 1.f;
;                 if (mode == 4) s = __shfl(ai ? sB : sA, m * 16 + fr);
;                 float ss = 0.f;
; #pragma unroll
;                 for (int bj = 0; bj < 2; ++bj) {
;                     u32x4 wh, wl;
; #pragma unroll
;                     for (int n = 0; n < 2; ++n) {
;                         const int q = 2 * bj + n;
;                         const unsigned h0 = n ? xh[cb][bj].z : xh[cb][bj].x, h1 = n ? xh[cb][bj].w : xh[cb][bj].y, l0 = n ? xl[cb][bj].z : xl[cb][bj].x, l1 = n ? xl[cb][bj].w : xl[cb][bj].y;
;                         f32x4 xo;
;                         if (mode == 5) xo = xi[cb][q];
;                         else { xo[0] = bf_lo(h0) + bf_lo(l0); xo[1] = bf_hi(h0) + bf_hi(l0); xo[2] = bf_lo(h1) + bf_lo(l1); xo[3] = bf_hi(h1) + bf_hi(l1); }
;                         f32x4 v;
;                         if (mode != 4) v = xo + acc[ai][bj][m][n] * alpha + bvv[q];
;                         else {
;                             const f32x4 a = acc[ai][bj][m][n] * s;
;                             const unsigned p0 = n ? pq[cb][bj].z : pq[cb][bj].x, p1 = n ? pq[cb][bj].w : pq[cb][bj].y;
;                             v[0] = xo[0] + sigmoidf_(a[0]) * bf_lo(p0); v[1] = xo[1] + sigmoidf_(a[1]) * bf_hi(p0);
;                             v[2] = xo[2] + sigmoidf_(a[2]) * bf_lo(p1); v[3] = xo[3] + sigmoidf_(a[3]) * bf_hi(p1);
;                         }
;                         const unsigned w0 = pk2(v[0], v[1]), w1 = pk2(v[2], v[3]);
	v_pk_mul_f32 v[126:127], v[126:127], v[200:201] op_sel_hi:[1,0]
	v_cndmask_b32_e64 v131, v205, v131, s[44:45]
	v_lshlrev_b32_e32 v191, 2, v131
	v_xor_b32_e32 v131, 32, v205
	v_mul_f32_e32 v126, 0xbfb8aa3b, v126
	v_cmp_lt_i32_e64 s[44:45], v131, v130
	v_exp_f32_e32 v126, v126
	v_pk_mul_f32 v[128:129], v[128:129], v[200:201] op_sel_hi:[1,0]
	v_cndmask_b32_e64 v130, v205, v131, s[44:45]
	v_lshlrev_b32_e32 v224, 2, v130
	v_lshlrev_b64 v[130:131], 10, v[194:195]
	v_lshl_add_u64 v[130:131], v[130:131], 0, v[188:189]
	v_lshlrev_b64 v[196:197], 1, v[130:131]
	v_add_f32_e32 v126, 1.0, v126
	v_lshl_add_u64 v[130:131], s[34:35], 0, v[196:197]
	v_lshl_add_u64 v[132:133], s[92:93], 0, v[196:197]
	v_lshl_add_u64 v[228:229], s[6:7], 0, v[196:197]
	v_rcp_f32_e32 v126, v126
	global_load_dwordx4 v[150:153], v[130:131], off
	global_load_dwordx4 v[154:157], v[132:133], off
	global_load_dwordx4 v[142:145], v[228:229], off
	global_load_dwordx4 v[134:137], v[130:131], off offset:256
	global_load_dwordx4 v[138:141], v[132:133], off offset:256
	s_nop 0
	global_load_dwordx4 v[130:133], v[228:229], off offset:256
	v_pk_mul_f32 v[122:123], v[122:123], v[200:201] op_sel_hi:[1,0]
	v_pk_mul_f32 v[124:125], v[124:125], v[200:201] op_sel_hi:[1,0]
	v_mul_f32_e32 v122, 0xbfb8aa3b, v122
	v_exp_f32_e32 v122, v122
	v_pk_mul_f32 v[118:119], v[118:119], v[200:201] op_sel_hi:[1,0]
	v_pk_mul_f32 v[120:121], v[120:121], v[200:201] op_sel_hi:[1,0]
	v_mul_f32_e32 v118, 0xbfb8aa3b, v118
	v_add_f32_e32 v122, 1.0, v122
	v_rcp_f32_e32 v122, v122
	v_exp_f32_e32 v118, v118
	v_pk_mul_f32 v[114:115], v[114:115], v[200:201] op_sel_hi:[1,0]
	v_pk_mul_f32 v[116:117], v[116:117], v[200:201] op_sel_hi:[1,0]
	v_mul_f32_e32 v114, 0xbfb8aa3b, v114
	v_add_f32_e32 v118, 1.0, v118
	v_rcp_f32_e32 v118, v118
	v_exp_f32_e32 v114, v114
	s_lshl_b32 s44, s2, 2
	s_ashr_i32 s45, s44, 31
	v_add_f32_e32 v114, 1.0, v114
	v_rcp_f32_e32 v114, v114
	s_waitcnt vmcnt(11)
	v_lshlrev_b32_e32 v227, 16, v170
	s_waitcnt vmcnt(10)
	v_lshlrev_b32_e32 v228, 16, v174
	v_and_b32_e32 v174, 0xffff0000, v174
	v_and_b32_e32 v170, 0xffff0000, v170
	v_add_f32_e32 v227, v228, v227
	v_add_f32_e32 v170, v174, v170
	v_lshlrev_b32_e32 v174, 16, v171
	v_lshlrev_b32_e32 v228, 16, v175
	v_and_b32_e32 v175, 0xffff0000, v175
	v_and_b32_e32 v171, 0xffff0000, v171
	v_add_f32_e32 v171, v175, v171
	s_waitcnt vmcnt(9)
	v_lshlrev_b32_e32 v175, 16, v166
	v_fmac_f32_e32 v227, v126, v175
	v_mul_f32_e32 v126, 0xbfb8aa3b, v127
	v_exp_f32_e32 v126, v126
	v_and_b32_e32 v127, 0xffff0000, v166
	v_add_f32_e32 v174, v228, v174
	v_add_f32_e32 v126, 1.0, v126
	v_rcp_f32_e32 v126, v126
	s_nop 0
	v_fmac_f32_e32 v170, v126, v127
	v_mul_f32_e32 v126, 0xbfb8aa3b, v128
	v_exp_f32_e32 v126, v126
	v_lshlrev_b32_e32 v127, 16, v167
	v_add_f32_e32 v126, 1.0, v126
	v_rcp_f32_e32 v126, v126
	s_nop 0
	v_fmac_f32_e32 v174, v126, v127
	v_mul_f32_e32 v126, 0xbfb8aa3b, v129
	v_exp_f32_e32 v126, v126
	v_and_b32_e32 v127, 0xffff0000, v167
	v_add_f32_e32 v126, 1.0, v126
	v_rcp_f32_e32 v126, v126
	s_nop 0
	v_fmac_f32_e32 v171, v126, v127
	v_cvt_pk_bf16_f32 v126, v227, v170
	v_cvt_pk_bf16_f32 v127, v174, v171
	s_nop 0
	v_lshlrev_b32_e32 v128, 16, v126
	v_and_b32_e32 v129, 0xffff0000, v126
	v_sub_f32_e32 v128, v227, v128
	v_sub_f32_e32 v129, v170, v129
	v_cvt_pk_bf16_f32 v166, v128, v129
	v_lshlrev_b32_e32 v128, 16, v127
	v_and_b32_e32 v129, 0xffff0000, v127
	v_sub_f32_e32 v128, v174, v128
	v_sub_f32_e32 v129, v171, v129
	v_cvt_pk_bf16_f32 v167, v128, v129
	v_mul_f32_e32 v128, v170, v170
	v_mul_f32_e32 v129, v171, v171
	v_fmac_f32_e32 v128, v227, v227
	v_fmac_f32_e32 v129, v174, v174
	v_add_f32_e32 v170, v128, v129
	v_lshlrev_b32_e32 v128, 16, v172
	v_lshlrev_b32_e32 v129, 16, v176
	v_add_f32_e32 v171, v129, v128
	v_and_b32_e32 v128, 0xffff0000, v176
	v_and_b32_e32 v129, 0xffff0000, v172
	v_add_f32_e32 v172, v128, v129
	v_lshlrev_b32_e32 v128, 16, v173
	v_lshlrev_b32_e32 v129, 16, v177
	v_add_f32_e32 v174, v129, v128
	v_and_b32_e32 v128, 0xffff0000, v177
	v_and_b32_e32 v129, 0xffff0000, v173
	v_add_f32_e32 v173, v128, v129
	v_lshlrev_b32_e32 v128, 16, v168
	v_fmac_f32_e32 v171, v122, v128
	v_mul_f32_e32 v122, 0xbfb8aa3b, v123
	v_exp_f32_e32 v122, v122
	v_and_b32_e32 v123, 0xffff0000, v168
	v_add_f32_e32 v122, 1.0, v122
	v_rcp_f32_e32 v122, v122
	s_nop 0
	v_fmac_f32_e32 v172, v122, v123
	v_mul_f32_e32 v122, 0xbfb8aa3b, v124
	v_exp_f32_e32 v122, v122
	v_lshlrev_b32_e32 v123, 16, v169
	v_cvt_pk_bf16_f32 v128, v171, v172
	v_add_f32_e32 v122, 1.0, v122
	v_rcp_f32_e32 v122, v122
	s_nop 0
	v_fmac_f32_e32 v174, v122, v123
	v_mul_f32_e32 v122, 0xbfb8aa3b, v125
	v_exp_f32_e32 v122, v122
	v_and_b32_e32 v123, 0xffff0000, v169
	v_lshl_add_u64 v[124:125], s[28:29], 0, v[198:199]
	v_add_f32_e32 v122, 1.0, v122
	v_rcp_f32_e32 v122, v122
	s_nop 0
	v_fmac_f32_e32 v173, v122, v123
	v_lshlrev_b32_e32 v122, 16, v128
	v_and_b32_e32 v123, 0xffff0000, v128
	v_sub_f32_e32 v122, v171, v122
	v_sub_f32_e32 v123, v172, v123
	v_cvt_pk_bf16_f32 v129, v174, v173
	v_cvt_pk_bf16_f32 v168, v122, v123
	s_nop 0
	v_lshlrev_b32_e32 v122, 16, v129
	v_and_b32_e32 v123, 0xffff0000, v129
	v_sub_f32_e32 v122, v174, v122
	v_sub_f32_e32 v123, v173, v123
	v_cvt_pk_bf16_f32 v169, v122, v123
	v_mul_f32_e32 v122, v172, v172
	v_mul_f32_e32 v123, v173, v173
	v_fmac_f32_e32 v122, v171, v171
	v_fmac_f32_e32 v123, v174, v174
	v_add_f32_e32 v122, v122, v123
	v_add_f32_e32 v170, v170, v122
	v_lshl_add_u64 v[122:123], s[10:11], 0, v[198:199]
	global_store_dwordx4 v[122:123], v[126:129], off
	global_store_dwordx4 v[124:125], v[166:169], off
	s_waitcnt vmcnt(10)
; __device__ __forceinline__ float bf_lo(unsigned w) { return __uint_as_float(w << 16); }
; __device__ __forceinline__ float bf_hi(unsigned w) { return __uint_as_float(w & 0xffff0000u); }
;     template <int mode> __device__ __forceinline__ void run(const f32x4 (&acc)[2][2][4][2], const Unit& u, int wr, int wc, int fr, int fq, const LAS float* sc) const {
;     ...
;                 for (int bj = 0; bj < 2; ++bj) {
;                     u32x4 wh, wl;
; #pragma unroll
;                     for (int n = 0; n < 2; ++n) {
;                         const int q = 2 * bj + n;
;                         const unsigned h0 = n ? xh[cb][bj].z : xh[cb][bj].x, h1 = n ? xh[cb][bj].w : xh[cb][bj].y, l0 = n ? xl[cb][bj].z : xl[cb][bj].x, l1 = n ? xl[cb][bj].w : xl[cb][bj].y;
;                         f32x4 xo;
;                         if (mode == 5) xo = xi[cb][q];
;                         else { xo[0] = bf_lo(h0) + bf_lo(l0); xo[1] = bf_hi(h0) + bf_hi(l0); xo[2] = bf_lo(h1) + bf_lo(l1); xo[3] = bf_hi(h1) + bf_hi(l1); }
;                         f32x4 v;
;                         if (mode != 4) v = xo + acc[ai][bj][m][n] * alpha + bvv[q];
;                         else {
;                             const f32x4 a = acc[ai][bj][m][n] * s;
;                             const unsigned p0 = n ? pq[cb][bj].z : pq[cb][bj].x, p1 = n ? pq[cb][bj].w : pq[cb][bj].y;
;                             v[0] = xo[0] + sigmoidf_(a[0]) * bf_lo(p0); v[1] = xo[1] + sigmoidf_(a[1]) * bf_hi(p0);
;                             v[2] = xo[2] + sigmoidf_(a[2]) * bf_lo(p1); v[3] = xo[3] + sigmoidf_(a[3]) * bf_hi(p1);
;                         }
;                         const unsigned w0 = pk2(v[0], v[1]), w1 = pk2(v[2], v[3]);
;                         const unsigned m0 = pk2(v[0] - bf_lo(w0), v[1] - bf_hi(w0)), m1 = pk2(v[2] - bf_lo(w1), v[3] - bf_hi(w1));
;                         if (n == 0) { wh.x = w0; wh.y = w1; wl.x = m0; wl.y = m1; } else { wh.z = w0; wh.w = w1; wl.z = m0; wl.w = m1; }
;                         ss += (v[0] * v[0] + v[1] * v[1]) + (v[2] * v[2] + v[3] * v[3]);
;                     }
;                     *(u32x4*)(xb + off + bj * HALF) = wh;
;                     *(u32x4*)(lout + off + bj * HALF) = wl;
;                 }
;                 ss += __shfl_xor(ss, 16); ss += __shfl_xor(ss, 32);
;                 if (fq == 0) ssq_out[(size_t)row * 16 + u.pn * 4 + wc] = ss;
	v_lshlrev_b32_e32 v126, 16, v158
	s_waitcnt vmcnt(9)
	v_lshlrev_b32_e32 v127, 16, v162
	v_add_f32_e32 v128, v127, v126
	v_and_b32_e32 v126, 0xffff0000, v162
	v_and_b32_e32 v127, 0xffff0000, v158
	v_add_f32_e32 v129, v126, v127
	v_lshlrev_b32_e32 v126, 16, v159
	v_lshlrev_b32_e32 v127, 16, v163
	v_add_f32_e32 v158, v127, v126
	v_and_b32_e32 v126, 0xffff0000, v163
	v_and_b32_e32 v127, 0xffff0000, v159
	v_add_f32_e32 v159, v126, v127
	s_waitcnt vmcnt(8)
	v_lshlrev_b32_e32 v126, 16, v146
	v_fmac_f32_e32 v128, v118, v126
	v_mul_f32_e32 v118, 0xbfb8aa3b, v119
	v_exp_f32_e32 v118, v118
	v_and_b32_e32 v119, 0xffff0000, v146
	v_add_f32_e32 v118, 1.0, v118
	v_rcp_f32_e32 v118, v118
	s_nop 0
	v_fmac_f32_e32 v129, v118, v119
	v_mul_f32_e32 v118, 0xbfb8aa3b, v120
	v_exp_f32_e32 v118, v118
	v_lshlrev_b32_e32 v119, 16, v147
	v_add_f32_e32 v118, 1.0, v118
	v_rcp_f32_e32 v118, v118
	s_nop 0
	v_fmac_f32_e32 v158, v118, v119
	v_mul_f32_e32 v118, 0xbfb8aa3b, v121
	v_exp_f32_e32 v118, v118
	v_and_b32_e32 v119, 0xffff0000, v147
	v_add_f32_e32 v118, 1.0, v118
	v_rcp_f32_e32 v118, v118
	s_nop 0
	v_fmac_f32_e32 v159, v118, v119
	v_cvt_pk_bf16_f32 v118, v128, v129
	v_cvt_pk_bf16_f32 v119, v158, v159
	s_nop 0
	v_lshlrev_b32_e32 v120, 16, v118
	v_and_b32_e32 v121, 0xffff0000, v118
	v_sub_f32_e32 v120, v128, v120
	v_sub_f32_e32 v121, v129, v121
	v_cvt_pk_bf16_f32 v126, v120, v121
	v_lshlrev_b32_e32 v120, 16, v119
	v_and_b32_e32 v121, 0xffff0000, v119
	v_sub_f32_e32 v120, v158, v120
	v_sub_f32_e32 v121, v159, v121
	v_cvt_pk_bf16_f32 v127, v120, v121
	v_mul_f32_e32 v120, v129, v129
	v_mul_f32_e32 v121, v159, v159
	v_fmac_f32_e32 v120, v128, v128
	v_fmac_f32_e32 v121, v158, v158
	v_add_f32_e32 v120, v120, v121
	v_add_f32_e32 v146, v120, v170
	v_lshlrev_b32_e32 v120, 16, v160
	v_lshlrev_b32_e32 v121, 16, v164
	v_add_f32_e32 v147, v121, v120
	v_and_b32_e32 v120, 0xffff0000, v164
	v_and_b32_e32 v121, 0xffff0000, v160
	v_add_f32_e32 v158, v120, v121
	v_lshlrev_b32_e32 v120, 16, v161
	v_lshlrev_b32_e32 v121, 16, v165
	v_add_f32_e32 v159, v121, v120
	v_and_b32_e32 v120, 0xffff0000, v165
	v_and_b32_e32 v121, 0xffff0000, v161
	v_add_f32_e32 v160, v120, v121
	v_lshlrev_b32_e32 v120, 16, v148
	v_fmac_f32_e32 v147, v114, v120
	v_mul_f32_e32 v114, 0xbfb8aa3b, v115
	v_exp_f32_e32 v114, v114
	v_and_b32_e32 v115, 0xffff0000, v148
	v_add_f32_e32 v114, 1.0, v114
	v_rcp_f32_e32 v114, v114
	s_nop 0
	v_fmac_f32_e32 v158, v114, v115
	v_mul_f32_e32 v114, 0xbfb8aa3b, v116
	v_exp_f32_e32 v114, v114
	v_lshlrev_b32_e32 v115, 16, v149
	v_cvt_pk_bf16_f32 v120, v147, v158
	v_add_f32_e32 v114, 1.0, v114
	v_rcp_f32_e32 v114, v114
	s_nop 0
	v_fmac_f32_e32 v159, v114, v115
	v_mul_f32_e32 v114, 0xbfb8aa3b, v117
	v_exp_f32_e32 v114, v114
	v_and_b32_e32 v115, 0xffff0000, v149
	v_add_f32_e32 v114, 1.0, v114
	v_rcp_f32_e32 v114, v114
	s_nop 0
	v_fmac_f32_e32 v160, v114, v115
	v_lshlrev_b32_e32 v114, 16, v120
	v_and_b32_e32 v115, 0xffff0000, v120
	v_sub_f32_e32 v114, v147, v114
	v_sub_f32_e32 v115, v158, v115
	v_cvt_pk_bf16_f32 v121, v159, v160
	v_cvt_pk_bf16_f32 v128, v114, v115
	s_nop 0
	v_lshlrev_b32_e32 v114, 16, v121
	v_and_b32_e32 v115, 0xffff0000, v121
	v_sub_f32_e32 v114, v159, v114
	v_sub_f32_e32 v115, v160, v115
	v_cvt_pk_bf16_f32 v129, v114, v115
	v_mul_f32_e32 v114, v158, v158
	v_mul_f32_e32 v115, v160, v160
	v_fmac_f32_e32 v114, v147, v147
	v_fmac_f32_e32 v115, v159, v159
	v_add_f32_e32 v114, v114, v115
	v_add_f32_e32 v114, v114, v146
	ds_bpermute_b32 v115, v191, v114
	global_store_dwordx4 v[122:123], v[118:121], off offset:256
	global_store_dwordx4 v[124:125], v[126:129], off offset:256
	s_waitcnt lgkmcnt(0)
	v_add_f32_e32 v114, v114, v115
	ds_bpermute_b32 v115, v224, v114
	s_and_saveexec_b64 s[4:5], s[40:41]
	s_cbranch_execz .LBB0_162
	v_lshlrev_b64 v[116:117], 6, v[192:193]
	v_lshl_add_u64 v[116:117], s[62:63], 0, v[116:117]
	v_lshl_add_u64 v[116:117], s[44:45], 2, v[116:117]
	s_lshl_b32 s24, s20, 2
	v_lshl_add_u64 v[116:117], v[116:117], 0, s[24:25]
	s_waitcnt lgkmcnt(0)
	v_add_f32_e32 v114, v114, v115
	global_store_dword v[116:117], v114, off

; #define PG8_STAGE(bufoff, gbase, voff) do { _Pragma("unroll") for (int _i = 0; _i < 2; ++_i) \
;         __builtin_amdgcn_global_load_lds((const unsigned*)((const char*)(gbase) + (voff)[_i]), (LAS unsigned*)(lds + (bufoff) + ldsw + _i * 8192), 16, 0, 0); } while (0)
; #define PG8_LDA(dst, b, h) do { _Pragma("unroll") for (int m = 0; m < 4; ++m) _Pragma("unroll") for (int k = 0; k < 2; ++k) dst[m][k] = *(const LAS bf16x8*)(lds + PG8_SA(b, h) + aoff + m * 2048 + k * 1024); } while (0)
; #define PG8_LDB(dst, b, h) do { _Pragma("unroll") for (int n = 0; n < 2; ++n) _Pragma("unroll") for (int k = 0; k < 2; ++k) dst[n][k] = *(const LAS bf16x8*)(lds + PG8_SB(b, h) + boff + n * 2048 + k * 1024); } while (0)
; #define PG8_MMA(ai, bj, At, Bt) do { __builtin_amdgcn_s_setprio(1); _Pragma("unroll") for (int m = 0; m < 4; ++m) _Pragma("unroll") for (int n = 0; n < 2; ++n) _Pragma("unroll") for (int k = 0; k < 2; ++k) \
;         acc[ai][bj][m][n] = __builtin_amdgcn_mfma_f32_16x16x32_bf16(Bt[n][k], At[m][k], acc[ai][bj][m][n], 0, 0, 0); __builtin_amdgcn_s_setprio(0); } while (0)
; #define PG8_WAIT_L(n) asm volatile("s_waitcnt lgkmcnt(" #n ")" ::: "memory")
; #define PG8_BAR __builtin_amdgcn_s_barrier()
; #define PG8_SCHED __builtin_amdgcn_sched_barrier(0)
; template <int MODE, class EpiT, class Sched>
; __device__ __forceinline__ void gemm_phase(LAS unsigned char* lds, const Gemm g, const Sched& S, const EpiT& E) {
;     ...
;         for (int t = 0; t < nt; t += 2) {
;             const bool last = (t == nt - 2);
;             const char* a1 = cA + (size_t)(t + 1) * kstep;
;             const char* a2 = last ? nA : cA + (size_t)(t + 2) * kstep; const char* b2 = last ? nB : cB + (size_t)(t + 2) * kstep;
;             const char* a3 = a2 + kstep; const char* b3 = b2 + kstep;
;             PG8_LDB(B0, 0, 0); PG8_SCHED; PG8_LDA(At, 0, 0); PG8_STAGE(PG8_SA(1, 1), a1 + hstep, voffA);
;             PG8_WAIT_L(8); PG8_BAR; PG8_WAIT_L(0); PG8_MMA(0, 0, At, B0); PG8_BAR; PG8_SCHED;
;             PG8_LDB(B1, 0, 1); PG8_STAGE(PG8_SB(0, 0), b2, voffB);
;             PG8_BAR; PG8_WAIT_L(0); PG8_MMA(0, 1, At, B1); PG8_BAR;
;             PG8_LDA(At, 0, 1); PG8_STAGE(PG8_SA(0, 0), a2, voffA);
;             PG8_BAR; PG8_WAIT_L(0); PG8_MMA(1, 0, At, B0); PG8_BAR; PG8_SCHED;
.LBB0_195:
	s_add_i32 vcc_lo, s44, 2
	s_add_u32 s52, s4, 0x80
	s_addc_u32 s45, s5, 0
	s_add_i32 s58, 0, 0x10000
	v_add_u32_e32 v74, s58, v194
	ds_read_b128 v[58:61], v74
	ds_read_b128 v[62:65], v74 offset:1024
	ds_read_b128 v[70:73], v74 offset:2048
	ds_read_b128 v[74:77], v74 offset:3072
	s_cmp_eq_u32 s75, s44
	s_cselect_b32 s44, s68, s52
	s_cselect_b32 s45, s69, s45
	s_cselect_b32 s53, s47, s90
	s_cselect_b32 s52, s46, s89
	v_lshl_add_u64 v[188:189], s[4:5], 0, v[176:177]
	s_add_i32 m0, s21, 0xc000
	ds_read_b128 v[138:141], v196
	ds_read_b128 v[142:145], v196 offset:1024
	ds_read_b128 v[146:149], v196 offset:2048
	ds_read_b128 v[150:153], v196 offset:3072
	ds_read_b128 v[162:165], v196 offset:4096
	ds_read_b128 v[166:169], v196 offset:5120
	ds_read_b128 v[170:173], v196 offset:6144
	ds_read_b128 v[184:187], v196 offset:7168
	global_load_lds_dwordx4 v[188:189], off
	v_lshl_add_u64 v[188:189], s[4:5], 0, v[182:183]
	s_add_i32 m0, s21, 0xe000
	s_nop 0
	global_load_lds_dwordx4 v[188:189], off
	s_waitcnt lgkmcnt(8)
	s_barrier
	s_waitcnt lgkmcnt(0)
	v_mfma_f32_16x16x32_bf16 v[158:161], v[58:61], v[138:141], v[158:161]
	v_mfma_f32_16x16x32_bf16 v[154:157], v[70:73], v[138:141], v[154:157]
	v_mfma_f32_16x16x32_bf16 v[126:129], v[58:61], v[146:149], v[126:129]
	v_mfma_f32_16x16x32_bf16 v[122:125], v[70:73], v[146:149], v[122:125]
	v_mfma_f32_16x16x32_bf16 v[110:113], v[58:61], v[162:165], v[110:113]
	v_mfma_f32_16x16x32_bf16 v[106:109], v[70:73], v[162:165], v[106:109]
	v_mfma_f32_16x16x32_bf16 v[94:97], v[58:61], v[170:173], v[94:97]
	v_mfma_f32_16x16x32_bf16 v[90:93], v[70:73], v[170:173], v[90:93]
	v_mfma_f32_16x16x32_bf16 v[158:161], v[62:65], v[142:145], v[158:161]
	v_mfma_f32_16x16x32_bf16 v[154:157], v[74:77], v[142:145], v[154:157]
	v_mfma_f32_16x16x32_bf16 v[126:129], v[62:65], v[150:153], v[126:129]
	v_mfma_f32_16x16x32_bf16 v[122:125], v[74:77], v[150:153], v[122:125]
	v_mfma_f32_16x16x32_bf16 v[110:113], v[62:65], v[166:169], v[110:113]
	v_mfma_f32_16x16x32_bf16 v[106:109], v[74:77], v[166:169], v[106:109]
	v_mfma_f32_16x16x32_bf16 v[94:97], v[62:65], v[184:187], v[94:97]
	v_mfma_f32_16x16x32_bf16 v[90:93], v[74:77], v[184:187], v[90:93]
	s_barrier
	s_add_i32 s59, 0, 0x14000
	v_add_u32_e32 v192, s59, v194
	s_add_i32 s58, s58, s20
	ds_read_b128 v[188:191], v192
	ds_read_b128 v[220:223], v192 offset:1024
	ds_read_b128 v[224:227], v192 offset:2048
	ds_read_b128 v[228:231], v192 offset:3072
	v_lshl_add_u64 v[192:193], s[52:53], 0, v[0:1]
	s_mov_b32 m0, s58
	v_lshl_add_u64 v[198:199], s[52:53], 0, v[174:175]
	global_load_lds_dwordx4 v[192:193], off
	s_add_i32 m0, s58, 0x2000
	s_nop 0
	global_load_lds_dwordx4 v[198:199], off
	s_barrier
	s_waitcnt lgkmcnt(0)
	v_mfma_f32_16x16x32_bf16 v[134:137], v[188:191], v[138:141], v[134:137]
	v_mfma_f32_16x16x32_bf16 v[130:133], v[224:227], v[138:141], v[130:133]
	v_mfma_f32_16x16x32_bf16 v[118:121], v[188:191], v[146:149], v[118:121]
	v_mfma_f32_16x16x32_bf16 v[114:117], v[224:227], v[146:149], v[114:117]
	v_mfma_f32_16x16x32_bf16 v[102:105], v[188:191], v[162:165], v[102:105]
	v_mfma_f32_16x16x32_bf16 v[98:101], v[224:227], v[162:165], v[98:101]
	v_mfma_f32_16x16x32_bf16 v[86:89], v[188:191], v[170:173], v[86:89]
	v_mfma_f32_16x16x32_bf16 v[82:85], v[224:227], v[170:173], v[82:85]
	v_mfma_f32_16x16x32_bf16 v[134:137], v[220:223], v[142:145], v[134:137]
	v_mfma_f32_16x16x32_bf16 v[130:133], v[228:231], v[142:145], v[130:133]
	v_mfma_f32_16x16x32_bf16 v[118:121], v[220:223], v[150:153], v[118:121]
	v_mfma_f32_16x16x32_bf16 v[114:117], v[228:231], v[150:153], v[114:117]
	v_mfma_f32_16x16x32_bf16 v[102:105], v[220:223], v[166:169], v[102:105]
	v_mfma_f32_16x16x32_bf16 v[98:101], v[228:231], v[166:169], v[98:101]
	v_mfma_f32_16x16x32_bf16 v[86:89], v[220:223], v[184:187], v[86:89]
	v_mfma_f32_16x16x32_bf16 v[82:85], v[228:231], v[184:187], v[82:85]
	s_barrier
	s_mov_b32 m0, s21
	v_lshl_add_u64 v[232:233], s[44:45], 0, v[0:1]
	ds_read_b128 v[138:141], v196 offset:16384
	ds_read_b128 v[142:145], v196 offset:17408
	ds_read_b128 v[146:149], v196 offset:18432
	ds_read_b128 v[150:153], v196 offset:19456
	ds_read_b128 v[162:165], v196 offset:20480
	ds_read_b128 v[166:169], v196 offset:21504
	ds_read_b128 v[170:173], v196 offset:22528
	ds_read_b128 v[184:187], v196 offset:23552
	global_load_lds_dwordx4 v[232:233], off
	v_lshl_add_u64 v[234:235], s[44:45], 0, v[174:175]
	s_mov_b32 m0, s50
	s_nop 0
	global_load_lds_dwordx4 v[234:235], off
	s_barrier
	s_waitcnt lgkmcnt(0)
	v_mfma_f32_16x16x32_bf16 v[78:81], v[58:61], v[138:141], v[78:81]
	v_mfma_f32_16x16x32_bf16 v[66:69], v[70:73], v[138:141], v[66:69]
	v_mfma_f32_16x16x32_bf16 v[46:49], v[58:61], v[146:149], v[46:49]
	v_mfma_f32_16x16x32_bf16 v[42:45], v[70:73], v[146:149], v[42:45]
	v_mfma_f32_16x16x32_bf16 v[30:33], v[58:61], v[162:165], v[30:33]
	v_mfma_f32_16x16x32_bf16 v[26:29], v[70:73], v[162:165], v[26:29]
	v_mfma_f32_16x16x32_bf16 v[14:17], v[58:61], v[170:173], v[14:17]
	v_mfma_f32_16x16x32_bf16 v[10:13], v[70:73], v[170:173], v[10:13]
	v_mfma_f32_16x16x32_bf16 v[78:81], v[62:65], v[142:145], v[78:81]
	v_mfma_f32_16x16x32_bf16 v[66:69], v[74:77], v[142:145], v[66:69]
	v_mfma_f32_16x16x32_bf16 v[46:49], v[62:65], v[150:153], v[46:49]
	v_mfma_f32_16x16x32_bf16 v[42:45], v[74:77], v[150:153], v[42:45]
	v_mfma_f32_16x16x32_bf16 v[30:33], v[62:65], v[166:169], v[30:33]
	v_mfma_f32_16x16x32_bf16 v[26:29], v[74:77], v[166:169], v[26:29]
	v_mfma_f32_16x16x32_bf16 v[14:17], v[62:65], v[184:187], v[14:17]
	v_mfma_f32_16x16x32_bf16 v[10:13], v[74:77], v[184:187], v[10:13]
	s_barrier
; #define PG8_STAGE(bufoff, gbase, voff) do { _Pragma("unroll") for (int _i = 0; _i < 2; ++_i) \
;         __builtin_amdgcn_global_load_lds((const unsigned*)((const char*)(gbase) + (voff)[_i]), (LAS unsigned*)(lds + (bufoff) + ldsw + _i * 8192), 16, 0, 0); } while (0)
; #define PG8_LDA(dst, b, h) do { _Pragma("unroll") for (int m = 0; m < 4; ++m) _Pragma("unroll") for (int k = 0; k < 2; ++k) dst[m][k] = *(const LAS bf16x8*)(lds + PG8_SA(b, h) + aoff + m * 2048 + k * 1024); } while (0)
; #define PG8_LDB(dst, b, h) do { _Pragma("unroll") for (int n = 0; n < 2; ++n) _Pragma("unroll") for (int k = 0; k < 2; ++k) dst[n][k] = *(const LAS bf16x8*)(lds + PG8_SB(b, h) + boff + n * 2048 + k * 1024); } while (0)
; #define PG8_MMA(ai, bj, At, Bt) do { __builtin_amdgcn_s_setprio(1); _Pragma("unroll") for (int m = 0; m < 4; ++m) _Pragma("unroll") for (int n = 0; n < 2; ++n) _Pragma("unroll") for (int k = 0; k < 2; ++k) \
;         acc[ai][bj][m][n] = __builtin_amdgcn_mfma_f32_16x16x32_bf16(Bt[n][k], At[m][k], acc[ai][bj][m][n], 0, 0, 0); __builtin_amdgcn_s_setprio(0); } while (0)
; #define PG8_WAIT_V(n) asm volatile("s_waitcnt vmcnt(" #n ")" ::: "memory")
; #define PG8_WAIT_L(n) asm volatile("s_waitcnt lgkmcnt(" #n ")" ::: "memory")
; #define PG8_BAR __builtin_amdgcn_s_barrier()
; #define PG8_SCHED __builtin_amdgcn_sched_barrier(0)
; template <int MODE, class EpiT, class Sched>
; __device__ __forceinline__ void gemm_phase(LAS unsigned char* lds, const Gemm g, const Sched& S, const EpiT& E) {
;     ...
;             PG8_STAGE(PG8_SB(0, 1), b2 + hstep, voffB);
;             PG8_WAIT_V(6); PG8_BAR; PG8_MMA(1, 1, At, B1); PG8_BAR;
;             PG8_LDB(B0, 1, 0); PG8_SCHED; PG8_LDA(At, 1, 0); PG8_STAGE(PG8_SA(0, 1), a2 + hstep, voffA);
;             PG8_WAIT_L(8); PG8_BAR; PG8_WAIT_L(0); PG8_MMA(0, 0, At, B0); PG8_BAR; PG8_SCHED;
;             PG8_LDB(B1, 1, 1); PG8_STAGE(PG8_SB(1, 0), b3, voffB);
;             PG8_BAR; PG8_WAIT_L(0); PG8_MMA(0, 1, At, B1); PG8_BAR;
	s_add_u32 s52, s52, s38
	s_addc_u32 s53, s53, 0
	s_add_i32 s58, s59, s20
	v_lshl_add_u64 v[236:237], s[52:53], 0, v[0:1]
	s_mov_b32 m0, s58
	v_lshl_add_u64 v[238:239], s[52:53], 0, v[174:175]
	global_load_lds_dwordx4 v[236:237], off
	s_add_i32 m0, s58, 0x2000
	s_nop 0
	global_load_lds_dwordx4 v[238:239], off
	s_waitcnt vmcnt(6)
	s_barrier
	v_mfma_f32_16x16x32_bf16 v[54:57], v[188:191], v[138:141], v[54:57]
	v_mfma_f32_16x16x32_bf16 v[50:53], v[224:227], v[138:141], v[50:53]
	v_mfma_f32_16x16x32_bf16 v[38:41], v[188:191], v[146:149], v[38:41]
	v_mfma_f32_16x16x32_bf16 v[34:37], v[224:227], v[146:149], v[34:37]
	v_mfma_f32_16x16x32_bf16 v[22:25], v[188:191], v[162:165], v[22:25]
	v_mfma_f32_16x16x32_bf16 v[18:21], v[224:227], v[162:165], v[18:21]
	v_mfma_f32_16x16x32_bf16 v[6:9], v[188:191], v[170:173], v[6:9]
	v_mfma_f32_16x16x32_bf16 v[2:5], v[224:227], v[170:173], v[2:5]
	v_mfma_f32_16x16x32_bf16 v[54:57], v[220:223], v[142:145], v[54:57]
	v_mfma_f32_16x16x32_bf16 v[50:53], v[228:231], v[142:145], v[50:53]
	v_mfma_f32_16x16x32_bf16 v[38:41], v[220:223], v[150:153], v[38:41]
	v_mfma_f32_16x16x32_bf16 v[34:37], v[228:231], v[150:153], v[34:37]
	v_mfma_f32_16x16x32_bf16 v[22:25], v[220:223], v[166:169], v[22:25]
	v_mfma_f32_16x16x32_bf16 v[18:21], v[228:231], v[166:169], v[18:21]
	v_mfma_f32_16x16x32_bf16 v[6:9], v[220:223], v[184:187], v[6:9]
	v_mfma_f32_16x16x32_bf16 v[2:5], v[228:231], v[184:187], v[2:5]
	s_barrier
	s_add_i32 s52, 0, 0x18000
	v_add_u32_e32 v74, s52, v194
	ds_read_b128 v[58:61], v74
	ds_read_b128 v[62:65], v74 offset:1024
	ds_read_b128 v[70:73], v74 offset:2048
	ds_read_b128 v[74:77], v74 offset:3072
	s_add_u32 s44, s44, s38
	s_addc_u32 s45, s45, 0
	s_mov_b32 m0, s51
	v_lshl_add_u64 v[188:189], s[44:45], 0, v[0:1]
	ds_read_b128 v[138:141], v196 offset:32768
	ds_read_b128 v[142:145], v196 offset:33792
	ds_read_b128 v[146:149], v196 offset:34816
	ds_read_b128 v[150:153], v196 offset:35840
	ds_read_b128 v[162:165], v196 offset:36864
	ds_read_b128 v[166:169], v196 offset:37888
	ds_read_b128 v[170:173], v196 offset:38912
	ds_read_b128 v[184:187], v196 offset:39936
	global_load_lds_dwordx4 v[188:189], off
	v_lshl_add_u64 v[188:189], s[44:45], 0, v[174:175]
	s_mov_b32 m0, s56
	s_nop 0
	global_load_lds_dwordx4 v[188:189], off
	s_waitcnt lgkmcnt(8)
	s_barrier
	s_waitcnt lgkmcnt(0)
	v_mfma_f32_16x16x32_bf16 v[158:161], v[58:61], v[138:141], v[158:161]
	v_mfma_f32_16x16x32_bf16 v[154:157], v[70:73], v[138:141], v[154:157]
	v_mfma_f32_16x16x32_bf16 v[126:129], v[58:61], v[146:149], v[126:129]
	v_mfma_f32_16x16x32_bf16 v[122:125], v[70:73], v[146:149], v[122:125]
	v_mfma_f32_16x16x32_bf16 v[110:113], v[58:61], v[162:165], v[110:113]
	v_mfma_f32_16x16x32_bf16 v[106:109], v[70:73], v[162:165], v[106:109]
	v_mfma_f32_16x16x32_bf16 v[94:97], v[58:61], v[170:173], v[94:97]
	v_mfma_f32_16x16x32_bf16 v[90:93], v[70:73], v[170:173], v[90:93]
	v_mfma_f32_16x16x32_bf16 v[158:161], v[62:65], v[142:145], v[158:161]
	v_mfma_f32_16x16x32_bf16 v[154:157], v[74:77], v[142:145], v[154:157]
	v_mfma_f32_16x16x32_bf16 v[126:129], v[62:65], v[150:153], v[126:129]
	v_mfma_f32_16x16x32_bf16 v[122:125], v[74:77], v[150:153], v[122:125]
	v_mfma_f32_16x16x32_bf16 v[110:113], v[62:65], v[166:169], v[110:113]
	v_mfma_f32_16x16x32_bf16 v[106:109], v[74:77], v[166:169], v[106:109]
	v_mfma_f32_16x16x32_bf16 v[94:97], v[62:65], v[184:187], v[94:97]
	v_mfma_f32_16x16x32_bf16 v[90:93], v[74:77], v[184:187], v[90:93]
	s_barrier
	s_add_i32 s44, 0, 0x1c000
	s_add_i32 s45, s52, s20
	v_add_u32_e32 v197, s44, v194
	v_lshl_add_u64 v[192:193], v[192:193], 0, s[76:77]
	s_mov_b32 m0, s45
	ds_read_b128 v[188:191], v197
	ds_read_b128 v[220:223], v197 offset:1024
	ds_read_b128 v[224:227], v197 offset:2048
	ds_read_b128 v[228:231], v197 offset:3072
	global_load_lds_dwordx4 v[192:193], off
	v_lshl_add_u64 v[192:193], v[198:199], 0, s[76:77]
	s_add_i32 m0, s45, 0x2000
	s_nop 0
	global_load_lds_dwordx4 v[192:193], off
	s_barrier
; #define PG8_STAGE(bufoff, gbase, voff) do { _Pragma("unroll") for (int _i = 0; _i < 2; ++_i) \
;         __builtin_amdgcn_global_load_lds((const unsigned*)((const char*)(gbase) + (voff)[_i]), (LAS unsigned*)(lds + (bufoff) + ldsw + _i * 8192), 16, 0, 0); } while (0)
; #define PG8_LDA(dst, b, h) do { _Pragma("unroll") for (int m = 0; m < 4; ++m) _Pragma("unroll") for (int k = 0; k < 2; ++k) dst[m][k] = *(const LAS bf16x8*)(lds + PG8_SA(b, h) + aoff + m * 2048 + k * 1024); } while (0)
; #define PG8_MMA(ai, bj, At, Bt) do { __builtin_amdgcn_s_setprio(1); _Pragma("unroll") for (int m = 0; m < 4; ++m) _Pragma("unroll") for (int n = 0; n < 2; ++n) _Pragma("unroll") for (int k = 0; k < 2; ++k) \
;         acc[ai][bj][m][n] = __builtin_amdgcn_mfma_f32_16x16x32_bf16(Bt[n][k], At[m][k], acc[ai][bj][m][n], 0, 0, 0); __builtin_amdgcn_s_setprio(0); } while (0)
; #define PG8_WAIT_V(n) asm volatile("s_waitcnt vmcnt(" #n ")" ::: "memory")
; #define PG8_WAIT_L(n) asm volatile("s_waitcnt lgkmcnt(" #n ")" ::: "memory")
; #define PG8_BAR __builtin_amdgcn_s_barrier()
; #define PG8_SCHED __builtin_amdgcn_sched_barrier(0)
;     template <int mode> __device__ __forceinline__ void run(const f32x4 (&acc)[2][2][4][2], const Unit& u, int wr, int wc, int fr, int fq, const LAS float* sc) const {
;     ...
;             f32x4 bvv[4];
; #pragma unroll
;             for (int q = 0; q < 4; ++q) bvv[q] = (mode != 4 && bias) ? *(const f32x4*)(bias + col0 + (q >> 1) * HALF + (q & 1) * 4) : (f32x4){0.f, 0.f, 0.f, 0.f};
; template <int MODE, class EpiT, class Sched>
; __device__ __forceinline__ void gemm_phase(LAS unsigned char* lds, const Gemm g, const Sched& S, const EpiT& E) {
;     ...
;             PG8_BAR; PG8_WAIT_L(0); PG8_MMA(0, 1, At, B1); PG8_BAR;
;             PG8_LDA(At, 1, 1); PG8_STAGE(PG8_SA(1, 0), a3, voffA);
;             PG8_BAR; PG8_WAIT_L(0); PG8_MMA(1, 0, At, B0); PG8_BAR; PG8_SCHED;
;             PG8_STAGE(PG8_SB(1, 1), b3 + hstep, voffB);
;             PG8_WAIT_V(6); PG8_BAR; PG8_MMA(1, 1, At, B1); PG8_BAR;
;         }
	s_waitcnt lgkmcnt(0)
	v_mfma_f32_16x16x32_bf16 v[134:137], v[188:191], v[138:141], v[134:137]
	v_mfma_f32_16x16x32_bf16 v[130:133], v[224:227], v[138:141], v[130:133]
	v_mfma_f32_16x16x32_bf16 v[118:121], v[188:191], v[146:149], v[118:121]
	v_mfma_f32_16x16x32_bf16 v[114:117], v[224:227], v[146:149], v[114:117]
	v_mfma_f32_16x16x32_bf16 v[102:105], v[188:191], v[162:165], v[102:105]
	v_mfma_f32_16x16x32_bf16 v[98:101], v[224:227], v[162:165], v[98:101]
	v_mfma_f32_16x16x32_bf16 v[86:89], v[188:191], v[170:173], v[86:89]
	v_mfma_f32_16x16x32_bf16 v[82:85], v[224:227], v[170:173], v[82:85]
	v_mfma_f32_16x16x32_bf16 v[134:137], v[220:223], v[142:145], v[134:137]
	v_mfma_f32_16x16x32_bf16 v[130:133], v[228:231], v[142:145], v[130:133]
	v_mfma_f32_16x16x32_bf16 v[118:121], v[220:223], v[150:153], v[118:121]
	v_mfma_f32_16x16x32_bf16 v[114:117], v[228:231], v[150:153], v[114:117]
	v_mfma_f32_16x16x32_bf16 v[102:105], v[220:223], v[166:169], v[102:105]
	v_mfma_f32_16x16x32_bf16 v[98:101], v[228:231], v[166:169], v[98:101]
	v_mfma_f32_16x16x32_bf16 v[86:89], v[220:223], v[184:187], v[86:89]
	v_mfma_f32_16x16x32_bf16 v[82:85], v[228:231], v[184:187], v[82:85]
	s_barrier
	s_mov_b32 m0, s61
	v_lshl_add_u64 v[192:193], v[232:233], 0, s[76:77]
	ds_read_b128 v[138:141], v196 offset:49152
	ds_read_b128 v[142:145], v196 offset:50176
	ds_read_b128 v[146:149], v196 offset:51200
	ds_read_b128 v[150:153], v196 offset:52224
	ds_read_b128 v[162:165], v196 offset:53248
	ds_read_b128 v[166:169], v196 offset:54272
	ds_read_b128 v[170:173], v196 offset:55296
	ds_read_b128 v[184:187], v196 offset:56320
	global_load_lds_dwordx4 v[192:193], off
	v_lshl_add_u64 v[192:193], v[234:235], 0, s[76:77]
	s_mov_b32 m0, s74
	s_nop 0
	global_load_lds_dwordx4 v[192:193], off
	s_barrier
	s_waitcnt lgkmcnt(0)
	v_mfma_f32_16x16x32_bf16 v[78:81], v[58:61], v[138:141], v[78:81]
	v_mfma_f32_16x16x32_bf16 v[66:69], v[70:73], v[138:141], v[66:69]
	v_mfma_f32_16x16x32_bf16 v[46:49], v[58:61], v[146:149], v[46:49]
	v_mfma_f32_16x16x32_bf16 v[42:45], v[70:73], v[146:149], v[42:45]
	v_mfma_f32_16x16x32_bf16 v[30:33], v[58:61], v[162:165], v[30:33]
	v_mfma_f32_16x16x32_bf16 v[26:29], v[70:73], v[162:165], v[26:29]
	v_mfma_f32_16x16x32_bf16 v[14:17], v[58:61], v[170:173], v[14:17]
	v_mfma_f32_16x16x32_bf16 v[10:13], v[70:73], v[170:173], v[10:13]
	v_mfma_f32_16x16x32_bf16 v[78:81], v[62:65], v[142:145], v[78:81]
	v_mfma_f32_16x16x32_bf16 v[66:69], v[74:77], v[142:145], v[66:69]
	v_mfma_f32_16x16x32_bf16 v[46:49], v[62:65], v[150:153], v[46:49]
	v_mfma_f32_16x16x32_bf16 v[42:45], v[74:77], v[150:153], v[42:45]
	v_mfma_f32_16x16x32_bf16 v[30:33], v[62:65], v[166:169], v[30:33]
	v_mfma_f32_16x16x32_bf16 v[26:29], v[74:77], v[166:169], v[26:29]
	v_mfma_f32_16x16x32_bf16 v[14:17], v[62:65], v[184:187], v[14:17]
	v_mfma_f32_16x16x32_bf16 v[10:13], v[74:77], v[184:187], v[10:13]
	s_barrier
	s_add_i32 s44, s44, s20
	v_lshl_add_u64 v[58:59], v[236:237], 0, s[76:77]
	s_mov_b32 m0, s44
	s_nop 0
	global_load_lds_dwordx4 v[58:59], off
	v_lshl_add_u64 v[58:59], v[238:239], 0, s[76:77]
	s_add_i32 m0, s44, 0x2000
	s_nop 0
	global_load_lds_dwordx4 v[58:59], off
	s_waitcnt vmcnt(6)
	s_barrier
	v_mfma_f32_16x16x32_bf16 v[54:57], v[188:191], v[138:141], v[54:57]
	v_mfma_f32_16x16x32_bf16 v[50:53], v[224:227], v[138:141], v[50:53]
	v_mfma_f32_16x16x32_bf16 v[38:41], v[188:191], v[146:149], v[38:41]
	v_mfma_f32_16x16x32_bf16 v[34:37], v[224:227], v[146:149], v[34:37]
	v_mfma_f32_16x16x32_bf16 v[22:25], v[188:191], v[162:165], v[22:25]
	v_mfma_f32_16x16x32_bf16 v[18:21], v[224:227], v[162:165], v[18:21]
	v_mfma_f32_16x16x32_bf16 v[6:9], v[188:191], v[170:173], v[6:9]
	v_mfma_f32_16x16x32_bf16 v[2:5], v[224:227], v[170:173], v[2:5]
	v_mfma_f32_16x16x32_bf16 v[54:57], v[220:223], v[142:145], v[54:57]
	v_mfma_f32_16x16x32_bf16 v[50:53], v[228:231], v[142:145], v[50:53]
	v_mfma_f32_16x16x32_bf16 v[38:41], v[220:223], v[150:153], v[38:41]
	v_mfma_f32_16x16x32_bf16 v[34:37], v[228:231], v[150:153], v[34:37]
	v_mfma_f32_16x16x32_bf16 v[22:25], v[220:223], v[166:169], v[22:25]
	v_mfma_f32_16x16x32_bf16 v[18:21], v[228:231], v[166:169], v[18:21]
	v_mfma_f32_16x16x32_bf16 v[6:9], v[220:223], v[184:187], v[6:9]
	v_mfma_f32_16x16x32_bf16 v[2:5], v[228:231], v[184:187], v[2:5]
	s_barrier
	s_add_u32 s4, s4, 0x100
	s_addc_u32 s5, s5, 0
	s_add_u32 s89, s89, 0x100
	s_addc_u32 s90, s90, 0
	s_cmp_ge_u32 vcc_lo, s60
	s_mov_b32 s44, vcc_lo
	s_cbranch_scc0 .LBB0_195
	v_lshl_or_b32 v186, s24, 8, v195
	v_ashrrev_i32_e32 v187, 31, v186
	v_mov_b32_e32 v70, 0
	v_cndmask_b32_e64 v58, 0, 1, s[78:79]
	v_lshl_add_u64 v[138:139], v[186:187], 2, s[12:13]
	v_cmp_ne_u32_e64 s[44:45], 1, v58
	s_andn2_b64 vcc, exec, s[78:79]
	v_mov_b32_e32 v74, 0
	v_mov_b32_e32 v75, v70
	v_mov_b32_e32 v184, 0
	v_mov_b32_e32 v185, v70
	s_cbranch_vccnz .LBB0_198
	global_load_dwordx4 v[74:77], v[138:139], off
	s_waitcnt vmcnt(0)
	v_mov_b32_e32 v184, v76
	v_mov_b32_e32 v185, v77

; #define PG8_STAGE(bufoff, gbase, voff) do { _Pragma("unroll") for (int _i = 0; _i < 2; ++_i) \
;         __builtin_amdgcn_global_load_lds((const unsigned*)((const char*)(gbase) + (voff)[_i]), (LAS unsigned*)(lds + (bufoff) + ldsw + _i * 8192), 16, 0, 0); } while (0)
; #define PG8_LDA(dst, b, h) do { _Pragma("unroll") for (int m = 0; m < 4; ++m) _Pragma("unroll") for (int k = 0; k < 2; ++k) dst[m][k] = *(const LAS bf16x8*)(lds + PG8_SA(b, h) + aoff + m * 2048 + k * 1024); } while (0)
; #define PG8_LDB(dst, b, h) do { _Pragma("unroll") for (int n = 0; n < 2; ++n) _Pragma("unroll") for (int k = 0; k < 2; ++k) dst[n][k] = *(const LAS bf16x8*)(lds + PG8_SB(b, h) + boff + n * 2048 + k * 1024); } while (0)
; #define PG8_MMA(ai, bj, At, Bt) do { __builtin_amdgcn_s_setprio(1); _Pragma("unroll") for (int m = 0; m < 4; ++m) _Pragma("unroll") for (int n = 0; n < 2; ++n) _Pragma("unroll") for (int k = 0; k < 2; ++k) \
;         acc[ai][bj][m][n] = __builtin_amdgcn_mfma_f32_16x16x32_bf16(Bt[n][k], At[m][k], acc[ai][bj][m][n], 0, 0, 0); __builtin_amdgcn_s_setprio(0); } while (0)
; #define PG8_WAIT_L(n) asm volatile("s_waitcnt lgkmcnt(" #n ")" ::: "memory")
; #define PG8_BAR __builtin_amdgcn_s_barrier()
; #define PG8_SCHED __builtin_amdgcn_sched_barrier(0)
; template <int MODE, class EpiT, class Sched>
; __device__ __forceinline__ void gemm_phase(LAS unsigned char* lds, const Gemm g, const Sched& S, const EpiT& E) {
;     ...
;         for (int t = 0; t < nt; t += 2) {
;             const bool last = (t == nt - 2);
;             const char* a1 = cA + (size_t)(t + 1) * kstep;
;             const char* a2 = last ? nA : cA + (size_t)(t + 2) * kstep; const char* b2 = last ? nB : cB + (size_t)(t + 2) * kstep;
;             const char* a3 = a2 + kstep; const char* b3 = b2 + kstep;
;             PG8_LDB(B0, 0, 0); PG8_SCHED; PG8_LDA(At, 0, 0); PG8_STAGE(PG8_SA(1, 1), a1 + hstep, voffA);
;             PG8_WAIT_L(8); PG8_BAR; PG8_WAIT_L(0); PG8_MMA(0, 0, At, B0); PG8_BAR; PG8_SCHED;
;             PG8_LDB(B1, 0, 1); PG8_STAGE(PG8_SB(0, 0), b2, voffB);
;             PG8_BAR; PG8_WAIT_L(0); PG8_MMA(0, 1, At, B1); PG8_BAR;
;             PG8_LDA(At, 0, 1); PG8_STAGE(PG8_SA(0, 0), a2, voffA);
;             PG8_BAR; PG8_WAIT_L(0); PG8_MMA(1, 0, At, B0); PG8_BAR; PG8_SCHED;
.LBB0_236:
	s_add_i32 s44, s34, 2
	s_add_u32 s38, s28, 0x80
	s_addc_u32 s35, s29, 0
	s_add_i32 s45, 0, 0x10000
	v_add_u32_e32 v136, s45, v139
	ds_read_b128 v[142:145], v136
	ds_read_b128 v[146:149], v136 offset:1024
	ds_read_b128 v[150:153], v136 offset:2048
	ds_read_b128 v[154:157], v136 offset:3072
	s_cmp_eq_u32 s52, s34
	s_cselect_b32 s34, s4, s38
	s_cselect_b32 s35, s5, s35
	s_cselect_b32 s39, s11, s43
	s_cselect_b32 s38, s10, s42
	v_lshl_add_u64 v[136:137], s[28:29], 0, v[132:133]
	s_add_i32 m0, s22, 0xc000
	ds_read_b128 v[158:161], v141
	ds_read_b128 v[162:165], v141 offset:1024
	ds_read_b128 v[166:169], v141 offset:2048
	ds_read_b128 v[170:173], v141 offset:3072
	ds_read_b128 v[174:177], v141 offset:4096
	ds_read_b128 v[182:185], v141 offset:5120
	ds_read_b128 v[186:189], v141 offset:6144
	ds_read_b128 v[190:193], v141 offset:7168
	global_load_lds_dwordx4 v[136:137], off
	v_lshl_add_u64 v[136:137], s[28:29], 0, v[134:135]
	s_add_i32 m0, s22, 0xe000
	s_nop 0
	global_load_lds_dwordx4 v[136:137], off
	s_waitcnt lgkmcnt(8)
	s_barrier
	s_waitcnt lgkmcnt(0)
	v_mfma_f32_16x16x32_bf16 v[126:129], v[142:145], v[158:161], v[126:129]
	v_mfma_f32_16x16x32_bf16 v[122:125], v[150:153], v[158:161], v[122:125]
	v_mfma_f32_16x16x32_bf16 v[118:121], v[142:145], v[166:169], v[118:121]
	v_mfma_f32_16x16x32_bf16 v[110:113], v[150:153], v[166:169], v[110:113]
	v_mfma_f32_16x16x32_bf16 v[102:105], v[142:145], v[174:177], v[102:105]
	v_mfma_f32_16x16x32_bf16 v[94:97], v[150:153], v[174:177], v[94:97]
	v_mfma_f32_16x16x32_bf16 v[86:89], v[142:145], v[186:189], v[86:89]
	v_mfma_f32_16x16x32_bf16 v[78:81], v[150:153], v[186:189], v[78:81]
	v_mfma_f32_16x16x32_bf16 v[126:129], v[146:149], v[162:165], v[126:129]
	v_mfma_f32_16x16x32_bf16 v[122:125], v[154:157], v[162:165], v[122:125]
	v_mfma_f32_16x16x32_bf16 v[118:121], v[146:149], v[170:173], v[118:121]
	v_mfma_f32_16x16x32_bf16 v[110:113], v[154:157], v[170:173], v[110:113]
	v_mfma_f32_16x16x32_bf16 v[102:105], v[146:149], v[182:185], v[102:105]
	v_mfma_f32_16x16x32_bf16 v[94:97], v[154:157], v[182:185], v[94:97]
	v_mfma_f32_16x16x32_bf16 v[86:89], v[146:149], v[190:193], v[86:89]
	v_mfma_f32_16x16x32_bf16 v[78:81], v[154:157], v[190:193], v[78:81]
	s_barrier
	s_add_i32 s58, 0, 0x14000
	v_add_u32_e32 v136, s58, v139
	s_add_i32 s45, s45, s9
	ds_read_b128 v[194:197], v136
	ds_read_b128 v[220:223], v136 offset:1024
	ds_read_b128 v[224:227], v136 offset:2048
	ds_read_b128 v[228:231], v136 offset:3072
	v_lshl_add_u64 v[136:137], s[38:39], 0, v[0:1]
	s_mov_b32 m0, s45
	v_lshl_add_u64 v[198:199], s[38:39], 0, v[130:131]
	global_load_lds_dwordx4 v[136:137], off
	s_add_i32 m0, s45, 0x2000
	s_nop 0
	global_load_lds_dwordx4 v[198:199], off
	s_barrier
	s_waitcnt lgkmcnt(0)
	v_mfma_f32_16x16x32_bf16 v[114:117], v[194:197], v[158:161], v[114:117]
	v_mfma_f32_16x16x32_bf16 v[106:109], v[224:227], v[158:161], v[106:109]
	v_mfma_f32_16x16x32_bf16 v[98:101], v[194:197], v[166:169], v[98:101]
	v_mfma_f32_16x16x32_bf16 v[90:93], v[224:227], v[166:169], v[90:93]
	v_mfma_f32_16x16x32_bf16 v[82:85], v[194:197], v[174:177], v[82:85]
	v_mfma_f32_16x16x32_bf16 v[74:77], v[224:227], v[174:177], v[74:77]
	v_mfma_f32_16x16x32_bf16 v[70:73], v[194:197], v[186:189], v[70:73]
	v_mfma_f32_16x16x32_bf16 v[66:69], v[224:227], v[186:189], v[66:69]
	v_mfma_f32_16x16x32_bf16 v[114:117], v[220:223], v[162:165], v[114:117]
	v_mfma_f32_16x16x32_bf16 v[106:109], v[228:231], v[162:165], v[106:109]
	v_mfma_f32_16x16x32_bf16 v[98:101], v[220:223], v[170:173], v[98:101]
	v_mfma_f32_16x16x32_bf16 v[90:93], v[228:231], v[170:173], v[90:93]
	v_mfma_f32_16x16x32_bf16 v[82:85], v[220:223], v[182:185], v[82:85]
	v_mfma_f32_16x16x32_bf16 v[74:77], v[228:231], v[182:185], v[74:77]
	v_mfma_f32_16x16x32_bf16 v[70:73], v[220:223], v[190:193], v[70:73]
	v_mfma_f32_16x16x32_bf16 v[66:69], v[228:231], v[190:193], v[66:69]
	s_barrier
	s_mov_b32 m0, s22
	v_lshl_add_u64 v[232:233], s[34:35], 0, v[0:1]
	ds_read_b128 v[158:161], v141 offset:16384
	ds_read_b128 v[162:165], v141 offset:17408
	ds_read_b128 v[166:169], v141 offset:18432
	ds_read_b128 v[170:173], v141 offset:19456
	ds_read_b128 v[174:177], v141 offset:20480
	ds_read_b128 v[182:185], v141 offset:21504
	ds_read_b128 v[186:189], v141 offset:22528
	ds_read_b128 v[190:193], v141 offset:23552
	global_load_lds_dwordx4 v[232:233], off
	v_lshl_add_u64 v[234:235], s[34:35], 0, v[130:131]
	s_mov_b32 m0, s23
	s_nop 0
	global_load_lds_dwordx4 v[234:235], off
	s_barrier
	s_waitcnt lgkmcnt(0)
	v_mfma_f32_16x16x32_bf16 v[62:65], v[142:145], v[158:161], v[62:65]
	v_mfma_f32_16x16x32_bf16 v[58:61], v[150:153], v[158:161], v[58:61]
	v_mfma_f32_16x16x32_bf16 v[54:57], v[142:145], v[166:169], v[54:57]
	v_mfma_f32_16x16x32_bf16 v[46:49], v[150:153], v[166:169], v[46:49]
	v_mfma_f32_16x16x32_bf16 v[38:41], v[142:145], v[174:177], v[38:41]
	v_mfma_f32_16x16x32_bf16 v[30:33], v[150:153], v[174:177], v[30:33]
	v_mfma_f32_16x16x32_bf16 v[22:25], v[142:145], v[186:189], v[22:25]
	v_mfma_f32_16x16x32_bf16 v[14:17], v[150:153], v[186:189], v[14:17]
	v_mfma_f32_16x16x32_bf16 v[62:65], v[146:149], v[162:165], v[62:65]
	v_mfma_f32_16x16x32_bf16 v[58:61], v[154:157], v[162:165], v[58:61]
	v_mfma_f32_16x16x32_bf16 v[54:57], v[146:149], v[170:173], v[54:57]
	v_mfma_f32_16x16x32_bf16 v[46:49], v[154:157], v[170:173], v[46:49]
	v_mfma_f32_16x16x32_bf16 v[38:41], v[146:149], v[182:185], v[38:41]
	v_mfma_f32_16x16x32_bf16 v[30:33], v[154:157], v[182:185], v[30:33]
	v_mfma_f32_16x16x32_bf16 v[22:25], v[146:149], v[190:193], v[22:25]
	v_mfma_f32_16x16x32_bf16 v[14:17], v[154:157], v[190:193], v[14:17]
	s_barrier
; #define PG8_STAGE(bufoff, gbase, voff) do { _Pragma("unroll") for (int _i = 0; _i < 2; ++_i) \
;         __builtin_amdgcn_global_load_lds((const unsigned*)((const char*)(gbase) + (voff)[_i]), (LAS unsigned*)(lds + (bufoff) + ldsw + _i * 8192), 16, 0, 0); } while (0)
; #define PG8_LDA(dst, b, h) do { _Pragma("unroll") for (int m = 0; m < 4; ++m) _Pragma("unroll") for (int k = 0; k < 2; ++k) dst[m][k] = *(const LAS bf16x8*)(lds + PG8_SA(b, h) + aoff + m * 2048 + k * 1024); } while (0)
; #define PG8_LDB(dst, b, h) do { _Pragma("unroll") for (int n = 0; n < 2; ++n) _Pragma("unroll") for (int k = 0; k < 2; ++k) dst[n][k] = *(const LAS bf16x8*)(lds + PG8_SB(b, h) + boff + n * 2048 + k * 1024); } while (0)
; #define PG8_MMA(ai, bj, At, Bt) do { __builtin_amdgcn_s_setprio(1); _Pragma("unroll") for (int m = 0; m < 4; ++m) _Pragma("unroll") for (int n = 0; n < 2; ++n) _Pragma("unroll") for (int k = 0; k < 2; ++k) \
;         acc[ai][bj][m][n] = __builtin_amdgcn_mfma_f32_16x16x32_bf16(Bt[n][k], At[m][k], acc[ai][bj][m][n], 0, 0, 0); __builtin_amdgcn_s_setprio(0); } while (0)
; #define PG8_WAIT_V(n) asm volatile("s_waitcnt vmcnt(" #n ")" ::: "memory")
; #define PG8_WAIT_L(n) asm volatile("s_waitcnt lgkmcnt(" #n ")" ::: "memory")
; #define PG8_BAR __builtin_amdgcn_s_barrier()
; #define PG8_SCHED __builtin_amdgcn_sched_barrier(0)
; template <int MODE, class EpiT, class Sched>
; __device__ __forceinline__ void gemm_phase(LAS unsigned char* lds, const Gemm g, const Sched& S, const EpiT& E) {
;     ...
;             PG8_STAGE(PG8_SB(0, 1), b2 + hstep, voffB);
;             PG8_WAIT_V(6); PG8_BAR; PG8_MMA(1, 1, At, B1); PG8_BAR;
;             PG8_LDB(B0, 1, 0); PG8_SCHED; PG8_LDA(At, 1, 0); PG8_STAGE(PG8_SA(0, 1), a2 + hstep, voffA);
;             PG8_WAIT_L(8); PG8_BAR; PG8_WAIT_L(0); PG8_MMA(0, 0, At, B0); PG8_BAR; PG8_SCHED;
;             PG8_LDB(B1, 1, 1); PG8_STAGE(PG8_SB(1, 0), b3, voffB);
;             PG8_BAR; PG8_WAIT_L(0); PG8_MMA(0, 1, At, B1); PG8_BAR;
	s_add_u32 s38, s38, s24
	s_addc_u32 s39, s39, 0
	s_add_i32 s45, s58, s9
	v_lshl_add_u64 v[236:237], s[38:39], 0, v[0:1]
	s_mov_b32 m0, s45
	v_lshl_add_u64 v[238:239], s[38:39], 0, v[130:131]
	global_load_lds_dwordx4 v[236:237], off
	s_add_i32 m0, s45, 0x2000
	s_nop 0
	global_load_lds_dwordx4 v[238:239], off
	s_waitcnt vmcnt(6)
	s_barrier
	v_mfma_f32_16x16x32_bf16 v[50:53], v[194:197], v[158:161], v[50:53]
	v_mfma_f32_16x16x32_bf16 v[42:45], v[224:227], v[158:161], v[42:45]
	v_mfma_f32_16x16x32_bf16 v[34:37], v[194:197], v[166:169], v[34:37]
	v_mfma_f32_16x16x32_bf16 v[26:29], v[224:227], v[166:169], v[26:29]
	v_mfma_f32_16x16x32_bf16 v[18:21], v[194:197], v[174:177], v[18:21]
	v_mfma_f32_16x16x32_bf16 v[10:13], v[224:227], v[174:177], v[10:13]
	v_mfma_f32_16x16x32_bf16 v[6:9], v[194:197], v[186:189], v[6:9]
	v_mfma_f32_16x16x32_bf16 v[2:5], v[224:227], v[186:189], v[2:5]
	v_mfma_f32_16x16x32_bf16 v[50:53], v[220:223], v[162:165], v[50:53]
	v_mfma_f32_16x16x32_bf16 v[42:45], v[228:231], v[162:165], v[42:45]
	v_mfma_f32_16x16x32_bf16 v[34:37], v[220:223], v[170:173], v[34:37]
	v_mfma_f32_16x16x32_bf16 v[26:29], v[228:231], v[170:173], v[26:29]
	v_mfma_f32_16x16x32_bf16 v[18:21], v[220:223], v[182:185], v[18:21]
	v_mfma_f32_16x16x32_bf16 v[10:13], v[228:231], v[182:185], v[10:13]
	v_mfma_f32_16x16x32_bf16 v[6:9], v[220:223], v[190:193], v[6:9]
	v_mfma_f32_16x16x32_bf16 v[2:5], v[228:231], v[190:193], v[2:5]
	s_barrier
	s_add_i32 s38, 0, 0x18000
	v_add_u32_e32 v154, s38, v139
	ds_read_b128 v[142:145], v154
	ds_read_b128 v[146:149], v154 offset:1024
	ds_read_b128 v[150:153], v154 offset:2048
	ds_read_b128 v[154:157], v154 offset:3072
	s_add_u32 s34, s34, s24
	s_addc_u32 s35, s35, 0
	s_mov_b32 m0, s30
	v_lshl_add_u64 v[194:195], s[34:35], 0, v[0:1]
	ds_read_b128 v[158:161], v141 offset:32768
	ds_read_b128 v[162:165], v141 offset:33792
	ds_read_b128 v[166:169], v141 offset:34816
	ds_read_b128 v[170:173], v141 offset:35840
	ds_read_b128 v[174:177], v141 offset:36864
	ds_read_b128 v[182:185], v141 offset:37888
	ds_read_b128 v[186:189], v141 offset:38912
	ds_read_b128 v[190:193], v141 offset:39936
	global_load_lds_dwordx4 v[194:195], off
	v_lshl_add_u64 v[194:195], s[34:35], 0, v[130:131]
	s_mov_b32 m0, s46
	s_nop 0
	global_load_lds_dwordx4 v[194:195], off
	s_waitcnt lgkmcnt(8)
	s_barrier
	s_waitcnt lgkmcnt(0)
	v_mfma_f32_16x16x32_bf16 v[126:129], v[142:145], v[158:161], v[126:129]
	v_mfma_f32_16x16x32_bf16 v[122:125], v[150:153], v[158:161], v[122:125]
	v_mfma_f32_16x16x32_bf16 v[118:121], v[142:145], v[166:169], v[118:121]
	v_mfma_f32_16x16x32_bf16 v[110:113], v[150:153], v[166:169], v[110:113]
	v_mfma_f32_16x16x32_bf16 v[102:105], v[142:145], v[174:177], v[102:105]
	v_mfma_f32_16x16x32_bf16 v[94:97], v[150:153], v[174:177], v[94:97]
	v_mfma_f32_16x16x32_bf16 v[86:89], v[142:145], v[186:189], v[86:89]
	v_mfma_f32_16x16x32_bf16 v[78:81], v[150:153], v[186:189], v[78:81]
	v_mfma_f32_16x16x32_bf16 v[126:129], v[146:149], v[162:165], v[126:129]
	v_mfma_f32_16x16x32_bf16 v[122:125], v[154:157], v[162:165], v[122:125]
	v_mfma_f32_16x16x32_bf16 v[118:121], v[146:149], v[170:173], v[118:121]
	v_mfma_f32_16x16x32_bf16 v[110:113], v[154:157], v[170:173], v[110:113]
	v_mfma_f32_16x16x32_bf16 v[102:105], v[146:149], v[182:185], v[102:105]
	v_mfma_f32_16x16x32_bf16 v[94:97], v[154:157], v[182:185], v[94:97]
	v_mfma_f32_16x16x32_bf16 v[86:89], v[146:149], v[190:193], v[86:89]
	v_mfma_f32_16x16x32_bf16 v[78:81], v[154:157], v[190:193], v[78:81]
	s_barrier
	s_add_i32 s34, 0, 0x1c000
	s_add_i32 s35, s38, s9
	v_add_u32_e32 v181, s34, v139
	v_lshl_add_u64 v[136:137], v[136:137], 0, s[76:77]
	s_mov_b32 m0, s35
	ds_read_b128 v[194:197], v181
	ds_read_b128 v[220:223], v181 offset:1024
	ds_read_b128 v[224:227], v181 offset:2048
	ds_read_b128 v[228:231], v181 offset:3072
	global_load_lds_dwordx4 v[136:137], off
	v_lshl_add_u64 v[136:137], v[198:199], 0, s[76:77]
	s_add_i32 m0, s35, 0x2000
	s_nop 0
	global_load_lds_dwordx4 v[136:137], off
	s_barrier
	s_waitcnt lgkmcnt(0)
	v_mfma_f32_16x16x32_bf16 v[114:117], v[194:197], v[158:161], v[114:117]
	v_mfma_f32_16x16x32_bf16 v[106:109], v[224:227], v[158:161], v[106:109]
	v_mfma_f32_16x16x32_bf16 v[98:101], v[194:197], v[166:169], v[98:101]
	v_mfma_f32_16x16x32_bf16 v[90:93], v[224:227], v[166:169], v[90:93]
	v_mfma_f32_16x16x32_bf16 v[82:85], v[194:197], v[174:177], v[82:85]
	v_mfma_f32_16x16x32_bf16 v[74:77], v[224:227], v[174:177], v[74:77]
	v_mfma_f32_16x16x32_bf16 v[70:73], v[194:197], v[186:189], v[70:73]
	v_mfma_f32_16x16x32_bf16 v[66:69], v[224:227], v[186:189], v[66:69]
	v_mfma_f32_16x16x32_bf16 v[114:117], v[220:223], v[162:165], v[114:117]
	v_mfma_f32_16x16x32_bf16 v[106:109], v[228:231], v[162:165], v[106:109]
	v_mfma_f32_16x16x32_bf16 v[98:101], v[220:223], v[170:173], v[98:101]
	v_mfma_f32_16x16x32_bf16 v[90:93], v[228:231], v[170:173], v[90:93]
	v_mfma_f32_16x16x32_bf16 v[82:85], v[220:223], v[182:185], v[82:85]
	v_mfma_f32_16x16x32_bf16 v[74:77], v[228:231], v[182:185], v[74:77]
	v_mfma_f32_16x16x32_bf16 v[70:73], v[220:223], v[190:193], v[70:73]
	v_mfma_f32_16x16x32_bf16 v[66:69], v[228:231], v[190:193], v[66:69]
	s_barrier
	s_mov_b32 m0, s50
	v_lshl_add_u64 v[136:137], v[232:233], 0, s[76:77]
	ds_read_b128 v[158:161], v141 offset:49152
	ds_read_b128 v[162:165], v141 offset:50176
	ds_read_b128 v[166:169], v141 offset:51200
	ds_read_b128 v[170:173], v141 offset:52224
	ds_read_b128 v[174:177], v141 offset:53248
	ds_read_b128 v[182:185], v141 offset:54272
	ds_read_b128 v[186:189], v141 offset:55296
	ds_read_b128 v[190:193], v141 offset:56320
	global_load_lds_dwordx4 v[136:137], off
	v_lshl_add_u64 v[136:137], v[234:235], 0, s[76:77]
	s_mov_b32 m0, s51
	s_nop 0
	global_load_lds_dwordx4 v[136:137], off
	s_barrier
; #define PG8_STAGE(bufoff, gbase, voff) do { _Pragma("unroll") for (int _i = 0; _i < 2; ++_i) \
;         __builtin_amdgcn_global_load_lds((const unsigned*)((const char*)(gbase) + (voff)[_i]), (LAS unsigned*)(lds + (bufoff) + ldsw + _i * 8192), 16, 0, 0); } while (0)
; #define PG8_LDA(dst, b, h) do { _Pragma("unroll") for (int m = 0; m < 4; ++m) _Pragma("unroll") for (int k = 0; k < 2; ++k) dst[m][k] = *(const LAS bf16x8*)(lds + PG8_SA(b, h) + aoff + m * 2048 + k * 1024); } while (0)
; #define PG8_MMA(ai, bj, At, Bt) do { __builtin_amdgcn_s_setprio(1); _Pragma("unroll") for (int m = 0; m < 4; ++m) _Pragma("unroll") for (int n = 0; n < 2; ++n) _Pragma("unroll") for (int k = 0; k < 2; ++k) \
;         acc[ai][bj][m][n] = __builtin_amdgcn_mfma_f32_16x16x32_bf16(Bt[n][k], At[m][k], acc[ai][bj][m][n], 0, 0, 0); __builtin_amdgcn_s_setprio(0); } while (0)
; #define PG8_WAIT_V(n) asm volatile("s_waitcnt vmcnt(" #n ")" ::: "memory")
; #define PG8_WAIT_L(n) asm volatile("s_waitcnt lgkmcnt(" #n ")" ::: "memory")
; #define PG8_BAR __builtin_amdgcn_s_barrier()
; #define PG8_SCHED __builtin_amdgcn_sched_barrier(0)
; template <int MODE, class EpiT, class Sched>
; __device__ __forceinline__ void gemm_phase(LAS unsigned char* lds, const Gemm g, const Sched& S, const EpiT& E) {
;     ...
;             PG8_BAR; PG8_WAIT_L(0); PG8_MMA(0, 1, At, B1); PG8_BAR;
;             PG8_LDA(At, 1, 1); PG8_STAGE(PG8_SA(1, 0), a3, voffA);
;             PG8_BAR; PG8_WAIT_L(0); PG8_MMA(1, 0, At, B0); PG8_BAR; PG8_SCHED;
;             PG8_STAGE(PG8_SB(1, 1), b3 + hstep, voffB);
;             PG8_WAIT_V(6); PG8_BAR; PG8_MMA(1, 1, At, B1); PG8_BAR;
	s_waitcnt lgkmcnt(0)
	v_mfma_f32_16x16x32_bf16 v[62:65], v[142:145], v[158:161], v[62:65]
	v_mfma_f32_16x16x32_bf16 v[58:61], v[150:153], v[158:161], v[58:61]
	v_mfma_f32_16x16x32_bf16 v[54:57], v[142:145], v[166:169], v[54:57]
	v_mfma_f32_16x16x32_bf16 v[46:49], v[150:153], v[166:169], v[46:49]
	v_mfma_f32_16x16x32_bf16 v[38:41], v[142:145], v[174:177], v[38:41]
	v_mfma_f32_16x16x32_bf16 v[30:33], v[150:153], v[174:177], v[30:33]
	v_mfma_f32_16x16x32_bf16 v[22:25], v[142:145], v[186:189], v[22:25]
	v_mfma_f32_16x16x32_bf16 v[14:17], v[150:153], v[186:189], v[14:17]
	v_mfma_f32_16x16x32_bf16 v[62:65], v[146:149], v[162:165], v[62:65]
	v_mfma_f32_16x16x32_bf16 v[58:61], v[154:157], v[162:165], v[58:61]
	v_mfma_f32_16x16x32_bf16 v[54:57], v[146:149], v[170:173], v[54:57]
	v_mfma_f32_16x16x32_bf16 v[46:49], v[154:157], v[170:173], v[46:49]
	v_mfma_f32_16x16x32_bf16 v[38:41], v[146:149], v[182:185], v[38:41]
	v_mfma_f32_16x16x32_bf16 v[30:33], v[154:157], v[182:185], v[30:33]
	v_mfma_f32_16x16x32_bf16 v[22:25], v[146:149], v[190:193], v[22:25]
	v_mfma_f32_16x16x32_bf16 v[14:17], v[154:157], v[190:193], v[14:17]
	s_barrier
	s_add_i32 s34, s34, s9
	v_lshl_add_u64 v[136:137], v[236:237], 0, s[76:77]
	s_mov_b32 m0, s34
	s_nop 0
	global_load_lds_dwordx4 v[136:137], off
	v_lshl_add_u64 v[136:137], v[238:239], 0, s[76:77]
	s_add_i32 m0, s34, 0x2000
	s_nop 0
	global_load_lds_dwordx4 v[136:137], off
	s_waitcnt vmcnt(6)
	s_barrier
	v_mfma_f32_16x16x32_bf16 v[50:53], v[194:197], v[158:161], v[50:53]
	v_mfma_f32_16x16x32_bf16 v[42:45], v[224:227], v[158:161], v[42:45]
	v_mfma_f32_16x16x32_bf16 v[34:37], v[194:197], v[166:169], v[34:37]
	v_mfma_f32_16x16x32_bf16 v[26:29], v[224:227], v[166:169], v[26:29]
	v_mfma_f32_16x16x32_bf16 v[18:21], v[194:197], v[174:177], v[18:21]
	v_mfma_f32_16x16x32_bf16 v[10:13], v[224:227], v[174:177], v[10:13]
	v_mfma_f32_16x16x32_bf16 v[6:9], v[194:197], v[186:189], v[6:9]
	v_mfma_f32_16x16x32_bf16 v[2:5], v[224:227], v[186:189], v[2:5]
	v_mfma_f32_16x16x32_bf16 v[50:53], v[220:223], v[162:165], v[50:53]
	v_mfma_f32_16x16x32_bf16 v[42:45], v[228:231], v[162:165], v[42:45]
	v_mfma_f32_16x16x32_bf16 v[34:37], v[220:223], v[170:173], v[34:37]
	v_mfma_f32_16x16x32_bf16 v[26:29], v[228:231], v[170:173], v[26:29]
	v_mfma_f32_16x16x32_bf16 v[18:21], v[220:223], v[182:185], v[18:21]
	v_mfma_f32_16x16x32_bf16 v[10:13], v[228:231], v[182:185], v[10:13]
	v_mfma_f32_16x16x32_bf16 v[6:9], v[220:223], v[190:193], v[6:9]
	v_mfma_f32_16x16x32_bf16 v[2:5], v[228:231], v[190:193], v[2:5]
	s_barrier
	s_add_u32 s28, s28, 0x100
	s_addc_u32 s29, s29, 0
	s_add_u32 s42, s42, 0x100
	s_addc_u32 s43, s43, 0
	s_cmp_ge_u32 s44, s47
	s_mov_b32 s34, s44
	s_cbranch_scc0 .LBB0_236
; __device__ __forceinline__ unsigned pk2(float lo, float hi) { unsigned r; asm volatile("v_cvt_pk_bf16_f32 %0, %1, %2" : "=v"(r) : "v"(lo), "v"(hi)); return r; }
; #define PG8_WAIT_V(n) asm volatile("s_waitcnt vmcnt(" #n ")" ::: "memory")
; #define PG8_BAR __builtin_amdgcn_s_barrier()
;     template <int mode> __device__ __forceinline__ void run(const f32x4 (&acc)[2][2][4][2], const Unit& u, int wr, int wc, int fr, int fq, const LAS float* sc) const {
;     ...
;         } else if (mode == 2) {
;             const int col0 = u.pn * BM + wc * 32 + 8 * fq;
; #pragma unroll
;             for (int ai = 0; ai < 2; ++ai)
; #pragma unroll
;                 for (int m = 0; m < 4; ++m) {
;                     bf16_t* rowp = ob + (size_t)(row0 + ai * HALF + m * 16) * D + col0;
; #pragma unroll
;                     for (int bj = 0; bj < 2; ++bj) {
;                         const f32x4 v0 = acc[ai][bj][m][0], v1 = acc[ai][bj][m][1];
;                         u32x4 w; w.x = pk2(v0[0], v0[1]); w.y = pk2(v0[2], v0[3]); w.z = pk2(v1[0], v1[1]); w.w = pk2(v1[2], v1[3]);
;                         *(u32x4*)(rowp + bj * HALF) = w;
;                     }
;                 }
; template <int MODE, class EpiT, class Sched>
; __device__ __forceinline__ void gemm_phase(LAS unsigned char* lds, const Gemm g, const Sched& S, const EpiT& E) {
;     ...
;     PG8_WAIT_V(0);
;     if (wr == 0) PG8_BAR;
;     PG8_BAR;
	v_lshl_add_u32 v142, s56, 8, v138
	v_lshl_or_b32 v136, s61, 8, v140
	v_ashrrev_i32_e32 v143, 31, v142
	v_ashrrev_i32_e32 v137, 31, v136
	v_lshlrev_b64 v[144:145], 11, v[142:143]
	v_lshl_add_u64 v[144:145], s[6:7], 0, v[144:145]
	v_lshlrev_b64 v[146:147], 1, v[136:137]
	v_lshl_add_u64 v[136:137], v[144:145], 0, v[146:147]
	v_cvt_pk_bf16_f32 v126, v126, v127
	v_cvt_pk_bf16_f32 v127, v128, v129
	v_cvt_pk_bf16_f32 v128, v122, v123
	v_cvt_pk_bf16_f32 v129, v124, v125
	global_store_dwordx4 v[136:137], v[126:129], off
	v_cvt_pk_bf16_f32 v114, v114, v115
	v_cvt_pk_bf16_f32 v115, v116, v117
	v_cvt_pk_bf16_f32 v116, v106, v107
	v_or_b32_e32 v106, 16, v142
	v_ashrrev_i32_e32 v107, 31, v106
	v_lshlrev_b64 v[106:107], 11, v[106:107]
	v_lshl_add_u64 v[106:107], s[6:7], 0, v[106:107]
	v_cvt_pk_bf16_f32 v117, v108, v109
	global_store_dwordx4 v[136:137], v[114:117], off offset:256
	s_mov_b64 s[28:29], 0x40000
	s_mov_b32 s61, s57
	v_lshl_add_u64 v[114:115], v[106:107], 0, v[146:147]
	v_cvt_pk_bf16_f32 v106, v118, v119
	v_cvt_pk_bf16_f32 v107, v120, v121
	v_cvt_pk_bf16_f32 v108, v110, v111
	v_cvt_pk_bf16_f32 v109, v112, v113
	global_store_dwordx4 v[114:115], v[106:109], off
	v_cvt_pk_bf16_f32 v98, v98, v99
	v_cvt_pk_bf16_f32 v99, v100, v101
	v_cvt_pk_bf16_f32 v100, v90, v91
	v_or_b32_e32 v90, 32, v142
	v_ashrrev_i32_e32 v91, 31, v90
	v_lshlrev_b64 v[90:91], 11, v[90:91]
	v_lshl_add_u64 v[90:91], s[6:7], 0, v[90:91]
	v_cvt_pk_bf16_f32 v101, v92, v93
	global_store_dwordx4 v[114:115], v[98:101], off offset:256
	s_mov_b32 s56, s60
	s_mov_b64 s[34:35], s[10:11]
	v_lshl_add_u64 v[98:99], v[90:91], 0, v[146:147]
	v_cvt_pk_bf16_f32 v90, v102, v103
	v_cvt_pk_bf16_f32 v91, v104, v105
	v_cvt_pk_bf16_f32 v92, v94, v95
	v_cvt_pk_bf16_f32 v93, v96, v97
	global_store_dwordx4 v[98:99], v[90:93], off
	v_cvt_pk_bf16_f32 v82, v82, v83
	v_cvt_pk_bf16_f32 v83, v84, v85
	v_cvt_pk_bf16_f32 v84, v74, v75
	v_or_b32_e32 v74, 48, v142
	v_ashrrev_i32_e32 v75, 31, v74
	v_lshlrev_b64 v[74:75], 11, v[74:75]
	v_lshl_add_u64 v[74:75], s[6:7], 0, v[74:75]
	v_cvt_pk_bf16_f32 v85, v76, v77
	global_store_dwordx4 v[98:99], v[82:85], off offset:256
	s_nop 1
	v_lshl_add_u64 v[82:83], v[74:75], 0, v[146:147]
	v_cvt_pk_bf16_f32 v74, v86, v87
	v_cvt_pk_bf16_f32 v75, v88, v89
	v_cvt_pk_bf16_f32 v76, v78, v79
	v_cvt_pk_bf16_f32 v77, v80, v81
	global_store_dwordx4 v[82:83], v[74:77], off
	v_cvt_pk_bf16_f32 v70, v70, v71
	v_cvt_pk_bf16_f32 v71, v72, v73
	v_cvt_pk_bf16_f32 v72, v66, v67
	v_cvt_pk_bf16_f32 v73, v68, v69
	global_store_dwordx4 v[82:83], v[70:73], off offset:256
	v_cvt_pk_bf16_f32 v62, v62, v63
	v_cvt_pk_bf16_f32 v63, v64, v65
	v_cvt_pk_bf16_f32 v64, v58, v59
	v_add_co_u32_e32 v58, vcc, s91, v136
	v_lshl_add_u64 v[66:67], v[136:137], 0, s[28:29]
	s_nop 0
	v_addc_co_u32_e32 v59, vcc, 0, v137, vcc
	v_cvt_pk_bf16_f32 v65, v60, v61
	global_store_dwordx4 v[58:59], v[62:65], off
	v_cvt_pk_bf16_f32 v50, v50, v51
	v_cvt_pk_bf16_f32 v51, v52, v53
	s_mov_b64 s[28:29], 0x48000
	v_cvt_pk_bf16_f32 v52, v42, v43
	v_cvt_pk_bf16_f32 v53, v44, v45
	global_store_dwordx4 v[66:67], v[50:53], off offset:256
	v_cvt_pk_bf16_f32 v42, v54, v55
	v_cvt_pk_bf16_f32 v43, v56, v57
	v_cvt_pk_bf16_f32 v44, v46, v47
	v_cvt_pk_bf16_f32 v45, v48, v49
	s_nop 1
	v_lshl_add_u64 v[50:51], v[136:137], 0, s[28:29]
	s_mov_b32 s28, 0x48000
	v_add_co_u32_e32 v46, vcc, s28, v136
	s_mov_b64 s[28:29], 0x50000
	s_nop 0
	v_addc_co_u32_e32 v47, vcc, 0, v137, vcc
	global_store_dwordx4 v[46:47], v[42:45], off
	v_cvt_pk_bf16_f32 v34, v34, v35
	v_cvt_pk_bf16_f32 v35, v36, v37
	v_cvt_pk_bf16_f32 v36, v26, v27
	v_cvt_pk_bf16_f32 v37, v28, v29
	global_store_dwordx4 v[50:51], v[34:37], off offset:256
	v_cvt_pk_bf16_f32 v26, v38, v39
	v_cvt_pk_bf16_f32 v27, v40, v41
	v_cvt_pk_bf16_f32 v28, v30, v31
	v_cvt_pk_bf16_f32 v29, v32, v33
	s_nop 1
	v_lshl_add_u64 v[34:35], v[136:137], 0, s[28:29]
	s_mov_b32 s28, 0x50000
	v_add_co_u32_e32 v30, vcc, s28, v136
	s_mov_b64 s[28:29], 0x58000
	s_nop 0
	v_addc_co_u32_e32 v31, vcc, 0, v137, vcc
	global_store_dwordx4 v[30:31], v[26:29], off
	v_cvt_pk_bf16_f32 v18, v18, v19
	v_cvt_pk_bf16_f32 v19, v20, v21
	v_cvt_pk_bf16_f32 v20, v10, v11
	v_cvt_pk_bf16_f32 v21, v12, v13
	global_store_dwordx4 v[34:35], v[18:21], off offset:256
	v_cvt_pk_bf16_f32 v10, v22, v23
	v_cvt_pk_bf16_f32 v11, v24, v25
	v_cvt_pk_bf16_f32 v12, v14, v15
	v_cvt_pk_bf16_f32 v13, v16, v17
	s_nop 1
	v_lshl_add_u64 v[18:19], v[136:137], 0, s[28:29]
	s_mov_b32 s28, 0x58000
	v_add_co_u32_e32 v14, vcc, s28, v136
	s_mov_b64 s[28:29], s[4:5]
	s_nop 0
	v_addc_co_u32_e32 v15, vcc, 0, v137, vcc
	s_and_b64 vcc, exec, s[40:41]
	global_store_dwordx4 v[14:15], v[10:13], off
	v_cvt_pk_bf16_f32 v6, v6, v7
	v_cvt_pk_bf16_f32 v7, v8, v9
	v_cvt_pk_bf16_f32 v8, v2, v3
	v_cvt_pk_bf16_f32 v9, v4, v5
	global_store_dwordx4 v[18:19], v[6:9], off offset:256
	s_cbranch_vccz .LBB0_229
	s_waitcnt vmcnt(0)
	v_readlane_b32 s46, v247, 49
	v_readlane_b32 s50, v246, 29
	v_readlane_b32 s56, v246, 31
	v_readlane_b32 s58, v246, 33
	v_readlane_b32 s60, v246, 35
	s_cmpk_gt_u32 s2, 0xff
	s_mov_b32 s52, 0x800000
	s_movk_i32 s53, 0x1000
	s_movk_i32 s23, 0x2000
	s_movk_i32 s30, 0x2840
	s_movk_i32 s42, 0x3000
	s_mov_b64 s[44:45], 0x1800
	v_readlane_b32 s47, v247, 50
	v_readlane_b32 s43, v247, 51
	v_readlane_b32 s51, v246, 30
	v_readlane_b32 s57, v246, 32
	v_readlane_b32 s59, v246, 34
	v_readlane_b32 s61, v246, 36
	s_cbranch_scc1 .LBB0_240
	s_barrier

; #define PG8_STAGE(bufoff, gbase, voff) do { _Pragma("unroll") for (int _i = 0; _i < 2; ++_i) \
;         __builtin_amdgcn_global_load_lds((const unsigned*)((const char*)(gbase) + (voff)[_i]), (LAS unsigned*)(lds + (bufoff) + ldsw + _i * 8192), 16, 0, 0); } while (0)
; #define PG8_LDA(dst, b, h) do { _Pragma("unroll") for (int m = 0; m < 4; ++m) _Pragma("unroll") for (int k = 0; k < 2; ++k) dst[m][k] = *(const LAS bf16x8*)(lds + PG8_SA(b, h) + aoff + m * 2048 + k * 1024); } while (0)
; #define PG8_LDB(dst, b, h) do { _Pragma("unroll") for (int n = 0; n < 2; ++n) _Pragma("unroll") for (int k = 0; k < 2; ++k) dst[n][k] = *(const LAS bf16x8*)(lds + PG8_SB(b, h) + boff + n * 2048 + k * 1024); } while (0)
; #define PG8_MMA(ai, bj, At, Bt) do { __builtin_amdgcn_s_setprio(1); _Pragma("unroll") for (int m = 0; m < 4; ++m) _Pragma("unroll") for (int n = 0; n < 2; ++n) _Pragma("unroll") for (int k = 0; k < 2; ++k) \
;         acc[ai][bj][m][n] = __builtin_amdgcn_mfma_f32_16x16x32_bf16(Bt[n][k], At[m][k], acc[ai][bj][m][n], 0, 0, 0); __builtin_amdgcn_s_setprio(0); } while (0)
; #define PG8_WAIT_L(n) asm volatile("s_waitcnt lgkmcnt(" #n ")" ::: "memory")
; #define PG8_BAR __builtin_amdgcn_s_barrier()
; #define PG8_SCHED __builtin_amdgcn_sched_barrier(0)
; template <int MODE, class EpiT, class Sched>
; __device__ __forceinline__ void gemm_phase(LAS unsigned char* lds, const Gemm g, const Sched& S, const EpiT& E) {
;     ...
;         for (int t = 0; t < nt; t += 2) {
;             const bool last = (t == nt - 2);
;             const char* a1 = cA + (size_t)(t + 1) * kstep;
;             const char* a2 = last ? nA : cA + (size_t)(t + 2) * kstep; const char* b2 = last ? nB : cB + (size_t)(t + 2) * kstep;
;             const char* a3 = a2 + kstep; const char* b3 = b2 + kstep;
;             PG8_LDB(B0, 0, 0); PG8_SCHED; PG8_LDA(At, 0, 0); PG8_STAGE(PG8_SA(1, 1), a1 + hstep, voffA);
;             PG8_WAIT_L(8); PG8_BAR; PG8_WAIT_L(0); PG8_MMA(0, 0, At, B0); PG8_BAR; PG8_SCHED;
;             PG8_LDB(B1, 0, 1); PG8_STAGE(PG8_SB(0, 0), b2, voffB);
;             PG8_BAR; PG8_WAIT_L(0); PG8_MMA(0, 1, At, B1); PG8_BAR;
;             PG8_LDA(At, 0, 1); PG8_STAGE(PG8_SA(0, 0), a2, voffA);
;             PG8_BAR; PG8_WAIT_L(0); PG8_MMA(1, 0, At, B0); PG8_BAR; PG8_SCHED;
.LBB0_280:
	s_add_i32 s68, s46, 2
	s_add_u32 s52, s10, s44
	s_addc_u32 s47, s11, s45
	s_add_u32 s58, s4, s44
	s_addc_u32 s53, s5, s45
	s_add_i32 s59, 0, 0x10000
	v_add_u32_e32 v152, s59, v157
	ds_read_b128 v[134:137], v152
	ds_read_b128 v[138:141], v152 offset:1024
	ds_read_b128 v[142:145], v152 offset:2048
	ds_read_b128 v[152:155], v152 offset:3072
	s_cmp_eq_u32 s60, s46
	s_cselect_b32 s46, s34, s52
	s_cselect_b32 s47, s35, s47
	s_cselect_b32 s53, s39, s53
	s_cselect_b32 s52, s38, s58
	v_lshl_add_u64 v[198:199], s[10:11], 0, v[132:133]
	s_add_i32 m0, s30, 0xc000
	ds_read_b128 v[162:165], v160
	ds_read_b128 v[166:169], v160 offset:1024
	ds_read_b128 v[170:173], v160 offset:2048
	ds_read_b128 v[174:177], v160 offset:3072
	ds_read_b128 v[182:185], v160 offset:4096
	ds_read_b128 v[186:189], v160 offset:5120
	ds_read_b128 v[190:193], v160 offset:6144
	ds_read_b128 v[194:197], v160 offset:7168
	global_load_lds_dwordx4 v[198:199], off
	v_lshl_add_u64 v[198:199], s[10:11], 0, v[130:131]
	s_add_i32 m0, s30, 0xe000
	s_nop 0
	global_load_lds_dwordx4 v[198:199], off
	s_waitcnt lgkmcnt(8)
	s_barrier
	s_waitcnt lgkmcnt(0)
	v_mfma_f32_16x16x32_bf16 v[126:129], v[134:137], v[162:165], v[126:129]
	v_mfma_f32_16x16x32_bf16 v[122:125], v[142:145], v[162:165], v[122:125]
	v_mfma_f32_16x16x32_bf16 v[118:121], v[134:137], v[170:173], v[118:121]
	v_mfma_f32_16x16x32_bf16 v[114:117], v[142:145], v[170:173], v[114:117]
	v_mfma_f32_16x16x32_bf16 v[110:113], v[134:137], v[182:185], v[110:113]
	v_mfma_f32_16x16x32_bf16 v[106:109], v[142:145], v[182:185], v[106:109]
	v_mfma_f32_16x16x32_bf16 v[102:105], v[134:137], v[190:193], v[102:105]
	v_mfma_f32_16x16x32_bf16 v[98:101], v[142:145], v[190:193], v[98:101]
	v_mfma_f32_16x16x32_bf16 v[126:129], v[138:141], v[166:169], v[126:129]
	v_mfma_f32_16x16x32_bf16 v[122:125], v[152:155], v[166:169], v[122:125]
	v_mfma_f32_16x16x32_bf16 v[118:121], v[138:141], v[174:177], v[118:121]
	v_mfma_f32_16x16x32_bf16 v[114:117], v[152:155], v[174:177], v[114:117]
	v_mfma_f32_16x16x32_bf16 v[110:113], v[138:141], v[186:189], v[110:113]
	v_mfma_f32_16x16x32_bf16 v[106:109], v[152:155], v[186:189], v[106:109]
	v_mfma_f32_16x16x32_bf16 v[102:105], v[138:141], v[194:197], v[102:105]
	v_mfma_f32_16x16x32_bf16 v[98:101], v[152:155], v[194:197], v[98:101]
	s_barrier
	s_add_i32 s58, 0, 0x14000
	s_add_i32 s59, s59, s24
	v_add_u32_e32 v161, s58, v157
	v_lshl_add_u64 v[198:199], s[52:53], 0, v[0:1]
	s_mov_b32 m0, s59
	ds_read_b128 v[220:223], v161
	ds_read_b128 v[224:227], v161 offset:1024
	ds_read_b128 v[228:231], v161 offset:2048
	ds_read_b128 v[232:235], v161 offset:3072
	global_load_lds_dwordx4 v[198:199], off
	v_lshl_add_u64 v[236:237], s[52:53], 0, v[146:147]
	s_add_i32 m0, s59, 0x2000
	s_nop 0
	global_load_lds_dwordx4 v[236:237], off
	s_barrier
	s_waitcnt lgkmcnt(0)
	v_mfma_f32_16x16x32_bf16 v[94:97], v[220:223], v[162:165], v[94:97]
	v_mfma_f32_16x16x32_bf16 v[90:93], v[228:231], v[162:165], v[90:93]
	v_mfma_f32_16x16x32_bf16 v[86:89], v[220:223], v[170:173], v[86:89]
	v_mfma_f32_16x16x32_bf16 v[82:85], v[228:231], v[170:173], v[82:85]
	v_mfma_f32_16x16x32_bf16 v[78:81], v[220:223], v[182:185], v[78:81]
	v_mfma_f32_16x16x32_bf16 v[74:77], v[228:231], v[182:185], v[74:77]
	v_mfma_f32_16x16x32_bf16 v[70:73], v[220:223], v[190:193], v[70:73]
	v_mfma_f32_16x16x32_bf16 v[66:69], v[228:231], v[190:193], v[66:69]
	v_mfma_f32_16x16x32_bf16 v[94:97], v[224:227], v[166:169], v[94:97]
	v_mfma_f32_16x16x32_bf16 v[90:93], v[232:235], v[166:169], v[90:93]
	v_mfma_f32_16x16x32_bf16 v[86:89], v[224:227], v[174:177], v[86:89]
	v_mfma_f32_16x16x32_bf16 v[82:85], v[232:235], v[174:177], v[82:85]
	v_mfma_f32_16x16x32_bf16 v[78:81], v[224:227], v[186:189], v[78:81]
	v_mfma_f32_16x16x32_bf16 v[74:77], v[232:235], v[186:189], v[74:77]
	v_mfma_f32_16x16x32_bf16 v[70:73], v[224:227], v[194:197], v[70:73]
	v_mfma_f32_16x16x32_bf16 v[66:69], v[232:235], v[194:197], v[66:69]
	s_barrier
	s_mov_b32 m0, s30
	v_lshl_add_u64 v[238:239], s[46:47], 0, v[0:1]
	ds_read_b128 v[162:165], v160 offset:16384
	ds_read_b128 v[166:169], v160 offset:17408
	ds_read_b128 v[170:173], v160 offset:18432
	ds_read_b128 v[174:177], v160 offset:19456
	ds_read_b128 v[182:185], v160 offset:20480
	ds_read_b128 v[186:189], v160 offset:21504
	ds_read_b128 v[190:193], v160 offset:22528
	ds_read_b128 v[194:197], v160 offset:23552
	global_load_lds_dwordx4 v[238:239], off
	v_lshl_add_u64 v[240:241], s[46:47], 0, v[146:147]
	s_mov_b32 m0, s50
	s_nop 0
	global_load_lds_dwordx4 v[240:241], off
	s_barrier
	s_waitcnt lgkmcnt(0)
	v_mfma_f32_16x16x32_bf16 v[62:65], v[134:137], v[162:165], v[62:65]
	v_mfma_f32_16x16x32_bf16 v[58:61], v[142:145], v[162:165], v[58:61]
	v_mfma_f32_16x16x32_bf16 v[54:57], v[134:137], v[170:173], v[54:57]
	v_mfma_f32_16x16x32_bf16 v[50:53], v[142:145], v[170:173], v[50:53]
	v_mfma_f32_16x16x32_bf16 v[46:49], v[134:137], v[182:185], v[46:49]
	v_mfma_f32_16x16x32_bf16 v[42:45], v[142:145], v[182:185], v[42:45]
	v_mfma_f32_16x16x32_bf16 v[38:41], v[134:137], v[190:193], v[38:41]
	v_mfma_f32_16x16x32_bf16 v[34:37], v[142:145], v[190:193], v[34:37]
	v_mfma_f32_16x16x32_bf16 v[62:65], v[138:141], v[166:169], v[62:65]
	v_mfma_f32_16x16x32_bf16 v[58:61], v[152:155], v[166:169], v[58:61]
	v_mfma_f32_16x16x32_bf16 v[54:57], v[138:141], v[174:177], v[54:57]
	v_mfma_f32_16x16x32_bf16 v[50:53], v[152:155], v[174:177], v[50:53]
	v_mfma_f32_16x16x32_bf16 v[46:49], v[138:141], v[186:189], v[46:49]
	v_mfma_f32_16x16x32_bf16 v[42:45], v[152:155], v[186:189], v[42:45]
	v_mfma_f32_16x16x32_bf16 v[38:41], v[138:141], v[194:197], v[38:41]
	v_mfma_f32_16x16x32_bf16 v[34:37], v[152:155], v[194:197], v[34:37]
	s_barrier
; #define PG8_STAGE(bufoff, gbase, voff) do { _Pragma("unroll") for (int _i = 0; _i < 2; ++_i) \
;         __builtin_amdgcn_global_load_lds((const unsigned*)((const char*)(gbase) + (voff)[_i]), (LAS unsigned*)(lds + (bufoff) + ldsw + _i * 8192), 16, 0, 0); } while (0)
; #define PG8_LDA(dst, b, h) do { _Pragma("unroll") for (int m = 0; m < 4; ++m) _Pragma("unroll") for (int k = 0; k < 2; ++k) dst[m][k] = *(const LAS bf16x8*)(lds + PG8_SA(b, h) + aoff + m * 2048 + k * 1024); } while (0)
; #define PG8_LDB(dst, b, h) do { _Pragma("unroll") for (int n = 0; n < 2; ++n) _Pragma("unroll") for (int k = 0; k < 2; ++k) dst[n][k] = *(const LAS bf16x8*)(lds + PG8_SB(b, h) + boff + n * 2048 + k * 1024); } while (0)
; #define PG8_MMA(ai, bj, At, Bt) do { __builtin_amdgcn_s_setprio(1); _Pragma("unroll") for (int m = 0; m < 4; ++m) _Pragma("unroll") for (int n = 0; n < 2; ++n) _Pragma("unroll") for (int k = 0; k < 2; ++k) \
;         acc[ai][bj][m][n] = __builtin_amdgcn_mfma_f32_16x16x32_bf16(Bt[n][k], At[m][k], acc[ai][bj][m][n], 0, 0, 0); __builtin_amdgcn_s_setprio(0); } while (0)
; #define PG8_WAIT_V(n) asm volatile("s_waitcnt vmcnt(" #n ")" ::: "memory")
; #define PG8_WAIT_L(n) asm volatile("s_waitcnt lgkmcnt(" #n ")" ::: "memory")
; #define PG8_BAR __builtin_amdgcn_s_barrier()
; #define PG8_SCHED __builtin_amdgcn_sched_barrier(0)
; template <int MODE, class EpiT, class Sched>
; __device__ __forceinline__ void gemm_phase(LAS unsigned char* lds, const Gemm g, const Sched& S, const EpiT& E) {
;     ...
;             PG8_STAGE(PG8_SB(0, 1), b2 + hstep, voffB);
;             PG8_WAIT_V(6); PG8_BAR; PG8_MMA(1, 1, At, B1); PG8_BAR;
;             PG8_LDB(B0, 1, 0); PG8_SCHED; PG8_LDA(At, 1, 0); PG8_STAGE(PG8_SA(0, 1), a2 + hstep, voffA);
;             PG8_WAIT_L(8); PG8_BAR; PG8_WAIT_L(0); PG8_MMA(0, 0, At, B0); PG8_BAR; PG8_SCHED;
;             PG8_LDB(B1, 1, 1); PG8_STAGE(PG8_SB(1, 0), b3, voffB);
;             PG8_BAR; PG8_WAIT_L(0); PG8_MMA(0, 1, At, B1); PG8_BAR;
	s_add_u32 s52, s52, s22
	s_addc_u32 s53, s53, 0
	s_add_i32 s58, s58, s24
	v_lshl_add_u64 v[242:243], s[52:53], 0, v[0:1]
	s_mov_b32 m0, s58
	v_lshl_add_u64 v[244:245], s[52:53], 0, v[146:147]
	global_load_lds_dwordx4 v[242:243], off
	s_add_i32 m0, s58, 0x2000
	s_nop 0
	global_load_lds_dwordx4 v[244:245], off
	s_waitcnt vmcnt(6)
	s_barrier
	v_mfma_f32_16x16x32_bf16 v[30:33], v[220:223], v[162:165], v[30:33]
	v_mfma_f32_16x16x32_bf16 v[26:29], v[228:231], v[162:165], v[26:29]
	v_mfma_f32_16x16x32_bf16 v[22:25], v[220:223], v[170:173], v[22:25]
	v_mfma_f32_16x16x32_bf16 v[18:21], v[228:231], v[170:173], v[18:21]
	v_mfma_f32_16x16x32_bf16 v[14:17], v[220:223], v[182:185], v[14:17]
	v_mfma_f32_16x16x32_bf16 v[10:13], v[228:231], v[182:185], v[10:13]
	v_mfma_f32_16x16x32_bf16 v[6:9], v[220:223], v[190:193], v[6:9]
	v_mfma_f32_16x16x32_bf16 v[2:5], v[228:231], v[190:193], v[2:5]
	v_mfma_f32_16x16x32_bf16 v[30:33], v[224:227], v[166:169], v[30:33]
	v_mfma_f32_16x16x32_bf16 v[26:29], v[232:235], v[166:169], v[26:29]
	v_mfma_f32_16x16x32_bf16 v[22:25], v[224:227], v[174:177], v[22:25]
	v_mfma_f32_16x16x32_bf16 v[18:21], v[232:235], v[174:177], v[18:21]
	v_mfma_f32_16x16x32_bf16 v[14:17], v[224:227], v[186:189], v[14:17]
	v_mfma_f32_16x16x32_bf16 v[10:13], v[232:235], v[186:189], v[10:13]
	v_mfma_f32_16x16x32_bf16 v[6:9], v[224:227], v[194:197], v[6:9]
	v_mfma_f32_16x16x32_bf16 v[2:5], v[232:235], v[194:197], v[2:5]
	s_barrier
	s_add_i32 s52, 0, 0x18000
	v_add_u32_e32 v152, s52, v157
	ds_read_b128 v[134:137], v152
	ds_read_b128 v[138:141], v152 offset:1024
	ds_read_b128 v[142:145], v152 offset:2048
	ds_read_b128 v[152:155], v152 offset:3072
	s_add_u32 s46, s46, s22
	s_addc_u32 s47, s47, 0
	s_mov_b32 m0, s51
	v_lshl_add_u64 v[220:221], s[46:47], 0, v[0:1]
	ds_read_b128 v[162:165], v160 offset:32768
	ds_read_b128 v[166:169], v160 offset:33792
	ds_read_b128 v[170:173], v160 offset:34816
	ds_read_b128 v[174:177], v160 offset:35840
	ds_read_b128 v[182:185], v160 offset:36864
	ds_read_b128 v[186:189], v160 offset:37888
	ds_read_b128 v[190:193], v160 offset:38912
	ds_read_b128 v[194:197], v160 offset:39936
	global_load_lds_dwordx4 v[220:221], off
	v_lshl_add_u64 v[220:221], s[46:47], 0, v[146:147]
	s_mov_b32 m0, s54
	s_nop 0
	global_load_lds_dwordx4 v[220:221], off
	s_waitcnt lgkmcnt(8)
	s_barrier
	s_waitcnt lgkmcnt(0)
	v_mfma_f32_16x16x32_bf16 v[126:129], v[134:137], v[162:165], v[126:129]
	v_mfma_f32_16x16x32_bf16 v[122:125], v[142:145], v[162:165], v[122:125]
	v_mfma_f32_16x16x32_bf16 v[118:121], v[134:137], v[170:173], v[118:121]
	v_mfma_f32_16x16x32_bf16 v[114:117], v[142:145], v[170:173], v[114:117]
	v_mfma_f32_16x16x32_bf16 v[110:113], v[134:137], v[182:185], v[110:113]
	v_mfma_f32_16x16x32_bf16 v[106:109], v[142:145], v[182:185], v[106:109]
	v_mfma_f32_16x16x32_bf16 v[102:105], v[134:137], v[190:193], v[102:105]
	v_mfma_f32_16x16x32_bf16 v[98:101], v[142:145], v[190:193], v[98:101]
	v_mfma_f32_16x16x32_bf16 v[126:129], v[138:141], v[166:169], v[126:129]
	v_mfma_f32_16x16x32_bf16 v[122:125], v[152:155], v[166:169], v[122:125]
	v_mfma_f32_16x16x32_bf16 v[118:121], v[138:141], v[174:177], v[118:121]
	v_mfma_f32_16x16x32_bf16 v[114:117], v[152:155], v[174:177], v[114:117]
	v_mfma_f32_16x16x32_bf16 v[110:113], v[138:141], v[186:189], v[110:113]
	v_mfma_f32_16x16x32_bf16 v[106:109], v[152:155], v[186:189], v[106:109]
	v_mfma_f32_16x16x32_bf16 v[102:105], v[138:141], v[194:197], v[102:105]
	v_mfma_f32_16x16x32_bf16 v[98:101], v[152:155], v[194:197], v[98:101]
	s_barrier
	s_add_i32 s46, 0, 0x1c000
	s_add_i32 s47, s52, s24
	v_add_u32_e32 v161, s46, v157
	v_lshl_add_u64 v[198:199], v[198:199], 0, s[76:77]
	s_mov_b32 m0, s47
	ds_read_b128 v[220:223], v161
	ds_read_b128 v[224:227], v161 offset:1024
	ds_read_b128 v[228:231], v161 offset:2048
	ds_read_b128 v[232:235], v161 offset:3072
	global_load_lds_dwordx4 v[198:199], off
	v_lshl_add_u64 v[198:199], v[236:237], 0, s[76:77]
	s_add_i32 m0, s47, 0x2000
	s_nop 0
	global_load_lds_dwordx4 v[198:199], off
	s_barrier
; #define PG8_STAGE(bufoff, gbase, voff) do { _Pragma("unroll") for (int _i = 0; _i < 2; ++_i) \
;         __builtin_amdgcn_global_load_lds((const unsigned*)((const char*)(gbase) + (voff)[_i]), (LAS unsigned*)(lds + (bufoff) + ldsw + _i * 8192), 16, 0, 0); } while (0)
; #define PG8_LDA(dst, b, h) do { _Pragma("unroll") for (int m = 0; m < 4; ++m) _Pragma("unroll") for (int k = 0; k < 2; ++k) dst[m][k] = *(const LAS bf16x8*)(lds + PG8_SA(b, h) + aoff + m * 2048 + k * 1024); } while (0)
; #define PG8_MMA(ai, bj, At, Bt) do { __builtin_amdgcn_s_setprio(1); _Pragma("unroll") for (int m = 0; m < 4; ++m) _Pragma("unroll") for (int n = 0; n < 2; ++n) _Pragma("unroll") for (int k = 0; k < 2; ++k) \
;         acc[ai][bj][m][n] = __builtin_amdgcn_mfma_f32_16x16x32_bf16(Bt[n][k], At[m][k], acc[ai][bj][m][n], 0, 0, 0); __builtin_amdgcn_s_setprio(0); } while (0)
; #define PG8_WAIT_V(n) asm volatile("s_waitcnt vmcnt(" #n ")" ::: "memory")
; #define PG8_WAIT_L(n) asm volatile("s_waitcnt lgkmcnt(" #n ")" ::: "memory")
; #define PG8_BAR __builtin_amdgcn_s_barrier()
; #define PG8_SCHED __builtin_amdgcn_sched_barrier(0)
;     template <int mode> __device__ __forceinline__ void run(const f32x4 (&acc)[2][2][4][2], const Unit& u, int wr, int wc, int fr, int fq, const LAS float* sc) const {
;     ...
;             const int col0 = u.pn * BM + wc * 32 + 8 * fq;
;             f32x4 bv[2][2];
; #pragma unroll
;             for (int bj = 0; bj < 2; ++bj)
; #pragma unroll
;                 for (int n = 0; n < 2; ++n) bv[bj][n] = bias ? *(const f32x4*)(bias + col0 + bj * HALF + 4 * n) : (f32x4){0.f, 0.f, 0.f, 0.f};
; template <int MODE, class EpiT, class Sched>
; __device__ __forceinline__ void gemm_phase(LAS unsigned char* lds, const Gemm g, const Sched& S, const EpiT& E) {
;     ...
;             PG8_BAR; PG8_WAIT_L(0); PG8_MMA(0, 1, At, B1); PG8_BAR;
;             PG8_LDA(At, 1, 1); PG8_STAGE(PG8_SA(1, 0), a3, voffA);
;             PG8_BAR; PG8_WAIT_L(0); PG8_MMA(1, 0, At, B0); PG8_BAR; PG8_SCHED;
;             PG8_STAGE(PG8_SB(1, 1), b3 + hstep, voffB);
;             PG8_WAIT_V(6); PG8_BAR; PG8_MMA(1, 1, At, B1); PG8_BAR;
;         }
	s_waitcnt lgkmcnt(0)
	v_mfma_f32_16x16x32_bf16 v[94:97], v[220:223], v[162:165], v[94:97]
	v_mfma_f32_16x16x32_bf16 v[90:93], v[228:231], v[162:165], v[90:93]
	v_mfma_f32_16x16x32_bf16 v[86:89], v[220:223], v[170:173], v[86:89]
	v_mfma_f32_16x16x32_bf16 v[82:85], v[228:231], v[170:173], v[82:85]
	v_mfma_f32_16x16x32_bf16 v[78:81], v[220:223], v[182:185], v[78:81]
	v_mfma_f32_16x16x32_bf16 v[74:77], v[228:231], v[182:185], v[74:77]
	v_mfma_f32_16x16x32_bf16 v[70:73], v[220:223], v[190:193], v[70:73]
	v_mfma_f32_16x16x32_bf16 v[66:69], v[228:231], v[190:193], v[66:69]
	v_mfma_f32_16x16x32_bf16 v[94:97], v[224:227], v[166:169], v[94:97]
	v_mfma_f32_16x16x32_bf16 v[90:93], v[232:235], v[166:169], v[90:93]
	v_mfma_f32_16x16x32_bf16 v[86:89], v[224:227], v[174:177], v[86:89]
	v_mfma_f32_16x16x32_bf16 v[82:85], v[232:235], v[174:177], v[82:85]
	v_mfma_f32_16x16x32_bf16 v[78:81], v[224:227], v[186:189], v[78:81]
	v_mfma_f32_16x16x32_bf16 v[74:77], v[232:235], v[186:189], v[74:77]
	v_mfma_f32_16x16x32_bf16 v[70:73], v[224:227], v[194:197], v[70:73]
	v_mfma_f32_16x16x32_bf16 v[66:69], v[232:235], v[194:197], v[66:69]
	s_barrier
	s_mov_b32 m0, s56
	v_lshl_add_u64 v[198:199], v[238:239], 0, s[76:77]
	ds_read_b128 v[162:165], v160 offset:49152
	ds_read_b128 v[166:169], v160 offset:50176
	ds_read_b128 v[170:173], v160 offset:51200
	ds_read_b128 v[174:177], v160 offset:52224
	ds_read_b128 v[182:185], v160 offset:53248
	ds_read_b128 v[186:189], v160 offset:54272
	ds_read_b128 v[190:193], v160 offset:55296
	ds_read_b128 v[194:197], v160 offset:56320
	global_load_lds_dwordx4 v[198:199], off
	v_lshl_add_u64 v[198:199], v[240:241], 0, s[76:77]
	s_mov_b32 m0, s57
	s_nop 0
	global_load_lds_dwordx4 v[198:199], off
	s_barrier
	s_waitcnt lgkmcnt(0)
	v_mfma_f32_16x16x32_bf16 v[62:65], v[134:137], v[162:165], v[62:65]
	v_mfma_f32_16x16x32_bf16 v[58:61], v[142:145], v[162:165], v[58:61]
	v_mfma_f32_16x16x32_bf16 v[54:57], v[134:137], v[170:173], v[54:57]
	v_mfma_f32_16x16x32_bf16 v[50:53], v[142:145], v[170:173], v[50:53]
	v_mfma_f32_16x16x32_bf16 v[46:49], v[134:137], v[182:185], v[46:49]
	v_mfma_f32_16x16x32_bf16 v[42:45], v[142:145], v[182:185], v[42:45]
	v_mfma_f32_16x16x32_bf16 v[38:41], v[134:137], v[190:193], v[38:41]
	v_mfma_f32_16x16x32_bf16 v[34:37], v[142:145], v[190:193], v[34:37]
	v_mfma_f32_16x16x32_bf16 v[62:65], v[138:141], v[166:169], v[62:65]
	v_mfma_f32_16x16x32_bf16 v[58:61], v[152:155], v[166:169], v[58:61]
	v_mfma_f32_16x16x32_bf16 v[54:57], v[138:141], v[174:177], v[54:57]
	v_mfma_f32_16x16x32_bf16 v[50:53], v[152:155], v[174:177], v[50:53]
	v_mfma_f32_16x16x32_bf16 v[46:49], v[138:141], v[186:189], v[46:49]
	v_mfma_f32_16x16x32_bf16 v[42:45], v[152:155], v[186:189], v[42:45]
	v_mfma_f32_16x16x32_bf16 v[38:41], v[138:141], v[194:197], v[38:41]
	v_mfma_f32_16x16x32_bf16 v[34:37], v[152:155], v[194:197], v[34:37]
	s_barrier
	s_add_i32 s46, s46, s24
	v_lshl_add_u64 v[134:135], v[242:243], 0, s[76:77]
	s_mov_b32 m0, s46
	s_nop 0
	global_load_lds_dwordx4 v[134:135], off
	v_lshl_add_u64 v[134:135], v[244:245], 0, s[76:77]
	s_add_i32 m0, s46, 0x2000
	s_nop 0
	global_load_lds_dwordx4 v[134:135], off
	s_waitcnt vmcnt(6)
	s_barrier
	v_mfma_f32_16x16x32_bf16 v[30:33], v[220:223], v[162:165], v[30:33]
	v_mfma_f32_16x16x32_bf16 v[26:29], v[228:231], v[162:165], v[26:29]
	v_mfma_f32_16x16x32_bf16 v[22:25], v[220:223], v[170:173], v[22:25]
	v_mfma_f32_16x16x32_bf16 v[18:21], v[228:231], v[170:173], v[18:21]
	v_mfma_f32_16x16x32_bf16 v[14:17], v[220:223], v[182:185], v[14:17]
	v_mfma_f32_16x16x32_bf16 v[10:13], v[228:231], v[182:185], v[10:13]
	v_mfma_f32_16x16x32_bf16 v[6:9], v[220:223], v[190:193], v[6:9]
	v_mfma_f32_16x16x32_bf16 v[2:5], v[228:231], v[190:193], v[2:5]
	v_mfma_f32_16x16x32_bf16 v[30:33], v[224:227], v[166:169], v[30:33]
	v_mfma_f32_16x16x32_bf16 v[26:29], v[232:235], v[166:169], v[26:29]
	v_mfma_f32_16x16x32_bf16 v[22:25], v[224:227], v[174:177], v[22:25]
	v_mfma_f32_16x16x32_bf16 v[18:21], v[232:235], v[174:177], v[18:21]
	v_mfma_f32_16x16x32_bf16 v[14:17], v[224:227], v[186:189], v[14:17]
	v_mfma_f32_16x16x32_bf16 v[10:13], v[232:235], v[186:189], v[10:13]
	v_mfma_f32_16x16x32_bf16 v[6:9], v[224:227], v[194:197], v[6:9]
	v_mfma_f32_16x16x32_bf16 v[2:5], v[232:235], v[194:197], v[2:5]
	s_barrier
	s_add_u32 s44, s44, 0x100
	s_addc_u32 s45, s45, 0
	v_lshl_add_u64 v[132:133], v[132:133], 0, s[80:81]
	v_lshl_add_u64 v[130:131], v[130:131], 0, s[80:81]
	s_cmp_ge_u32 s68, s55
	s_mov_b32 s46, s68
	s_cbranch_scc0 .LBB0_280
	v_lshl_or_b32 v152, s3, 8, v159
	v_ashrrev_i32_e32 v153, 31, v152
	v_cndmask_b32_e64 v131, 0, 1, s[28:29]
	v_lshl_add_u64 v[154:155], v[152:153], 2, s[12:13]
	v_mov_b32_e32 v130, 0
	v_cmp_ne_u32_e64 s[44:45], 1, v131
	s_andn2_b64 vcc, exec, s[28:29]
	v_mov_b32_e32 v134, 0
	v_mov_b32_e32 v135, 0
	v_mov_b32_e32 v136, 0
	v_mov_b32_e32 v137, 0
	s_cbranch_vccnz .LBB0_283
	global_load_dwordx4 v[134:137], v[154:155], off

; #define PG8_STAGE(bufoff, gbase, voff) do { _Pragma("unroll") for (int _i = 0; _i < 2; ++_i) \
;         __builtin_amdgcn_global_load_lds((const unsigned*)((const char*)(gbase) + (voff)[_i]), (LAS unsigned*)(lds + (bufoff) + ldsw + _i * 8192), 16, 0, 0); } while (0)
; #define PG8_LDA(dst, b, h) do { _Pragma("unroll") for (int m = 0; m < 4; ++m) _Pragma("unroll") for (int k = 0; k < 2; ++k) dst[m][k] = *(const LAS bf16x8*)(lds + PG8_SA(b, h) + aoff + m * 2048 + k * 1024); } while (0)
; #define PG8_LDB(dst, b, h) do { _Pragma("unroll") for (int n = 0; n < 2; ++n) _Pragma("unroll") for (int k = 0; k < 2; ++k) dst[n][k] = *(const LAS bf16x8*)(lds + PG8_SB(b, h) + boff + n * 2048 + k * 1024); } while (0)
; #define PG8_MMA(ai, bj, At, Bt) do { __builtin_amdgcn_s_setprio(1); _Pragma("unroll") for (int m = 0; m < 4; ++m) _Pragma("unroll") for (int n = 0; n < 2; ++n) _Pragma("unroll") for (int k = 0; k < 2; ++k) \
;         acc[ai][bj][m][n] = __builtin_amdgcn_mfma_f32_16x16x32_bf16(Bt[n][k], At[m][k], acc[ai][bj][m][n], 0, 0, 0); __builtin_amdgcn_s_setprio(0); } while (0)
; #define PG8_WAIT_L(n) asm volatile("s_waitcnt lgkmcnt(" #n ")" ::: "memory")
; #define PG8_BAR __builtin_amdgcn_s_barrier()
; #define PG8_SCHED __builtin_amdgcn_sched_barrier(0)
; template <int MODE, class EpiT, class Sched>
; __device__ __forceinline__ void gemm_phase(LAS unsigned char* lds, const Gemm g, const Sched& S, const EpiT& E) {
;     ...
;         for (int t = 0; t < nt; t += 2) {
;             const bool last = (t == nt - 2);
;             const char* a1 = cA + (size_t)(t + 1) * kstep;
;             const char* a2 = last ? nA : cA + (size_t)(t + 2) * kstep; const char* b2 = last ? nB : cB + (size_t)(t + 2) * kstep;
;             const char* a3 = a2 + kstep; const char* b3 = b2 + kstep;
;             PG8_LDB(B0, 0, 0); PG8_SCHED; PG8_LDA(At, 0, 0); PG8_STAGE(PG8_SA(1, 1), a1 + hstep, voffA);
;             PG8_WAIT_L(8); PG8_BAR; PG8_WAIT_L(0); PG8_MMA(0, 0, At, B0); PG8_BAR; PG8_SCHED;
;             PG8_LDB(B1, 0, 1); PG8_STAGE(PG8_SB(0, 0), b2, voffB);
;             PG8_BAR; PG8_WAIT_L(0); PG8_MMA(0, 1, At, B1); PG8_BAR;
;             PG8_LDA(At, 0, 1); PG8_STAGE(PG8_SA(0, 0), a2, voffA);
;             PG8_BAR; PG8_WAIT_L(0); PG8_MMA(1, 0, At, B0); PG8_BAR; PG8_SCHED;
.LBB0_332:
	s_add_i32 s23, s22, 2
	s_add_u32 s30, s12, s4
	s_addc_u32 s38, s13, s5
	s_add_u32 s44, s10, s4
	s_addc_u32 s45, s11, s5
	s_add_i32 s58, 0, 0x10000
	v_add_u32_e32 v145, s58, v141
	ds_read_b128 v[146:149], v145
	ds_read_b128 v[150:153], v145 offset:1024
	ds_read_b128 v[154:157], v145 offset:2048
	ds_read_b128 v[158:161], v145 offset:3072
	s_cmp_eq_u32 s55, s22
	s_cselect_b32 s39, s29, s38
	s_cselect_b32 s38, s28, s30
	s_cselect_b32 s45, s35, s45
	s_cselect_b32 s44, s34, s44
	v_lshl_add_u64 v[198:199], s[12:13], 0, v[138:139]
	s_add_i32 m0, s47, 0xc000
	ds_read_b128 v[162:165], v144
	ds_read_b128 v[166:169], v144 offset:1024
	ds_read_b128 v[170:173], v144 offset:2048
	ds_read_b128 v[174:177], v144 offset:3072
	ds_read_b128 v[182:185], v144 offset:4096
	ds_read_b128 v[186:189], v144 offset:5120
	ds_read_b128 v[190:193], v144 offset:6144
	ds_read_b128 v[194:197], v144 offset:7168
	global_load_lds_dwordx4 v[198:199], off
	v_lshl_add_u64 v[198:199], s[12:13], 0, v[136:137]
	s_add_i32 m0, s47, 0xe000
	s_nop 0
	global_load_lds_dwordx4 v[198:199], off
	s_waitcnt lgkmcnt(8)
	s_barrier
	s_waitcnt lgkmcnt(0)
	v_mfma_f32_16x16x32_bf16 v[126:129], v[146:149], v[162:165], v[126:129]
	v_mfma_f32_16x16x32_bf16 v[122:125], v[154:157], v[162:165], v[122:125]
	v_mfma_f32_16x16x32_bf16 v[118:121], v[146:149], v[170:173], v[118:121]
	v_mfma_f32_16x16x32_bf16 v[114:117], v[154:157], v[170:173], v[114:117]
	v_mfma_f32_16x16x32_bf16 v[110:113], v[146:149], v[182:185], v[110:113]
	v_mfma_f32_16x16x32_bf16 v[106:109], v[154:157], v[182:185], v[106:109]
	v_mfma_f32_16x16x32_bf16 v[102:105], v[146:149], v[190:193], v[102:105]
	v_mfma_f32_16x16x32_bf16 v[98:101], v[154:157], v[190:193], v[98:101]
	v_mfma_f32_16x16x32_bf16 v[126:129], v[150:153], v[166:169], v[126:129]
	v_mfma_f32_16x16x32_bf16 v[122:125], v[158:161], v[166:169], v[122:125]
	v_mfma_f32_16x16x32_bf16 v[118:121], v[150:153], v[174:177], v[118:121]
	v_mfma_f32_16x16x32_bf16 v[114:117], v[158:161], v[174:177], v[114:117]
	v_mfma_f32_16x16x32_bf16 v[110:113], v[150:153], v[186:189], v[110:113]
	v_mfma_f32_16x16x32_bf16 v[106:109], v[158:161], v[186:189], v[106:109]
	v_mfma_f32_16x16x32_bf16 v[102:105], v[150:153], v[194:197], v[102:105]
	v_mfma_f32_16x16x32_bf16 v[98:101], v[158:161], v[194:197], v[98:101]
	s_barrier
	s_add_i32 s22, 0, 0x14000
	s_add_i32 s30, s58, s46
	v_add_u32_e32 v145, s22, v141
	v_lshl_add_u64 v[198:199], s[44:45], 0, v[0:1]
	s_mov_b32 m0, s30
	ds_read_b128 v[220:223], v145
	ds_read_b128 v[224:227], v145 offset:1024
	ds_read_b128 v[228:231], v145 offset:2048
	ds_read_b128 v[232:235], v145 offset:3072
	global_load_lds_dwordx4 v[198:199], off
	v_lshl_add_u64 v[236:237], s[44:45], 0, v[130:131]
	s_add_i32 m0, s30, 0x2000
	s_nop 0
	global_load_lds_dwordx4 v[236:237], off
	s_barrier
	s_waitcnt lgkmcnt(0)
	v_mfma_f32_16x16x32_bf16 v[94:97], v[220:223], v[162:165], v[94:97]
	v_mfma_f32_16x16x32_bf16 v[90:93], v[228:231], v[162:165], v[90:93]
	v_mfma_f32_16x16x32_bf16 v[86:89], v[220:223], v[170:173], v[86:89]
	v_mfma_f32_16x16x32_bf16 v[82:85], v[228:231], v[170:173], v[82:85]
	v_mfma_f32_16x16x32_bf16 v[78:81], v[220:223], v[182:185], v[78:81]
	v_mfma_f32_16x16x32_bf16 v[74:77], v[228:231], v[182:185], v[74:77]
	v_mfma_f32_16x16x32_bf16 v[70:73], v[220:223], v[190:193], v[70:73]
	v_mfma_f32_16x16x32_bf16 v[66:69], v[228:231], v[190:193], v[66:69]
	v_mfma_f32_16x16x32_bf16 v[94:97], v[224:227], v[166:169], v[94:97]
	v_mfma_f32_16x16x32_bf16 v[90:93], v[232:235], v[166:169], v[90:93]
	v_mfma_f32_16x16x32_bf16 v[86:89], v[224:227], v[174:177], v[86:89]
	v_mfma_f32_16x16x32_bf16 v[82:85], v[232:235], v[174:177], v[82:85]
	v_mfma_f32_16x16x32_bf16 v[78:81], v[224:227], v[186:189], v[78:81]
	v_mfma_f32_16x16x32_bf16 v[74:77], v[232:235], v[186:189], v[74:77]
	v_mfma_f32_16x16x32_bf16 v[70:73], v[224:227], v[194:197], v[70:73]
	v_mfma_f32_16x16x32_bf16 v[66:69], v[232:235], v[194:197], v[66:69]
	s_barrier
	s_mov_b32 m0, s47
	v_lshl_add_u64 v[238:239], s[38:39], 0, v[0:1]
	ds_read_b128 v[162:165], v144 offset:16384
	ds_read_b128 v[166:169], v144 offset:17408
	ds_read_b128 v[170:173], v144 offset:18432
	ds_read_b128 v[174:177], v144 offset:19456
	ds_read_b128 v[182:185], v144 offset:20480
	ds_read_b128 v[186:189], v144 offset:21504
	ds_read_b128 v[190:193], v144 offset:22528
	ds_read_b128 v[194:197], v144 offset:23552
	global_load_lds_dwordx4 v[238:239], off
	v_lshl_add_u64 v[240:241], s[38:39], 0, v[130:131]
	s_mov_b32 m0, s50
	s_nop 0
	global_load_lds_dwordx4 v[240:241], off
	s_barrier
	s_waitcnt lgkmcnt(0)
	v_mfma_f32_16x16x32_bf16 v[62:65], v[146:149], v[162:165], v[62:65]
	v_mfma_f32_16x16x32_bf16 v[58:61], v[154:157], v[162:165], v[58:61]
	v_mfma_f32_16x16x32_bf16 v[54:57], v[146:149], v[170:173], v[54:57]
	v_mfma_f32_16x16x32_bf16 v[50:53], v[154:157], v[170:173], v[50:53]
	v_mfma_f32_16x16x32_bf16 v[46:49], v[146:149], v[182:185], v[46:49]
	v_mfma_f32_16x16x32_bf16 v[42:45], v[154:157], v[182:185], v[42:45]
	v_mfma_f32_16x16x32_bf16 v[38:41], v[146:149], v[190:193], v[38:41]
	v_mfma_f32_16x16x32_bf16 v[34:37], v[154:157], v[190:193], v[34:37]
	v_mfma_f32_16x16x32_bf16 v[62:65], v[150:153], v[166:169], v[62:65]
	v_mfma_f32_16x16x32_bf16 v[58:61], v[158:161], v[166:169], v[58:61]
	v_mfma_f32_16x16x32_bf16 v[54:57], v[150:153], v[174:177], v[54:57]
	v_mfma_f32_16x16x32_bf16 v[50:53], v[158:161], v[174:177], v[50:53]
	v_mfma_f32_16x16x32_bf16 v[46:49], v[150:153], v[186:189], v[46:49]
	v_mfma_f32_16x16x32_bf16 v[42:45], v[158:161], v[186:189], v[42:45]
	v_mfma_f32_16x16x32_bf16 v[38:41], v[150:153], v[194:197], v[38:41]
	v_mfma_f32_16x16x32_bf16 v[34:37], v[158:161], v[194:197], v[34:37]
	s_barrier
; #define PG8_STAGE(bufoff, gbase, voff) do { _Pragma("unroll") for (int _i = 0; _i < 2; ++_i) \
;         __builtin_amdgcn_global_load_lds((const unsigned*)((const char*)(gbase) + (voff)[_i]), (LAS unsigned*)(lds + (bufoff) + ldsw + _i * 8192), 16, 0, 0); } while (0)
; #define PG8_LDA(dst, b, h) do { _Pragma("unroll") for (int m = 0; m < 4; ++m) _Pragma("unroll") for (int k = 0; k < 2; ++k) dst[m][k] = *(const LAS bf16x8*)(lds + PG8_SA(b, h) + aoff + m * 2048 + k * 1024); } while (0)
; #define PG8_LDB(dst, b, h) do { _Pragma("unroll") for (int n = 0; n < 2; ++n) _Pragma("unroll") for (int k = 0; k < 2; ++k) dst[n][k] = *(const LAS bf16x8*)(lds + PG8_SB(b, h) + boff + n * 2048 + k * 1024); } while (0)
; #define PG8_MMA(ai, bj, At, Bt) do { __builtin_amdgcn_s_setprio(1); _Pragma("unroll") for (int m = 0; m < 4; ++m) _Pragma("unroll") for (int n = 0; n < 2; ++n) _Pragma("unroll") for (int k = 0; k < 2; ++k) \
;         acc[ai][bj][m][n] = __builtin_amdgcn_mfma_f32_16x16x32_bf16(Bt[n][k], At[m][k], acc[ai][bj][m][n], 0, 0, 0); __builtin_amdgcn_s_setprio(0); } while (0)
; #define PG8_WAIT_V(n) asm volatile("s_waitcnt vmcnt(" #n ")" ::: "memory")
; #define PG8_WAIT_L(n) asm volatile("s_waitcnt lgkmcnt(" #n ")" ::: "memory")
; #define PG8_BAR __builtin_amdgcn_s_barrier()
; #define PG8_SCHED __builtin_amdgcn_sched_barrier(0)
; template <int MODE, class EpiT, class Sched>
; __device__ __forceinline__ void gemm_phase(LAS unsigned char* lds, const Gemm g, const Sched& S, const EpiT& E) {
;     ...
;             PG8_STAGE(PG8_SB(0, 1), b2 + hstep, voffB);
;             PG8_WAIT_V(6); PG8_BAR; PG8_MMA(1, 1, At, B1); PG8_BAR;
;             PG8_LDB(B0, 1, 0); PG8_SCHED; PG8_LDA(At, 1, 0); PG8_STAGE(PG8_SA(0, 1), a2 + hstep, voffA);
;             PG8_WAIT_L(8); PG8_BAR; PG8_WAIT_L(0); PG8_MMA(0, 0, At, B0); PG8_BAR; PG8_SCHED;
;             PG8_LDB(B1, 1, 1); PG8_STAGE(PG8_SB(1, 0), b3, voffB);
;             PG8_BAR; PG8_WAIT_L(0); PG8_MMA(0, 1, At, B1); PG8_BAR;
	s_add_u32 s44, s44, s21
	s_addc_u32 s45, s45, 0
	s_add_i32 s22, s22, s46
	v_lshl_add_u64 v[242:243], s[44:45], 0, v[0:1]
	s_mov_b32 m0, s22
	v_lshl_add_u64 v[244:245], s[44:45], 0, v[130:131]
	global_load_lds_dwordx4 v[242:243], off
	s_add_i32 m0, s22, 0x2000
	s_nop 0
	global_load_lds_dwordx4 v[244:245], off
	s_waitcnt vmcnt(6)
	s_barrier
	v_mfma_f32_16x16x32_bf16 v[30:33], v[220:223], v[162:165], v[30:33]
	v_mfma_f32_16x16x32_bf16 v[26:29], v[228:231], v[162:165], v[26:29]
	v_mfma_f32_16x16x32_bf16 v[22:25], v[220:223], v[170:173], v[22:25]
	v_mfma_f32_16x16x32_bf16 v[18:21], v[228:231], v[170:173], v[18:21]
	v_mfma_f32_16x16x32_bf16 v[14:17], v[220:223], v[182:185], v[14:17]
	v_mfma_f32_16x16x32_bf16 v[10:13], v[228:231], v[182:185], v[10:13]
	v_mfma_f32_16x16x32_bf16 v[6:9], v[220:223], v[190:193], v[6:9]
	v_mfma_f32_16x16x32_bf16 v[2:5], v[228:231], v[190:193], v[2:5]
	v_mfma_f32_16x16x32_bf16 v[30:33], v[224:227], v[166:169], v[30:33]
	v_mfma_f32_16x16x32_bf16 v[26:29], v[232:235], v[166:169], v[26:29]
	v_mfma_f32_16x16x32_bf16 v[22:25], v[224:227], v[174:177], v[22:25]
	v_mfma_f32_16x16x32_bf16 v[18:21], v[232:235], v[174:177], v[18:21]
	v_mfma_f32_16x16x32_bf16 v[14:17], v[224:227], v[186:189], v[14:17]
	v_mfma_f32_16x16x32_bf16 v[10:13], v[232:235], v[186:189], v[10:13]
	v_mfma_f32_16x16x32_bf16 v[6:9], v[224:227], v[194:197], v[6:9]
	v_mfma_f32_16x16x32_bf16 v[2:5], v[232:235], v[194:197], v[2:5]
	s_barrier
	s_add_i32 s22, 0, 0x18000
	v_add_u32_e32 v145, s22, v141
	ds_read_b128 v[146:149], v145
	ds_read_b128 v[150:153], v145 offset:1024
	ds_read_b128 v[154:157], v145 offset:2048
	ds_read_b128 v[158:161], v145 offset:3072
	s_add_u32 s38, s38, s21
	s_addc_u32 s39, s39, 0
	s_mov_b32 m0, s51
	v_lshl_add_u64 v[220:221], s[38:39], 0, v[0:1]
	ds_read_b128 v[162:165], v144 offset:32768
	ds_read_b128 v[166:169], v144 offset:33792
	ds_read_b128 v[170:173], v144 offset:34816
	ds_read_b128 v[174:177], v144 offset:35840
	ds_read_b128 v[182:185], v144 offset:36864
	ds_read_b128 v[186:189], v144 offset:37888
	ds_read_b128 v[190:193], v144 offset:38912
	ds_read_b128 v[194:197], v144 offset:39936
	global_load_lds_dwordx4 v[220:221], off
	v_lshl_add_u64 v[220:221], s[38:39], 0, v[130:131]
	s_mov_b32 m0, s52
	s_nop 0
	global_load_lds_dwordx4 v[220:221], off
	s_waitcnt lgkmcnt(8)
	s_barrier
	s_waitcnt lgkmcnt(0)
	v_mfma_f32_16x16x32_bf16 v[126:129], v[146:149], v[162:165], v[126:129]
	v_mfma_f32_16x16x32_bf16 v[122:125], v[154:157], v[162:165], v[122:125]
	v_mfma_f32_16x16x32_bf16 v[118:121], v[146:149], v[170:173], v[118:121]
	v_mfma_f32_16x16x32_bf16 v[114:117], v[154:157], v[170:173], v[114:117]
	v_mfma_f32_16x16x32_bf16 v[110:113], v[146:149], v[182:185], v[110:113]
	v_mfma_f32_16x16x32_bf16 v[106:109], v[154:157], v[182:185], v[106:109]
	v_mfma_f32_16x16x32_bf16 v[102:105], v[146:149], v[190:193], v[102:105]
	v_mfma_f32_16x16x32_bf16 v[98:101], v[154:157], v[190:193], v[98:101]
	v_mfma_f32_16x16x32_bf16 v[126:129], v[150:153], v[166:169], v[126:129]
	v_mfma_f32_16x16x32_bf16 v[122:125], v[158:161], v[166:169], v[122:125]
	v_mfma_f32_16x16x32_bf16 v[118:121], v[150:153], v[174:177], v[118:121]
	v_mfma_f32_16x16x32_bf16 v[114:117], v[158:161], v[174:177], v[114:117]
	v_mfma_f32_16x16x32_bf16 v[110:113], v[150:153], v[186:189], v[110:113]
	v_mfma_f32_16x16x32_bf16 v[106:109], v[158:161], v[186:189], v[106:109]
	v_mfma_f32_16x16x32_bf16 v[102:105], v[150:153], v[194:197], v[102:105]
	v_mfma_f32_16x16x32_bf16 v[98:101], v[158:161], v[194:197], v[98:101]
	s_barrier
	s_add_i32 s30, 0, 0x1c000
	s_add_i32 s22, s22, s46
	v_add_u32_e32 v145, s30, v141
	v_lshl_add_u64 v[198:199], v[198:199], 0, s[76:77]
	s_mov_b32 m0, s22
	ds_read_b128 v[220:223], v145
	ds_read_b128 v[224:227], v145 offset:1024
	ds_read_b128 v[228:231], v145 offset:2048
	ds_read_b128 v[232:235], v145 offset:3072
	global_load_lds_dwordx4 v[198:199], off
	v_lshl_add_u64 v[198:199], v[236:237], 0, s[76:77]
	s_add_i32 m0, s22, 0x2000
	s_nop 0
	global_load_lds_dwordx4 v[198:199], off
	s_barrier
	s_waitcnt lgkmcnt(0)
	v_mfma_f32_16x16x32_bf16 v[94:97], v[220:223], v[162:165], v[94:97]
	v_mfma_f32_16x16x32_bf16 v[90:93], v[228:231], v[162:165], v[90:93]
	v_mfma_f32_16x16x32_bf16 v[86:89], v[220:223], v[170:173], v[86:89]
	v_mfma_f32_16x16x32_bf16 v[82:85], v[228:231], v[170:173], v[82:85]
	v_mfma_f32_16x16x32_bf16 v[78:81], v[220:223], v[182:185], v[78:81]
	v_mfma_f32_16x16x32_bf16 v[74:77], v[228:231], v[182:185], v[74:77]
	v_mfma_f32_16x16x32_bf16 v[70:73], v[220:223], v[190:193], v[70:73]
	v_mfma_f32_16x16x32_bf16 v[66:69], v[228:231], v[190:193], v[66:69]
	v_mfma_f32_16x16x32_bf16 v[94:97], v[224:227], v[166:169], v[94:97]
	v_mfma_f32_16x16x32_bf16 v[90:93], v[232:235], v[166:169], v[90:93]
	v_mfma_f32_16x16x32_bf16 v[86:89], v[224:227], v[174:177], v[86:89]
	v_mfma_f32_16x16x32_bf16 v[82:85], v[232:235], v[174:177], v[82:85]
	v_mfma_f32_16x16x32_bf16 v[78:81], v[224:227], v[186:189], v[78:81]
	v_mfma_f32_16x16x32_bf16 v[74:77], v[232:235], v[186:189], v[74:77]
	v_mfma_f32_16x16x32_bf16 v[70:73], v[224:227], v[194:197], v[70:73]
	v_mfma_f32_16x16x32_bf16 v[66:69], v[232:235], v[194:197], v[66:69]
	s_barrier
	s_mov_b32 m0, s53
	v_lshl_add_u64 v[198:199], v[238:239], 0, s[76:77]
	ds_read_b128 v[162:165], v144 offset:49152
	ds_read_b128 v[166:169], v144 offset:50176
	ds_read_b128 v[170:173], v144 offset:51200
	ds_read_b128 v[174:177], v144 offset:52224
	ds_read_b128 v[182:185], v144 offset:53248
	ds_read_b128 v[186:189], v144 offset:54272
	ds_read_b128 v[190:193], v144 offset:55296
	ds_read_b128 v[194:197], v144 offset:56320
	global_load_lds_dwordx4 v[198:199], off
	v_lshl_add_u64 v[198:199], v[240:241], 0, s[76:77]
	s_mov_b32 m0, s54
	s_nop 0
	global_load_lds_dwordx4 v[198:199], off
	s_barrier
; __device__ __forceinline__ unsigned pk2(float lo, float hi) { unsigned r; asm volatile("v_cvt_pk_bf16_f32 %0, %1, %2" : "=v"(r) : "v"(lo), "v"(hi)); return r; }
; __device__ __forceinline__ float siluf_(float x) { return x * __builtin_amdgcn_rcpf(1.0f + __expf(-x)); }
; #define PG8_STAGE(bufoff, gbase, voff) do { _Pragma("unroll") for (int _i = 0; _i < 2; ++_i) \
;         __builtin_amdgcn_global_load_lds((const unsigned*)((const char*)(gbase) + (voff)[_i]), (LAS unsigned*)(lds + (bufoff) + ldsw + _i * 8192), 16, 0, 0); } while (0)
; #define PG8_WAIT_V(n) asm volatile("s_waitcnt vmcnt(" #n ")" ::: "memory")
; #define PG8_WAIT_L(n) asm volatile("s_waitcnt lgkmcnt(" #n ")" ::: "memory")
;     template <int mode> __device__ __forceinline__ void run(const f32x4 (&acc)[2][2][4][2], const Unit& u, int wr, int wc, int fr, int fq, const LAS float* sc) const {
;     ...
;                     const int row = row0 + ai * HALF + m * 16;
;                     const float s = sc[ai * HALF + wr * 64 + m * 16 + fr];
;                     const f32x4 g0 = acc[ai][0][m][0] * s, u0 = acc[ai][1][m][0] * s, g1 = acc[ai][0][m][1] * s, u1 = acc[ai][1][m][1] * s;
;                     u32x4 w;
;                     w.x = pk2(siluf_(g0[0]) * u0[0], siluf_(g0[1]) * u0[1]); w.y = pk2(siluf_(g0[2]) * u0[2], siluf_(g0[3]) * u0[3]);
;                     w.z = pk2(siluf_(g1[0]) * u1[0], siluf_(g1[1]) * u1[1]); w.w = pk2(siluf_(g1[2]) * u1[2], siluf_(g1[3]) * u1[3]);
;                     *(u32x4*)(ob + (size_t)row * FF + col0) = w;
; template <int MODE, class EpiT, class Sched>
; __device__ __forceinline__ void gemm_phase(LAS unsigned char* lds, const Gemm g, const Sched& S, const EpiT& E) {
;     ...
;             PG8_WAIT_V(6); PG8_BAR; PG8_MMA(1, 1, At, B1); PG8_BAR;
;             PG8_LDB(B0, 1, 0); PG8_SCHED; PG8_LDA(At, 1, 0); PG8_STAGE(PG8_SA(0, 1), a2 + hstep, voffA);
;             PG8_WAIT_L(8); PG8_BAR; PG8_WAIT_L(0); PG8_MMA(0, 0, At, B0); PG8_BAR; PG8_SCHED;
;             PG8_LDB(B1, 1, 1); PG8_STAGE(PG8_SB(1, 0), b3, voffB);
;             PG8_BAR; PG8_WAIT_L(0); PG8_MMA(0, 1, At, B1); PG8_BAR;
;             PG8_LDA(At, 1, 1); PG8_STAGE(PG8_SA(1, 0), a3, voffA);
;             PG8_BAR; PG8_WAIT_L(0); PG8_MMA(1, 0, At, B0); PG8_BAR; PG8_SCHED;
;             PG8_STAGE(PG8_SB(1, 1), b3 + hstep, voffB);
;             PG8_WAIT_V(6); PG8_BAR; PG8_MMA(1, 1, At, B1); PG8_BAR;
	s_waitcnt lgkmcnt(0)
	v_mfma_f32_16x16x32_bf16 v[62:65], v[146:149], v[162:165], v[62:65]
	v_mfma_f32_16x16x32_bf16 v[58:61], v[154:157], v[162:165], v[58:61]
	v_mfma_f32_16x16x32_bf16 v[54:57], v[146:149], v[170:173], v[54:57]
	v_mfma_f32_16x16x32_bf16 v[50:53], v[154:157], v[170:173], v[50:53]
	v_mfma_f32_16x16x32_bf16 v[46:49], v[146:149], v[182:185], v[46:49]
	v_mfma_f32_16x16x32_bf16 v[42:45], v[154:157], v[182:185], v[42:45]
	v_mfma_f32_16x16x32_bf16 v[38:41], v[146:149], v[190:193], v[38:41]
	v_mfma_f32_16x16x32_bf16 v[34:37], v[154:157], v[190:193], v[34:37]
	v_mfma_f32_16x16x32_bf16 v[62:65], v[150:153], v[166:169], v[62:65]
	v_mfma_f32_16x16x32_bf16 v[58:61], v[158:161], v[166:169], v[58:61]
	v_mfma_f32_16x16x32_bf16 v[54:57], v[150:153], v[174:177], v[54:57]
	v_mfma_f32_16x16x32_bf16 v[50:53], v[158:161], v[174:177], v[50:53]
	v_mfma_f32_16x16x32_bf16 v[46:49], v[150:153], v[186:189], v[46:49]
	v_mfma_f32_16x16x32_bf16 v[42:45], v[158:161], v[186:189], v[42:45]
	v_mfma_f32_16x16x32_bf16 v[38:41], v[150:153], v[194:197], v[38:41]
	v_mfma_f32_16x16x32_bf16 v[34:37], v[158:161], v[194:197], v[34:37]
	s_barrier
	s_add_i32 s22, s30, s46
	v_lshl_add_u64 v[146:147], v[242:243], 0, s[76:77]
	s_mov_b32 m0, s22
	s_nop 0
	global_load_lds_dwordx4 v[146:147], off
	v_lshl_add_u64 v[146:147], v[244:245], 0, s[76:77]
	s_add_i32 m0, s22, 0x2000
	s_nop 0
	global_load_lds_dwordx4 v[146:147], off
	s_waitcnt vmcnt(6)
	s_barrier
	v_mfma_f32_16x16x32_bf16 v[30:33], v[220:223], v[162:165], v[30:33]
	v_mfma_f32_16x16x32_bf16 v[26:29], v[228:231], v[162:165], v[26:29]
	v_mfma_f32_16x16x32_bf16 v[22:25], v[220:223], v[170:173], v[22:25]
	v_mfma_f32_16x16x32_bf16 v[18:21], v[228:231], v[170:173], v[18:21]
	v_mfma_f32_16x16x32_bf16 v[14:17], v[220:223], v[182:185], v[14:17]
	v_mfma_f32_16x16x32_bf16 v[10:13], v[228:231], v[182:185], v[10:13]
	v_mfma_f32_16x16x32_bf16 v[6:9], v[220:223], v[190:193], v[6:9]
	v_mfma_f32_16x16x32_bf16 v[2:5], v[228:231], v[190:193], v[2:5]
	v_mfma_f32_16x16x32_bf16 v[30:33], v[224:227], v[166:169], v[30:33]
	v_mfma_f32_16x16x32_bf16 v[26:29], v[232:235], v[166:169], v[26:29]
	v_mfma_f32_16x16x32_bf16 v[22:25], v[224:227], v[174:177], v[22:25]
	v_mfma_f32_16x16x32_bf16 v[18:21], v[232:235], v[174:177], v[18:21]
	v_mfma_f32_16x16x32_bf16 v[14:17], v[224:227], v[186:189], v[14:17]
	v_mfma_f32_16x16x32_bf16 v[10:13], v[232:235], v[186:189], v[10:13]
	v_mfma_f32_16x16x32_bf16 v[6:9], v[224:227], v[194:197], v[6:9]
	v_mfma_f32_16x16x32_bf16 v[2:5], v[232:235], v[194:197], v[2:5]
	s_barrier
	s_add_u32 s4, s4, 0x100
	s_addc_u32 s5, s5, 0
	v_lshl_add_u64 v[138:139], v[138:139], 0, s[80:81]
	v_lshl_add_u64 v[136:137], v[136:137], 0, s[80:81]
	s_cmp_ge_u32 s23, s16
	s_mov_b32 s22, s23
	s_cbranch_scc0 .LBB0_332
	v_lshl_add_u32 v145, s57, 10, v142
	ds_read_b32 v136, v145
	v_lshl_or_b32 v138, s8, 7, v143
	v_lshl_add_u32 v146, s9, 8, v140
	v_ashrrev_i32_e32 v139, 31, v138
	v_lshlrev_b64 v[138:139], 1, v[138:139]
	s_waitcnt lgkmcnt(0)
	v_pk_mul_f32 v[148:149], v[126:127], v[136:137] op_sel_hi:[1,0]
	v_pk_mul_f32 v[154:155], v[94:95], v[136:137] op_sel_hi:[1,0]
	v_mul_f32_e32 v147, 0xbfb8aa3b, v148
	v_exp_f32_e32 v147, v147
	v_pk_mul_f32 v[150:151], v[128:129], v[136:137] op_sel_hi:[1,0]
	v_pk_mul_f32 v[152:153], v[96:97], v[136:137] op_sel_hi:[1,0]
	v_pk_mul_f32 v[158:159], v[122:123], v[136:137] op_sel_hi:[1,0]
	v_add_f32_e32 v147, 1.0, v147
	v_rcp_f32_e32 v147, v147
	v_pk_mul_f32 v[156:157], v[124:125], v[136:137] op_sel_hi:[1,0]
	v_pk_mul_f32 v[160:161], v[92:93], v[136:137] op_sel_hi:[1,0]
	v_pk_mul_f32 v[136:137], v[90:91], v[136:137] op_sel_hi:[1,0]
	v_mul_f32_e32 v147, v148, v147
	v_mul_f32_e32 v148, 0xbfb8aa3b, v149
	v_exp_f32_e32 v148, v148
	v_mul_f32_e32 v147, v154, v147
	s_and_b64 vcc, exec, s[42:43]
	v_add_f32_e32 v148, 1.0, v148
	v_rcp_f32_e32 v148, v148
	s_nop 0
	v_mul_f32_e32 v148, v149, v148
	v_mul_f32_e32 v148, v155, v148
	v_cvt_pk_bf16_f32 v148, v147, v148
	v_mul_f32_e32 v147, 0xbfb8aa3b, v150
	v_mul_f32_e32 v149, 0xbfb8aa3b, v151
	v_exp_f32_e32 v147, v147
	v_exp_f32_e32 v149, v149
	v_add_f32_e32 v147, 1.0, v147
	v_add_f32_e32 v149, 1.0, v149
	v_rcp_f32_e32 v147, v147
	v_rcp_f32_e32 v149, v149
	v_mul_f32_e32 v147, v150, v147
	v_mul_f32_e32 v149, v151, v149
	v_mul_f32_e32 v147, v152, v147
	v_mul_f32_e32 v149, v153, v149
	v_cvt_pk_bf16_f32 v149, v147, v149
	v_mul_f32_e32 v147, 0xbfb8aa3b, v158
	v_exp_f32_e32 v147, v147
	s_nop 0
	v_add_f32_e32 v147, 1.0, v147
	v_rcp_f32_e32 v147, v147
	s_nop 0
	v_mul_f32_e32 v147, v158, v147
	v_mul_f32_e32 v136, v136, v147
	v_mul_f32_e32 v147, 0xbfb8aa3b, v159
	v_exp_f32_e32 v147, v147
	s_nop 0
	v_add_f32_e32 v147, 1.0, v147
	v_rcp_f32_e32 v147, v147
	s_nop 0
	v_mul_f32_e32 v147, v159, v147
	v_mul_f32_e32 v137, v137, v147
	v_cvt_pk_bf16_f32 v150, v136, v137
	v_mul_f32_e32 v136, 0xbfb8aa3b, v156
	v_mul_f32_e32 v137, 0xbfb8aa3b, v157
	v_exp_f32_e32 v136, v136
	v_exp_f32_e32 v137, v137
	v_or_b32_e32 v147, 16, v146
	v_add_f32_e32 v136, 1.0, v136
	v_add_f32_e32 v137, 1.0, v137
	v_rcp_f32_e32 v136, v136
	v_rcp_f32_e32 v137, v137
	v_mul_f32_e32 v136, v156, v136
	v_mul_f32_e32 v137, v157, v137
	v_mul_f32_e32 v136, v160, v136
	v_mul_f32_e32 v137, v161, v137
	v_cvt_pk_bf16_f32 v151, v136, v137
	v_mov_b64_e32 v[136:137], s[6:7]
	v_mad_i64_i32 v[152:153], s[4:5], v146, s33, v[136:137]
	v_lshl_add_u64 v[152:153], v[152:153], 0, v[138:139]
	global_store_dwordx4 v[152:153], v[148:151], off
	ds_read_b32 v148, v145 offset:64
	s_waitcnt lgkmcnt(0)
; __device__ __forceinline__ unsigned pk2(float lo, float hi) { unsigned r; asm volatile("v_cvt_pk_bf16_f32 %0, %1, %2" : "=v"(r) : "v"(lo), "v"(hi)); return r; }
; __device__ __forceinline__ float siluf_(float x) { return x * __builtin_amdgcn_rcpf(1.0f + __expf(-x)); }
;     template <int mode> __device__ __forceinline__ void run(const f32x4 (&acc)[2][2][4][2], const Unit& u, int wr, int wc, int fr, int fq, const LAS float* sc) const {
;     ...
;                 for (int m = 0; m < 4; ++m) {
;                     const int row = row0 + ai * HALF + m * 16;
;                     const float s = sc[ai * HALF + wr * 64 + m * 16 + fr];
;                     const f32x4 g0 = acc[ai][0][m][0] * s, u0 = acc[ai][1][m][0] * s, g1 = acc[ai][0][m][1] * s, u1 = acc[ai][1][m][1] * s;
;                     u32x4 w;
;                     w.x = pk2(siluf_(g0[0]) * u0[0], siluf_(g0[1]) * u0[1]); w.y = pk2(siluf_(g0[2]) * u0[2], siluf_(g0[3]) * u0[3]);
;                     w.z = pk2(siluf_(g1[0]) * u1[0], siluf_(g1[1]) * u1[1]); w.w = pk2(siluf_(g1[2]) * u1[2], siluf_(g1[3]) * u1[3]);
;                     *(u32x4*)(ob + (size_t)row * FF + col0) = w;
;                 }
	v_pk_mul_f32 v[152:153], v[118:119], v[148:149] op_sel_hi:[1,0]
	v_pk_mul_f32 v[150:151], v[120:121], v[148:149] op_sel_hi:[1,0]
	v_pk_mul_f32 v[154:155], v[88:89], v[148:149] op_sel_hi:[1,0]
	v_pk_mul_f32 v[156:157], v[86:87], v[148:149] op_sel_hi:[1,0]
	v_pk_mul_f32 v[158:159], v[116:117], v[148:149] op_sel_hi:[1,0]
	v_pk_mul_f32 v[160:161], v[114:115], v[148:149] op_sel_hi:[1,0]
	v_pk_mul_f32 v[162:163], v[84:85], v[148:149] op_sel_hi:[1,0]
	v_pk_mul_f32 v[164:165], v[82:83], v[148:149] op_sel_hi:[1,0]
	v_mul_f32_e32 v148, 0xbfb8aa3b, v152
	v_mul_f32_e32 v149, 0xbfb8aa3b, v153
	v_exp_f32_e32 v148, v148
	v_exp_f32_e32 v149, v149
	v_add_f32_e32 v148, 1.0, v148
	v_add_f32_e32 v149, 1.0, v149
	v_rcp_f32_e32 v148, v148
	v_rcp_f32_e32 v149, v149
	v_mul_f32_e32 v148, v152, v148
	v_mul_f32_e32 v149, v153, v149
	v_mul_f32_e32 v148, v156, v148
	v_mul_f32_e32 v149, v157, v149
	v_cvt_pk_bf16_f32 v148, v148, v149
	v_mul_f32_e32 v149, 0xbfb8aa3b, v150
	v_exp_f32_e32 v149, v149
	v_mul_f32_e32 v152, 0xbfb8aa3b, v159
	v_exp_f32_e32 v152, v152
	v_add_f32_e32 v149, 1.0, v149
	v_rcp_f32_e32 v149, v149
	v_add_f32_e32 v152, 1.0, v152
	v_rcp_f32_e32 v152, v152
	v_mul_f32_e32 v149, v150, v149
	v_mul_f32_e32 v150, 0xbfb8aa3b, v151
	v_exp_f32_e32 v150, v150
	v_mul_f32_e32 v149, v154, v149
	v_mul_f32_e32 v152, v159, v152
	v_mul_f32_e32 v152, v163, v152
	v_add_f32_e32 v150, 1.0, v150
	v_rcp_f32_e32 v150, v150
	s_nop 0
	v_mul_f32_e32 v150, v151, v150
	v_mul_f32_e32 v150, v155, v150
	v_cvt_pk_bf16_f32 v149, v149, v150
	v_mul_f32_e32 v150, 0xbfb8aa3b, v160
	v_mul_f32_e32 v151, 0xbfb8aa3b, v161
	v_exp_f32_e32 v150, v150
	v_exp_f32_e32 v151, v151
	v_add_f32_e32 v150, 1.0, v150
	v_add_f32_e32 v151, 1.0, v151
	v_rcp_f32_e32 v150, v150
	v_rcp_f32_e32 v151, v151
	v_mul_f32_e32 v150, v160, v150
	v_mul_f32_e32 v151, v161, v151
	v_mul_f32_e32 v150, v164, v150
	v_mul_f32_e32 v151, v165, v151
	v_cvt_pk_bf16_f32 v150, v150, v151
	v_mul_f32_e32 v151, 0xbfb8aa3b, v158
	v_exp_f32_e32 v151, v151
	s_nop 0
	v_add_f32_e32 v151, 1.0, v151
	v_rcp_f32_e32 v151, v151
	s_nop 0
	v_mul_f32_e32 v151, v158, v151
	v_mul_f32_e32 v151, v162, v151
	v_cvt_pk_bf16_f32 v151, v151, v152
	v_mad_i64_i32 v[152:153], s[4:5], v147, s33, v[136:137]
	v_lshl_add_u64 v[152:153], v[152:153], 0, v[138:139]
	global_store_dwordx4 v[152:153], v[148:151], off
	ds_read_b32 v148, v145 offset:128
	v_or_b32_e32 v147, 32, v146
	s_waitcnt lgkmcnt(0)
	v_pk_mul_f32 v[152:153], v[110:111], v[148:149] op_sel_hi:[1,0]
	v_pk_mul_f32 v[150:151], v[112:113], v[148:149] op_sel_hi:[1,0]
	v_pk_mul_f32 v[154:155], v[80:81], v[148:149] op_sel_hi:[1,0]
	v_pk_mul_f32 v[156:157], v[78:79], v[148:149] op_sel_hi:[1,0]
	v_pk_mul_f32 v[158:159], v[108:109], v[148:149] op_sel_hi:[1,0]
	v_pk_mul_f32 v[160:161], v[106:107], v[148:149] op_sel_hi:[1,0]
	v_pk_mul_f32 v[162:163], v[76:77], v[148:149] op_sel_hi:[1,0]
	v_pk_mul_f32 v[164:165], v[74:75], v[148:149] op_sel_hi:[1,0]
	v_mul_f32_e32 v148, 0xbfb8aa3b, v152
	v_mul_f32_e32 v149, 0xbfb8aa3b, v153
	v_exp_f32_e32 v148, v148
	v_exp_f32_e32 v149, v149
	v_add_f32_e32 v148, 1.0, v148
	v_add_f32_e32 v149, 1.0, v149
	v_rcp_f32_e32 v148, v148
	v_rcp_f32_e32 v149, v149
	v_mul_f32_e32 v148, v152, v148
	v_mul_f32_e32 v149, v153, v149
	v_mul_f32_e32 v148, v156, v148
	v_mul_f32_e32 v149, v157, v149
	v_cvt_pk_bf16_f32 v148, v148, v149
	v_mul_f32_e32 v149, 0xbfb8aa3b, v150
	v_exp_f32_e32 v149, v149
	v_mul_f32_e32 v152, 0xbfb8aa3b, v159
	v_exp_f32_e32 v152, v152
	v_add_f32_e32 v149, 1.0, v149
	v_rcp_f32_e32 v149, v149
	v_add_f32_e32 v152, 1.0, v152
	v_rcp_f32_e32 v152, v152
	v_mul_f32_e32 v149, v150, v149
	v_mul_f32_e32 v150, 0xbfb8aa3b, v151
	v_exp_f32_e32 v150, v150
	v_mul_f32_e32 v149, v154, v149
	v_mul_f32_e32 v152, v159, v152
	v_mul_f32_e32 v152, v163, v152
	v_add_f32_e32 v150, 1.0, v150
	v_rcp_f32_e32 v150, v150
	s_nop 0
	v_mul_f32_e32 v150, v151, v150
	v_mul_f32_e32 v150, v155, v150
	v_cvt_pk_bf16_f32 v149, v149, v150
	v_mul_f32_e32 v150, 0xbfb8aa3b, v160
	v_mul_f32_e32 v151, 0xbfb8aa3b, v161
	v_exp_f32_e32 v150, v150
	v_exp_f32_e32 v151, v151
	v_add_f32_e32 v150, 1.0, v150
	v_add_f32_e32 v151, 1.0, v151
	v_rcp_f32_e32 v150, v150
	v_rcp_f32_e32 v151, v151
	v_mul_f32_e32 v150, v160, v150
	v_mul_f32_e32 v151, v161, v151
	v_mul_f32_e32 v150, v164, v150
	v_mul_f32_e32 v151, v165, v151
	v_cvt_pk_bf16_f32 v150, v150, v151
	v_mul_f32_e32 v151, 0xbfb8aa3b, v158
	v_exp_f32_e32 v151, v151
	s_nop 0
	v_add_f32_e32 v151, 1.0, v151
	v_rcp_f32_e32 v151, v151
	s_nop 0
	v_mul_f32_e32 v151, v158, v151
	v_mul_f32_e32 v151, v162, v151
	v_cvt_pk_bf16_f32 v151, v151, v152
	v_mad_i64_i32 v[152:153], s[4:5], v147, s33, v[136:137]
	v_lshl_add_u64 v[152:153], v[152:153], 0, v[138:139]
	global_store_dwordx4 v[152:153], v[148:151], off
	ds_read_b32 v148, v145 offset:192
	v_or_b32_e32 v147, 48, v146
	s_waitcnt lgkmcnt(0)
; __device__ __forceinline__ unsigned pk2(float lo, float hi) { unsigned r; asm volatile("v_cvt_pk_bf16_f32 %0, %1, %2" : "=v"(r) : "v"(lo), "v"(hi)); return r; }
; __device__ __forceinline__ float siluf_(float x) { return x * __builtin_amdgcn_rcpf(1.0f + __expf(-x)); }
;     template <int mode> __device__ __forceinline__ void run(const f32x4 (&acc)[2][2][4][2], const Unit& u, int wr, int wc, int fr, int fq, const LAS float* sc) const {
;     ...
;                 for (int m = 0; m < 4; ++m) {
;                     const int row = row0 + ai * HALF + m * 16;
;                     const float s = sc[ai * HALF + wr * 64 + m * 16 + fr];
;                     const f32x4 g0 = acc[ai][0][m][0] * s, u0 = acc[ai][1][m][0] * s, g1 = acc[ai][0][m][1] * s, u1 = acc[ai][1][m][1] * s;
;                     u32x4 w;
;                     w.x = pk2(siluf_(g0[0]) * u0[0], siluf_(g0[1]) * u0[1]); w.y = pk2(siluf_(g0[2]) * u0[2], siluf_(g0[3]) * u0[3]);
;                     w.z = pk2(siluf_(g1[0]) * u1[0], siluf_(g1[1]) * u1[1]); w.w = pk2(siluf_(g1[2]) * u1[2], siluf_(g1[3]) * u1[3]);
;                     *(u32x4*)(ob + (size_t)row * FF + col0) = w;
;                 }
	v_pk_mul_f32 v[152:153], v[102:103], v[148:149] op_sel_hi:[1,0]
	v_pk_mul_f32 v[150:151], v[104:105], v[148:149] op_sel_hi:[1,0]
	v_pk_mul_f32 v[154:155], v[72:73], v[148:149] op_sel_hi:[1,0]
	v_pk_mul_f32 v[156:157], v[70:71], v[148:149] op_sel_hi:[1,0]
	v_pk_mul_f32 v[158:159], v[100:101], v[148:149] op_sel_hi:[1,0]
	v_pk_mul_f32 v[160:161], v[98:99], v[148:149] op_sel_hi:[1,0]
	v_pk_mul_f32 v[162:163], v[68:69], v[148:149] op_sel_hi:[1,0]
	v_pk_mul_f32 v[164:165], v[66:67], v[148:149] op_sel_hi:[1,0]
	v_mul_f32_e32 v148, 0xbfb8aa3b, v152
	v_mul_f32_e32 v149, 0xbfb8aa3b, v153
	v_exp_f32_e32 v148, v148
	v_exp_f32_e32 v149, v149
	v_add_f32_e32 v148, 1.0, v148
	v_add_f32_e32 v149, 1.0, v149
	v_rcp_f32_e32 v148, v148
	v_rcp_f32_e32 v149, v149
	v_mul_f32_e32 v148, v152, v148
	v_mul_f32_e32 v149, v153, v149
	v_mul_f32_e32 v148, v156, v148
	v_mul_f32_e32 v149, v157, v149
	v_cvt_pk_bf16_f32 v148, v148, v149
	v_mul_f32_e32 v149, 0xbfb8aa3b, v150
	v_exp_f32_e32 v149, v149
	v_mul_f32_e32 v152, 0xbfb8aa3b, v159
	v_exp_f32_e32 v152, v152
	v_add_f32_e32 v149, 1.0, v149
	v_rcp_f32_e32 v149, v149
	v_add_f32_e32 v152, 1.0, v152
	v_rcp_f32_e32 v152, v152
	v_mul_f32_e32 v149, v150, v149
	v_mul_f32_e32 v150, 0xbfb8aa3b, v151
	v_exp_f32_e32 v150, v150
	v_mul_f32_e32 v149, v154, v149
	v_mul_f32_e32 v152, v159, v152
	v_mul_f32_e32 v152, v163, v152
	v_add_f32_e32 v150, 1.0, v150
	v_rcp_f32_e32 v150, v150
	s_nop 0
	v_mul_f32_e32 v150, v151, v150
	v_mul_f32_e32 v150, v155, v150
	v_cvt_pk_bf16_f32 v149, v149, v150
	v_mul_f32_e32 v150, 0xbfb8aa3b, v160
	v_mul_f32_e32 v151, 0xbfb8aa3b, v161
	v_exp_f32_e32 v150, v150
	v_exp_f32_e32 v151, v151
	v_add_f32_e32 v150, 1.0, v150
	v_add_f32_e32 v151, 1.0, v151
	v_rcp_f32_e32 v150, v150
	v_rcp_f32_e32 v151, v151
	v_mul_f32_e32 v150, v160, v150
	v_mul_f32_e32 v151, v161, v151
	v_mul_f32_e32 v150, v164, v150
	v_mul_f32_e32 v151, v165, v151
	v_cvt_pk_bf16_f32 v150, v150, v151
	v_mul_f32_e32 v151, 0xbfb8aa3b, v158
	v_exp_f32_e32 v151, v151
	s_nop 0
	v_add_f32_e32 v151, 1.0, v151
	v_rcp_f32_e32 v151, v151
	s_nop 0
	v_mul_f32_e32 v151, v158, v151
	v_mul_f32_e32 v151, v162, v151
	v_cvt_pk_bf16_f32 v151, v151, v152
	v_mad_i64_i32 v[152:153], s[4:5], v147, s33, v[136:137]
	v_lshl_add_u64 v[152:153], v[152:153], 0, v[138:139]
	global_store_dwordx4 v[152:153], v[148:151], off
	ds_read_b32 v148, v145 offset:512
	v_add_u32_e32 v147, 0x80, v146
	s_waitcnt lgkmcnt(0)
	v_pk_mul_f32 v[152:153], v[62:63], v[148:149] op_sel_hi:[1,0]
	v_pk_mul_f32 v[150:151], v[64:65], v[148:149] op_sel_hi:[1,0]
	v_pk_mul_f32 v[154:155], v[32:33], v[148:149] op_sel_hi:[1,0]
	v_pk_mul_f32 v[156:157], v[30:31], v[148:149] op_sel_hi:[1,0]
	v_pk_mul_f32 v[158:159], v[60:61], v[148:149] op_sel_hi:[1,0]
	v_pk_mul_f32 v[160:161], v[58:59], v[148:149] op_sel_hi:[1,0]
	v_pk_mul_f32 v[162:163], v[28:29], v[148:149] op_sel_hi:[1,0]
	v_pk_mul_f32 v[164:165], v[26:27], v[148:149] op_sel_hi:[1,0]
	v_mul_f32_e32 v148, 0xbfb8aa3b, v152
	v_mul_f32_e32 v149, 0xbfb8aa3b, v153
	v_exp_f32_e32 v148, v148
	v_exp_f32_e32 v149, v149
	v_add_f32_e32 v148, 1.0, v148
	v_add_f32_e32 v149, 1.0, v149
	v_rcp_f32_e32 v148, v148
	v_rcp_f32_e32 v149, v149
	v_mul_f32_e32 v148, v152, v148
	v_mul_f32_e32 v149, v153, v149
	v_mul_f32_e32 v148, v156, v148
	v_mul_f32_e32 v149, v157, v149
	v_cvt_pk_bf16_f32 v148, v148, v149
	v_mul_f32_e32 v149, 0xbfb8aa3b, v150
	v_exp_f32_e32 v149, v149
	v_mul_f32_e32 v152, 0xbfb8aa3b, v159
	v_exp_f32_e32 v152, v152
	v_add_f32_e32 v149, 1.0, v149
	v_rcp_f32_e32 v149, v149
	v_add_f32_e32 v152, 1.0, v152
	v_rcp_f32_e32 v152, v152
	v_mul_f32_e32 v149, v150, v149
	v_mul_f32_e32 v150, 0xbfb8aa3b, v151
	v_exp_f32_e32 v150, v150
	v_mul_f32_e32 v149, v154, v149
	v_mul_f32_e32 v152, v159, v152
	v_mul_f32_e32 v152, v163, v152
	v_add_f32_e32 v150, 1.0, v150
	v_rcp_f32_e32 v150, v150
	s_nop 0
	v_mul_f32_e32 v150, v151, v150
	v_mul_f32_e32 v150, v155, v150
	v_cvt_pk_bf16_f32 v149, v149, v150
	v_mul_f32_e32 v150, 0xbfb8aa3b, v160
	v_mul_f32_e32 v151, 0xbfb8aa3b, v161
	v_exp_f32_e32 v150, v150
	v_exp_f32_e32 v151, v151
	v_add_f32_e32 v150, 1.0, v150
	v_add_f32_e32 v151, 1.0, v151
	v_rcp_f32_e32 v150, v150
	v_rcp_f32_e32 v151, v151
	v_mul_f32_e32 v150, v160, v150
	v_mul_f32_e32 v151, v161, v151
	v_mul_f32_e32 v150, v164, v150
	v_mul_f32_e32 v151, v165, v151
	v_cvt_pk_bf16_f32 v150, v150, v151
	v_mul_f32_e32 v151, 0xbfb8aa3b, v158
	v_exp_f32_e32 v151, v151
	s_nop 0
	v_add_f32_e32 v151, 1.0, v151
	v_rcp_f32_e32 v151, v151
	s_nop 0
	v_mul_f32_e32 v151, v158, v151
	v_mul_f32_e32 v151, v162, v151
	v_cvt_pk_bf16_f32 v151, v151, v152
	v_mad_i64_i32 v[152:153], s[4:5], v147, s33, v[136:137]
	v_lshl_add_u64 v[152:153], v[152:153], 0, v[138:139]
	global_store_dwordx4 v[152:153], v[148:151], off
	ds_read_b32 v148, v145 offset:576
	v_add_u32_e32 v147, 0x90, v146
	s_waitcnt lgkmcnt(0)
; __device__ __forceinline__ unsigned pk2(float lo, float hi) { unsigned r; asm volatile("v_cvt_pk_bf16_f32 %0, %1, %2" : "=v"(r) : "v"(lo), "v"(hi)); return r; }
; __device__ __forceinline__ float siluf_(float x) { return x * __builtin_amdgcn_rcpf(1.0f + __expf(-x)); }
;     template <int mode> __device__ __forceinline__ void run(const f32x4 (&acc)[2][2][4][2], const Unit& u, int wr, int wc, int fr, int fq, const LAS float* sc) const {
;     ...
;                 for (int m = 0; m < 4; ++m) {
;                     const int row = row0 + ai * HALF + m * 16;
;                     const float s = sc[ai * HALF + wr * 64 + m * 16 + fr];
;                     const f32x4 g0 = acc[ai][0][m][0] * s, u0 = acc[ai][1][m][0] * s, g1 = acc[ai][0][m][1] * s, u1 = acc[ai][1][m][1] * s;
;                     u32x4 w;
;                     w.x = pk2(siluf_(g0[0]) * u0[0], siluf_(g0[1]) * u0[1]); w.y = pk2(siluf_(g0[2]) * u0[2], siluf_(g0[3]) * u0[3]);
;                     w.z = pk2(siluf_(g1[0]) * u1[0], siluf_(g1[1]) * u1[1]); w.w = pk2(siluf_(g1[2]) * u1[2], siluf_(g1[3]) * u1[3]);
;                     *(u32x4*)(ob + (size_t)row * FF + col0) = w;
;                 }
	v_pk_mul_f32 v[152:153], v[54:55], v[148:149] op_sel_hi:[1,0]
	v_pk_mul_f32 v[150:151], v[56:57], v[148:149] op_sel_hi:[1,0]
	v_pk_mul_f32 v[154:155], v[24:25], v[148:149] op_sel_hi:[1,0]
	v_pk_mul_f32 v[156:157], v[22:23], v[148:149] op_sel_hi:[1,0]
	v_pk_mul_f32 v[158:159], v[52:53], v[148:149] op_sel_hi:[1,0]
	v_pk_mul_f32 v[160:161], v[50:51], v[148:149] op_sel_hi:[1,0]
	v_pk_mul_f32 v[162:163], v[20:21], v[148:149] op_sel_hi:[1,0]
	v_pk_mul_f32 v[164:165], v[18:19], v[148:149] op_sel_hi:[1,0]
	v_mul_f32_e32 v148, 0xbfb8aa3b, v152
	v_mul_f32_e32 v149, 0xbfb8aa3b, v153
	v_exp_f32_e32 v148, v148
	v_exp_f32_e32 v149, v149
	v_add_f32_e32 v148, 1.0, v148
	v_add_f32_e32 v149, 1.0, v149
	v_rcp_f32_e32 v148, v148
	v_rcp_f32_e32 v149, v149
	v_mul_f32_e32 v148, v152, v148
	v_mul_f32_e32 v149, v153, v149
	v_mul_f32_e32 v148, v156, v148
	v_mul_f32_e32 v149, v157, v149
	v_cvt_pk_bf16_f32 v148, v148, v149
	v_mul_f32_e32 v149, 0xbfb8aa3b, v150
	v_exp_f32_e32 v149, v149
	v_mul_f32_e32 v152, 0xbfb8aa3b, v159
	v_exp_f32_e32 v152, v152
	v_add_f32_e32 v149, 1.0, v149
	v_rcp_f32_e32 v149, v149
	v_add_f32_e32 v152, 1.0, v152
	v_rcp_f32_e32 v152, v152
	v_mul_f32_e32 v149, v150, v149
	v_mul_f32_e32 v150, 0xbfb8aa3b, v151
	v_exp_f32_e32 v150, v150
	v_mul_f32_e32 v149, v154, v149
	v_mul_f32_e32 v152, v159, v152
	v_mul_f32_e32 v152, v163, v152
	v_add_f32_e32 v150, 1.0, v150
	v_rcp_f32_e32 v150, v150
	s_nop 0
	v_mul_f32_e32 v150, v151, v150
	v_mul_f32_e32 v150, v155, v150
	v_cvt_pk_bf16_f32 v149, v149, v150
	v_mul_f32_e32 v150, 0xbfb8aa3b, v160
	v_mul_f32_e32 v151, 0xbfb8aa3b, v161
	v_exp_f32_e32 v150, v150
	v_exp_f32_e32 v151, v151
	v_add_f32_e32 v150, 1.0, v150
	v_add_f32_e32 v151, 1.0, v151
	v_rcp_f32_e32 v150, v150
	v_rcp_f32_e32 v151, v151
	v_mul_f32_e32 v150, v160, v150
	v_mul_f32_e32 v151, v161, v151
	v_mul_f32_e32 v150, v164, v150
	v_mul_f32_e32 v151, v165, v151
	v_cvt_pk_bf16_f32 v150, v150, v151
	v_mul_f32_e32 v151, 0xbfb8aa3b, v158
	v_exp_f32_e32 v151, v151
	s_nop 0
	v_add_f32_e32 v151, 1.0, v151
	v_rcp_f32_e32 v151, v151
	s_nop 0
	v_mul_f32_e32 v151, v158, v151
	v_mul_f32_e32 v151, v162, v151
	v_cvt_pk_bf16_f32 v151, v151, v152
	v_mad_i64_i32 v[152:153], s[4:5], v147, s33, v[136:137]
	v_lshl_add_u64 v[152:153], v[152:153], 0, v[138:139]
	global_store_dwordx4 v[152:153], v[148:151], off
	ds_read_b32 v148, v145 offset:640
	v_add_u32_e32 v147, 0xa0, v146
	s_waitcnt lgkmcnt(0)
	v_pk_mul_f32 v[152:153], v[46:47], v[148:149] op_sel_hi:[1,0]
	v_pk_mul_f32 v[150:151], v[48:49], v[148:149] op_sel_hi:[1,0]
	v_pk_mul_f32 v[154:155], v[16:17], v[148:149] op_sel_hi:[1,0]
	v_pk_mul_f32 v[156:157], v[14:15], v[148:149] op_sel_hi:[1,0]
	v_pk_mul_f32 v[158:159], v[44:45], v[148:149] op_sel_hi:[1,0]
	v_pk_mul_f32 v[160:161], v[42:43], v[148:149] op_sel_hi:[1,0]
	v_pk_mul_f32 v[162:163], v[12:13], v[148:149] op_sel_hi:[1,0]
	v_pk_mul_f32 v[164:165], v[10:11], v[148:149] op_sel_hi:[1,0]
	v_mul_f32_e32 v148, 0xbfb8aa3b, v152
	v_mul_f32_e32 v149, 0xbfb8aa3b, v153
	v_exp_f32_e32 v148, v148
	v_exp_f32_e32 v149, v149
	v_add_f32_e32 v148, 1.0, v148
	v_add_f32_e32 v149, 1.0, v149
	v_rcp_f32_e32 v148, v148
	v_rcp_f32_e32 v149, v149
	v_mul_f32_e32 v148, v152, v148
	v_mul_f32_e32 v149, v153, v149
	v_mul_f32_e32 v148, v156, v148
	v_mul_f32_e32 v149, v157, v149
	v_cvt_pk_bf16_f32 v148, v148, v149
	v_mul_f32_e32 v149, 0xbfb8aa3b, v150
	v_exp_f32_e32 v149, v149
	v_mul_f32_e32 v152, 0xbfb8aa3b, v159
	v_exp_f32_e32 v152, v152
	v_add_f32_e32 v149, 1.0, v149
	v_rcp_f32_e32 v149, v149
	v_add_f32_e32 v152, 1.0, v152
	v_rcp_f32_e32 v152, v152
	v_mul_f32_e32 v149, v150, v149
	v_mul_f32_e32 v150, 0xbfb8aa3b, v151
	v_exp_f32_e32 v150, v150
	v_mul_f32_e32 v149, v154, v149
	v_mul_f32_e32 v152, v159, v152
	v_mul_f32_e32 v152, v163, v152
	v_add_f32_e32 v150, 1.0, v150
	v_rcp_f32_e32 v150, v150
	s_nop 0
	v_mul_f32_e32 v150, v151, v150
	v_mul_f32_e32 v150, v155, v150
	v_cvt_pk_bf16_f32 v149, v149, v150
	v_mul_f32_e32 v150, 0xbfb8aa3b, v160
	v_mul_f32_e32 v151, 0xbfb8aa3b, v161
	v_exp_f32_e32 v150, v150
	v_exp_f32_e32 v151, v151
	v_add_f32_e32 v150, 1.0, v150
	v_add_f32_e32 v151, 1.0, v151
	v_rcp_f32_e32 v150, v150
	v_rcp_f32_e32 v151, v151
	v_mul_f32_e32 v150, v160, v150
	v_mul_f32_e32 v151, v161, v151
	v_mul_f32_e32 v150, v164, v150
	v_mul_f32_e32 v151, v165, v151
	v_cvt_pk_bf16_f32 v150, v150, v151
	v_mul_f32_e32 v151, 0xbfb8aa3b, v158
	v_exp_f32_e32 v151, v151
	v_add_u32_e32 v164, 0xb0, v146
	v_add_f32_e32 v151, 1.0, v151
	v_rcp_f32_e32 v151, v151
	s_nop 0
	v_mul_f32_e32 v151, v158, v151
	v_mul_f32_e32 v151, v162, v151
	v_cvt_pk_bf16_f32 v151, v151, v152
	ds_read_b32 v146, v145 offset:704
	v_mad_i64_i32 v[152:153], s[4:5], v147, s33, v[136:137]
	v_lshl_add_u64 v[152:153], v[152:153], 0, v[138:139]
	global_store_dwordx4 v[152:153], v[148:151], off
	s_waitcnt lgkmcnt(0)
; __device__ __forceinline__ unsigned pk2(float lo, float hi) { unsigned r; asm volatile("v_cvt_pk_bf16_f32 %0, %1, %2" : "=v"(r) : "v"(lo), "v"(hi)); return r; }
; __device__ __forceinline__ float siluf_(float x) { return x * __builtin_amdgcn_rcpf(1.0f + __expf(-x)); }
;     template <int mode> __device__ __forceinline__ void run(const f32x4 (&acc)[2][2][4][2], const Unit& u, int wr, int wc, int fr, int fq, const LAS float* sc) const {
;     ...
;                     const int row = row0 + ai * HALF + m * 16;
;                     const float s = sc[ai * HALF + wr * 64 + m * 16 + fr];
;                     const f32x4 g0 = acc[ai][0][m][0] * s, u0 = acc[ai][1][m][0] * s, g1 = acc[ai][0][m][1] * s, u1 = acc[ai][1][m][1] * s;
;                     u32x4 w;
;                     w.x = pk2(siluf_(g0[0]) * u0[0], siluf_(g0[1]) * u0[1]); w.y = pk2(siluf_(g0[2]) * u0[2], siluf_(g0[3]) * u0[3]);
;                     w.z = pk2(siluf_(g1[0]) * u1[0], siluf_(g1[1]) * u1[1]); w.w = pk2(siluf_(g1[2]) * u1[2], siluf_(g1[3]) * u1[3]);
;                     *(u32x4*)(ob + (size_t)row * FF + col0) = w;
; template <int MODE, class EpiT, class Sched>
; __device__ __forceinline__ void gemm_phase(LAS unsigned char* lds, const Gemm g, const Sched& S, const EpiT& E) {
;     ...
;         if (!has_next) break;
; #pragma unroll
;         for (int a = 0; a < 2; ++a)
; #pragma unroll
;             for (int b = 0; b < 2; ++b)
; #pragma unroll
;                 for (int m = 0; m < 4; ++m)
; #pragma unroll
;                     for (int n = 0; n < 2; ++n) acc[a][b][m][n] = (f32x4){0.f, 0.f, 0.f, 0.f};
;         cur = nxt; cA = nA; cB = nB; ++ui;
	v_pk_mul_f32 v[152:153], v[8:9], v[146:147] op_sel_hi:[1,0]
	v_pk_mul_f32 v[154:155], v[6:7], v[146:147] op_sel_hi:[1,0]
	v_pk_mul_f32 v[150:151], v[38:39], v[146:147] op_sel_hi:[1,0]
	v_pk_mul_f32 v[148:149], v[40:41], v[146:147] op_sel_hi:[1,0]
	v_pk_mul_f32 v[156:157], v[36:37], v[146:147] op_sel_hi:[1,0]
	v_pk_mul_f32 v[158:159], v[34:35], v[146:147] op_sel_hi:[1,0]
	v_pk_mul_f32 v[160:161], v[4:5], v[146:147] op_sel_hi:[1,0]
	v_pk_mul_f32 v[162:163], v[2:3], v[146:147] op_sel_hi:[1,0]
	v_mul_f32_e32 v145, 0xbfb8aa3b, v150
	v_mul_f32_e32 v146, 0xbfb8aa3b, v151
	v_exp_f32_e32 v145, v145
	v_exp_f32_e32 v146, v146
	v_mul_f32_e32 v147, 0xbfb8aa3b, v149
	v_exp_f32_e32 v147, v147
	v_add_f32_e32 v145, 1.0, v145
	v_add_f32_e32 v146, 1.0, v146
	v_rcp_f32_e32 v145, v145
	v_rcp_f32_e32 v146, v146
	v_add_f32_e32 v147, 1.0, v147
	v_rcp_f32_e32 v147, v147
	v_mul_f32_e32 v145, v150, v145
	v_mul_f32_e32 v146, v151, v146
	v_mul_f32_e32 v145, v154, v145
	v_mul_f32_e32 v146, v155, v146
	v_cvt_pk_bf16_f32 v146, v145, v146
	v_mul_f32_e32 v145, 0xbfb8aa3b, v148
	v_exp_f32_e32 v145, v145
	v_mul_f32_e32 v147, v149, v147
	v_mul_f32_e32 v147, v153, v147
	v_mul_f32_e32 v149, 0xbfb8aa3b, v157
	v_add_f32_e32 v145, 1.0, v145
	v_rcp_f32_e32 v145, v145
	v_exp_f32_e32 v149, v149
	v_mad_i64_i32 v[136:137], s[4:5], v164, s33, v[136:137]
	v_mul_f32_e32 v145, v148, v145
	v_mul_f32_e32 v145, v152, v145
	v_cvt_pk_bf16_f32 v147, v145, v147
	v_mul_f32_e32 v145, 0xbfb8aa3b, v158
	v_mul_f32_e32 v148, 0xbfb8aa3b, v159
	v_exp_f32_e32 v145, v145
	v_exp_f32_e32 v148, v148
	v_add_f32_e32 v149, 1.0, v149
	v_rcp_f32_e32 v149, v149
	v_add_f32_e32 v145, 1.0, v145
	v_add_f32_e32 v148, 1.0, v148
	v_rcp_f32_e32 v145, v145
	v_rcp_f32_e32 v148, v148
	v_mul_f32_e32 v149, v157, v149
	v_mul_f32_e32 v149, v161, v149
	v_mul_f32_e32 v145, v158, v145
	v_mul_f32_e32 v148, v159, v148
	v_mul_f32_e32 v145, v162, v145
	v_mul_f32_e32 v148, v163, v148
	v_cvt_pk_bf16_f32 v148, v145, v148
	v_mul_f32_e32 v145, 0xbfb8aa3b, v156
	v_exp_f32_e32 v145, v145
	v_lshl_add_u64 v[136:137], v[136:137], 0, v[138:139]
	v_add_f32_e32 v145, 1.0, v145
	v_rcp_f32_e32 v145, v145
	s_nop 0
	v_mul_f32_e32 v145, v156, v145
	v_mul_f32_e32 v145, v160, v145
	v_cvt_pk_bf16_f32 v149, v145, v149
	global_store_dwordx4 v[136:137], v[146:149], off
	s_cbranch_vccnz .LBB0_324
	v_mov_b32_e32 v2, 0
	s_mov_b32 s9, s61
	s_mov_b32 s8, s60
	s_mov_b64 s[12:13], s[28:29]
	s_mov_b64 s[10:11], s[34:35]
	s_mov_b32 s57, s2
	v_mov_b32_e32 v3, v2
	v_mov_b32_e32 v4, v2
	v_mov_b32_e32 v5, v2
	v_mov_b32_e32 v6, v2
	v_mov_b32_e32 v7, v2
	v_mov_b32_e32 v8, v2
	v_mov_b32_e32 v9, v2
	v_mov_b32_e32 v10, v2
	v_mov_b32_e32 v11, v2
	v_mov_b32_e32 v12, v2
	v_mov_b32_e32 v13, v2
	v_mov_b32_e32 v14, v2
	v_mov_b32_e32 v15, v2
	v_mov_b32_e32 v16, v2
	v_mov_b32_e32 v17, v2
	v_mov_b32_e32 v18, v2
	v_mov_b32_e32 v19, v2
	v_mov_b32_e32 v20, v2
	v_mov_b32_e32 v21, v2
	v_mov_b32_e32 v22, v2
	v_mov_b32_e32 v23, v2
	v_mov_b32_e32 v24, v2
	v_mov_b32_e32 v25, v2
	v_mov_b32_e32 v26, v2
	v_mov_b32_e32 v27, v2
	v_mov_b32_e32 v28, v2
	v_mov_b32_e32 v29, v2
	v_mov_b32_e32 v30, v2
	v_mov_b32_e32 v31, v2
	v_mov_b32_e32 v32, v2
	v_mov_b32_e32 v33, v2
	v_mov_b32_e32 v34, v2
	v_mov_b32_e32 v35, v2
	v_mov_b32_e32 v36, v2
	v_mov_b32_e32 v37, v2
	v_mov_b32_e32 v38, v2
	v_mov_b32_e32 v39, v2
	v_mov_b32_e32 v40, v2
	v_mov_b32_e32 v41, v2
	v_mov_b32_e32 v42, v2
	v_mov_b32_e32 v43, v2
	v_mov_b32_e32 v44, v2
	v_mov_b32_e32 v45, v2
	v_mov_b32_e32 v46, v2
	v_mov_b32_e32 v47, v2
	v_mov_b32_e32 v48, v2
	v_mov_b32_e32 v49, v2
	v_mov_b32_e32 v50, v2
	v_mov_b32_e32 v51, v2
	v_mov_b32_e32 v52, v2
	v_mov_b32_e32 v53, v2
	v_mov_b32_e32 v54, v2
	v_mov_b32_e32 v55, v2
	v_mov_b32_e32 v56, v2
	v_mov_b32_e32 v57, v2
	v_mov_b32_e32 v58, v2
	v_mov_b32_e32 v59, v2
	v_mov_b32_e32 v60, v2
	v_mov_b32_e32 v61, v2
	v_mov_b32_e32 v62, v2
	v_mov_b32_e32 v63, v2
	v_mov_b32_e32 v64, v2
	v_mov_b32_e32 v65, v2
	v_mov_b32_e32 v66, v2
	v_mov_b32_e32 v67, v2
	v_mov_b32_e32 v68, v2
	v_mov_b32_e32 v69, v2
	v_mov_b32_e32 v70, v2
	v_mov_b32_e32 v71, v2
	v_mov_b32_e32 v72, v2
	v_mov_b32_e32 v73, v2
	v_mov_b32_e32 v74, v2
	v_mov_b32_e32 v75, v2
	v_mov_b32_e32 v76, v2
	v_mov_b32_e32 v77, v2
	v_mov_b32_e32 v78, v2
	v_mov_b32_e32 v79, v2
	v_mov_b32_e32 v80, v2
	v_mov_b32_e32 v81, v2
	v_mov_b32_e32 v82, v2
	v_mov_b32_e32 v83, v2
	v_mov_b32_e32 v84, v2
	v_mov_b32_e32 v85, v2
	v_mov_b32_e32 v86, v2
	v_mov_b32_e32 v87, v2
	v_mov_b32_e32 v88, v2
	v_mov_b32_e32 v89, v2
	v_mov_b32_e32 v90, v2
	v_mov_b32_e32 v91, v2
	v_mov_b32_e32 v92, v2
	v_mov_b32_e32 v93, v2
	v_mov_b32_e32 v94, v2
	v_mov_b32_e32 v95, v2
	v_mov_b32_e32 v96, v2
	v_mov_b32_e32 v97, v2
	v_mov_b32_e32 v98, v2
	v_mov_b32_e32 v99, v2
	v_mov_b32_e32 v100, v2
	v_mov_b32_e32 v101, v2
	v_mov_b32_e32 v102, v2
	v_mov_b32_e32 v103, v2
	v_mov_b32_e32 v104, v2
	v_mov_b32_e32 v105, v2
	v_mov_b32_e32 v106, v2
	v_mov_b32_e32 v107, v2
	v_mov_b32_e32 v108, v2
	v_mov_b32_e32 v109, v2
	v_mov_b32_e32 v110, v2
	v_mov_b32_e32 v111, v2
	v_mov_b32_e32 v112, v2
	v_mov_b32_e32 v113, v2
	v_mov_b32_e32 v114, v2
	v_mov_b32_e32 v115, v2
	v_mov_b32_e32 v116, v2
	v_mov_b32_e32 v117, v2
	v_mov_b32_e32 v118, v2
	v_mov_b32_e32 v119, v2
	v_mov_b32_e32 v120, v2
	v_mov_b32_e32 v121, v2
	v_mov_b32_e32 v122, v2
	v_mov_b32_e32 v123, v2
	v_mov_b32_e32 v124, v2
	v_mov_b32_e32 v125, v2
	v_mov_b32_e32 v126, v2
	v_mov_b32_e32 v127, v2
	v_mov_b32_e32 v128, v2
	v_mov_b32_e32 v129, v2
	s_branch .LBB0_324
